# DSA attention PV: four 8-key steps unrolled and double-buffered (gathers of next step in flight during compute)
# baseline (speedup 1.0000x reference)
;   __device__ __forceinline__ half_t* yb() const { return (half_t*)(ws() + OFF_yb); }
; __device__ __forceinline__ void dsa_item(const KP& p, int b, int tile, char* smem) {
;     ...
;     mx = fmaxf(mx, __shfl_xor(mx, 16));
;     mx = fmaxf(mx, __shfl_xor(mx, 32));
;     const float mxh = __shfl(mx, lane & 7);
;     __builtin_amdgcn_wave_barrier();
;     float sum = 0.f;
; #pragma unroll 4
;     for (int k = 0; k < 32; ++k) {
;       const int i = lane + 64 * k;
;       const float v = pbuf[i];
;       const float e = (v > -1e29f) ? __expf(v - mxh) : 0.f;
;       pbuf[i] = e;
;       sum += e;
;     }
;     sum += __shfl_xor(sum, 8);
;     sum += __shfl_xor(sum, 16);
;     sum += __shfl_xor(sum, 32);
;     const float inv = 1.f / sum;
;     __builtin_amdgcn_wave_barrier();
;     {
;       const int rs = lane >> 3, dc = lane & 7;
;       float acc[8][8];
; #pragma unroll
;       for (int h = 0; h < 8; ++h)
; #pragma unroll
;         for (int e = 0; e < 8; ++e) acc[h][e] = 0.f;
; #pragma unroll 1
;       for (int g8 = 0; g8 < 4; ++g8) {
;         h8 vv[8];
; #pragma unroll
;         for (int i = 0; i < 8; ++i) {
;           const int pos = (g8 * 8 + i) * 8 + rs;
;           const int s = (pos < nsel) ? (int)sel[tk * 256 + pos] : 0;
;           vv[i] = *(const h8*)(ub + (size_t)s * NU + C_BV + dc * 8);
;         }
; #pragma unroll
;         for (int i = 0; i < 8; ++i) {
;           const int pos = (g8 * 8 + i) * 8 + rs;
;           const f32x4 pa = *(const f32x4*)&pbuf[pos * 8];
;           const f32x4 pb = *(const f32x4*)&pbuf[pos * 8 + 4];
;           float vf[8];
; #pragma unroll
;           for (int e = 0; e < 8; ++e) vf[e] = (float)vv[i][e];
; #pragma unroll
;           for (int e = 0; e < 8; ++e) {
;             acc[0][e] += pa[0] * vf[e]; acc[1][e] += pa[1] * vf[e]; acc[2][e] += pa[2] * vf[e]; acc[3][e] += pa[3] * vf[e];
;             acc[4][e] += pb[0] * vf[e]; acc[5][e] += pb[1] * vf[e]; acc[6][e] += pb[2] * vf[e]; acc[7][e] += pb[3] * vf[e];
;           }
;         }
;       }
;       half_t* yrow = p.yb() + (size_t)(b * SEQ + t) * 512;
;       float v32[4][8], v16[2][8], v8[8];
;       const bool b2 = (rs & 4) != 0, b1 = (rs & 2) != 0, b0 = (rs & 1) != 0;
.LBB0_1423:
	v_mov_b32_e32 v250, v224
	v_and_b32_e32 v4, 64, v237
	v_xor_b32_e32 v0, 16, v237
	v_add_u32_e32 v2, 64, v4
	v_cmp_lt_i32_e32 vcc, v0, v2
	v_and_b32_e32 v5, 7, v129
	v_lshrrev_b32_e32 v165, 3, v131
	v_cndmask_b32_e32 v0, v237, v0, vcc
	v_lshlrev_b32_e32 v161, 2, v0
	v_xor_b32_e32 v0, 32, v237
	v_cmp_lt_i32_e32 vcc, v0, v2
	v_readlane_b32 s2, v252, 45
	v_readlane_b32 s3, v252, 46
	v_cndmask_b32_e32 v0, v237, v0, vcc
	v_lshlrev_b32_e32 v162, 2, v0
	v_or_b32_e32 v0, v4, v5
	v_lshlrev_b32_e32 v163, 2, v0
	v_xor_b32_e32 v0, 8, v237
	v_cmp_lt_i32_e32 vcc, v0, v2
	v_lshlrev_b32_e32 v3, 13, v135
	v_lshlrev_b32_e32 v2, 3, v5
	v_cndmask_b32_e32 v0, v237, v0, vcc
	v_lshlrev_b32_e32 v164, 2, v0
	v_and_b32_e32 v0, 32, v129
	v_cmp_eq_u32_e64 s[40:41], 0, v0
	v_and_b32_e32 v0, 16, v129
	v_cmp_eq_u32_e64 s[42:43], 0, v0
	v_and_b32_e32 v0, 8, v129
	v_cmp_eq_u32_e64 s[44:45], 0, v0
	v_or_b32_e32 v0, v4, v165
	v_lshlrev_b32_e32 v166, 2, v0
	v_lshlrev_b32_e32 v0, 7, v165
	v_lshl_add_u64 v[8:9], s[2:3], 0, v[0:1]
	v_lshlrev_b32_e32 v0, 4, v5
	s_waitcnt vmcnt(0)
	v_lshl_add_u64 v[82:83], v[8:9], 0, v[0:1]
	v_lshlrev_b32_e32 v0, 1, v165
	v_lshlrev_b32_e32 v4, 6, v165
	v_lshlrev_b32_e32 v6, 6, v157
	v_and_b32_e32 v7, 56, v129
	v_lshl_or_b32 v0, v135, 11, v0
	v_cmp_gt_u32_e64 s[38:39], 8, v157
	s_mov_b32 s8, 0
	v_lshl_or_b32 v167, v157, 2, v3
	v_lshl_or_b32 v168, v131, 2, v3
	v_lshl_or_b32 v169, v7, 2, v3
	v_add_u32_e32 v170, 0x8000, v0
	v_lshlrev_b32_e32 v84, 1, v6
	v_lshlrev_b32_e32 v0, 1, v2
	v_lshlrev_b32_e32 v86, 1, v4
	s_branch .LBB0_1425

; __device__ __forceinline__ void dsa_item(const KP& p, int b, int tile, char* smem) {
;     ...
; #pragma unroll 1
;       for (int g8 = 0; g8 < 4; ++g8) {
;         h8 vv[8];
; #pragma unroll
;         for (int i = 0; i < 8; ++i) {
;           const int pos = (g8 * 8 + i) * 8 + rs;
;           const int s = (pos < nsel) ? (int)sel[tk * 256 + pos] : 0;
;           vv[i] = *(const h8*)(ub + (size_t)s * NU + C_BV + dc * 8);
;         }
; #pragma unroll
;         for (int i = 0; i < 8; ++i) {
;           const int pos = (g8 * 8 + i) * 8 + rs;
;           const f32x4 pa = *(const f32x4*)&pbuf[pos * 8];
;           const f32x4 pb = *(const f32x4*)&pbuf[pos * 8 + 4];
;           float vf[8];
; #pragma unroll
;           for (int e = 0; e < 8; ++e) vf[e] = (float)vv[i][e];
; #pragma unroll
;           for (int e = 0; e < 8; ++e) {
;             acc[0][e] += pa[0] * vf[e]; acc[1][e] += pa[1] * vf[e]; acc[2][e] += pa[2] * vf[e]; acc[3][e] += pa[3] * vf[e];
;             acc[4][e] += pb[0] * vf[e]; acc[5][e] += pb[1] * vf[e]; acc[6][e] += pb[2] * vf[e]; acc[7][e] += pb[3] * vf[e];
;           }
;         }
.LBB0_1513:
	s_add_u32 s2, s78, 0x3880
	s_addc_u32 s3, s79, 0
	ds_read_u16 v2, v170 offset:0
	ds_read_u16 v6, v170 offset:16
	ds_read_u16 v10, v170 offset:32
	ds_read_u16 v14, v170 offset:48
	ds_read_u16 v22, v170 offset:64
	ds_read_u16 v26, v170 offset:80
	ds_read_u16 v18, v170 offset:96
	ds_read_u16 v30, v170 offset:112
	v_mov_b32_e32 v34, v165
	v_cmp_lt_i32_e32 vcc, v34, v85
	s_waitcnt lgkmcnt(7)
	s_nop 0
	v_cndmask_b32_e32 v2, 0, v2, vcc
	v_mul_u32_u24_e32 v2, 0x1d00, v2
	v_lshl_add_u32 v2, v2, 1, v0
	global_load_dwordx4 v[2:5], v2, s[2:3]
	v_add_u32_e32 v35, 8, v34
	v_cmp_lt_i32_e32 vcc, v35, v85
	s_waitcnt lgkmcnt(6)
	s_nop 0
	v_cndmask_b32_e32 v6, 0, v6, vcc
	v_mul_u32_u24_e32 v6, 0x1d00, v6
	v_lshl_add_u32 v6, v6, 1, v0
	global_load_dwordx4 v[6:9], v6, s[2:3]
	v_add_u32_e32 v35, 16, v34
	v_cmp_lt_i32_e32 vcc, v35, v85
	s_waitcnt lgkmcnt(5)
	s_nop 0
	v_cndmask_b32_e32 v10, 0, v10, vcc
	v_mul_u32_u24_e32 v10, 0x1d00, v10
	v_lshl_add_u32 v10, v10, 1, v0
	global_load_dwordx4 v[10:13], v10, s[2:3]
	v_add_u32_e32 v35, 24, v34
	v_cmp_lt_i32_e32 vcc, v35, v85
	s_waitcnt lgkmcnt(4)
	s_nop 0
	v_cndmask_b32_e32 v14, 0, v14, vcc
	v_mul_u32_u24_e32 v14, 0x1d00, v14
	v_lshl_add_u32 v14, v14, 1, v0
	global_load_dwordx4 v[14:17], v14, s[2:3]
	v_add_u32_e32 v35, 32, v34
	v_cmp_lt_i32_e32 vcc, v35, v85
	s_waitcnt lgkmcnt(3)
	s_nop 0
	v_cndmask_b32_e32 v22, 0, v22, vcc
	v_mul_u32_u24_e32 v22, 0x1d00, v22
	v_lshl_add_u32 v22, v22, 1, v0
	global_load_dwordx4 v[22:25], v22, s[2:3]
	v_add_u32_e32 v35, 40, v34
	v_cmp_lt_i32_e32 vcc, v35, v85
	s_waitcnt lgkmcnt(2)
	s_nop 0
	v_cndmask_b32_e32 v26, 0, v26, vcc
	v_mul_u32_u24_e32 v26, 0x1d00, v26
	v_lshl_add_u32 v26, v26, 1, v0
	global_load_dwordx4 v[26:29], v26, s[2:3]
	v_add_u32_e32 v35, 48, v34
	v_cmp_lt_i32_e32 vcc, v35, v85
	s_waitcnt lgkmcnt(1)
	s_nop 0
	v_cndmask_b32_e32 v18, 0, v18, vcc
	v_mul_u32_u24_e32 v18, 0x1d00, v18
	v_lshl_add_u32 v18, v18, 1, v0
	global_load_dwordx4 v[18:21], v18, s[2:3]
	v_add_u32_e32 v35, 56, v34
	v_cmp_lt_i32_e32 vcc, v35, v85
	s_waitcnt lgkmcnt(0)
	s_nop 0
	v_cndmask_b32_e32 v30, 0, v30, vcc
	v_mul_u32_u24_e32 v30, 0x1d00, v30
	v_lshl_add_u32 v30, v30, 1, v0
	global_load_dwordx4 v[30:33], v30, s[2:3]
	ds_read_u16 v204, v170 offset:128
	ds_read_u16 v208, v170 offset:144
	ds_read_u16 v212, v170 offset:160
	ds_read_u16 v216, v170 offset:176
	ds_read_u16 v224, v170 offset:192
	ds_read_u16 v228, v170 offset:208
	ds_read_u16 v220, v170 offset:224
	ds_read_u16 v232, v170 offset:240
	v_add_u32_e32 v34, 64, v165
	v_cmp_lt_i32_e32 vcc, v34, v85
	s_waitcnt lgkmcnt(7)
	s_nop 0
	v_cndmask_b32_e32 v204, 0, v204, vcc
	v_mul_u32_u24_e32 v204, 0x1d00, v204
	v_lshl_add_u32 v204, v204, 1, v0
	global_load_dwordx4 v[204:207], v204, s[2:3]
	v_add_u32_e32 v35, 8, v34
	v_cmp_lt_i32_e32 vcc, v35, v85
	s_waitcnt lgkmcnt(6)
	s_nop 0
	v_cndmask_b32_e32 v208, 0, v208, vcc
	v_mul_u32_u24_e32 v208, 0x1d00, v208
	v_lshl_add_u32 v208, v208, 1, v0
	global_load_dwordx4 v[208:211], v208, s[2:3]
	v_add_u32_e32 v35, 16, v34
	v_cmp_lt_i32_e32 vcc, v35, v85
	s_waitcnt lgkmcnt(5)
	s_nop 0
	v_cndmask_b32_e32 v212, 0, v212, vcc
	v_mul_u32_u24_e32 v212, 0x1d00, v212
	v_lshl_add_u32 v212, v212, 1, v0
	global_load_dwordx4 v[212:215], v212, s[2:3]
	v_add_u32_e32 v35, 24, v34
	v_cmp_lt_i32_e32 vcc, v35, v85
	s_waitcnt lgkmcnt(4)
	s_nop 0
	v_cndmask_b32_e32 v216, 0, v216, vcc
	v_mul_u32_u24_e32 v216, 0x1d00, v216
	v_lshl_add_u32 v216, v216, 1, v0
	global_load_dwordx4 v[216:219], v216, s[2:3]
	v_add_u32_e32 v35, 32, v34
	v_cmp_lt_i32_e32 vcc, v35, v85
	s_waitcnt lgkmcnt(3)
	s_nop 0
	v_cndmask_b32_e32 v224, 0, v224, vcc
	v_mul_u32_u24_e32 v224, 0x1d00, v224
	v_lshl_add_u32 v224, v224, 1, v0
	global_load_dwordx4 v[224:227], v224, s[2:3]
	v_add_u32_e32 v35, 40, v34
	v_cmp_lt_i32_e32 vcc, v35, v85
	s_waitcnt lgkmcnt(2)
	s_nop 0
	v_cndmask_b32_e32 v228, 0, v228, vcc
	v_mul_u32_u24_e32 v228, 0x1d00, v228
	v_lshl_add_u32 v228, v228, 1, v0
	global_load_dwordx4 v[228:231], v228, s[2:3]
	v_add_u32_e32 v35, 48, v34
	v_cmp_lt_i32_e32 vcc, v35, v85
	s_waitcnt lgkmcnt(1)
	s_nop 0
	v_cndmask_b32_e32 v220, 0, v220, vcc
	v_mul_u32_u24_e32 v220, 0x1d00, v220
	v_lshl_add_u32 v220, v220, 1, v0
	global_load_dwordx4 v[220:223], v220, s[2:3]
	v_add_u32_e32 v35, 56, v34
	v_cmp_lt_i32_e32 vcc, v35, v85
	s_waitcnt lgkmcnt(0)
	s_nop 0
	v_cndmask_b32_e32 v232, 0, v232, vcc
	v_mul_u32_u24_e32 v232, 0x1d00, v232
	v_lshl_add_u32 v232, v232, 1, v0
	global_load_dwordx4 v[232:235], v232, s[2:3]
	s_waitcnt vmcnt(15)
	v_cvt_f32_f16_sdwa v175, v2 dst_sel:DWORD dst_unused:UNUSED_PAD src0_sel:WORD_1
	v_cvt_f32_f16_e32 v174, v2
	s_waitcnt vmcnt(14)
	v_cvt_f32_f16_sdwa v177, v6 dst_sel:DWORD dst_unused:UNUSED_PAD src0_sel:WORD_1
	v_cvt_f32_f16_e32 v176, v6
	ds_read_b128 v[58:61], v172
	ds_read_b128 v[34:37], v172 offset:16
	ds_read_b128 v[62:65], v172 offset:256
	ds_read_b128 v[38:41], v172 offset:272
	ds_read_b128 v[66:69], v172 offset:512
	ds_read_b128 v[42:45], v172 offset:528
	ds_read_b128 v[70:73], v172 offset:768
	ds_read_b128 v[46:49], v172 offset:784
	ds_read_b128 v[74:77], v172 offset:1024
	ds_read_b128 v[50:53], v172 offset:1040
	s_waitcnt vmcnt(13)
	v_cvt_f32_f16_sdwa v179, v10 dst_sel:DWORD dst_unused:UNUSED_PAD src0_sel:WORD_1
	v_cvt_f32_f16_e32 v178, v10
	s_waitcnt lgkmcnt(8)
	v_mov_b32_e32 v156, v37
	s_waitcnt vmcnt(12)
	v_cvt_f32_f16_sdwa v181, v14 dst_sel:DWORD dst_unused:UNUSED_PAD src0_sel:WORD_1
	v_cvt_f32_f16_e32 v180, v14
	v_pk_fma_f32 v[148:149], v[156:157], v[174:175], v[148:149] op_sel_hi:[0,1,1]
	s_waitcnt lgkmcnt(6)
	v_mov_b32_e32 v6, v41
	s_waitcnt vmcnt(11)
; __device__ __forceinline__ void dsa_item(const KP& p, int b, int tile, char* smem) {
;     ...
;         for (int i = 0; i < 8; ++i) {
;           const int pos = (g8 * 8 + i) * 8 + rs;
;           const f32x4 pa = *(const f32x4*)&pbuf[pos * 8];
;           const f32x4 pb = *(const f32x4*)&pbuf[pos * 8 + 4];
;           float vf[8];
; #pragma unroll
;           for (int e = 0; e < 8; ++e) vf[e] = (float)vv[i][e];
; #pragma unroll
;           for (int e = 0; e < 8; ++e) {
;             acc[0][e] += pa[0] * vf[e]; acc[1][e] += pa[1] * vf[e]; acc[2][e] += pa[2] * vf[e]; acc[3][e] += pa[3] * vf[e];
;             acc[4][e] += pb[0] * vf[e]; acc[5][e] += pb[1] * vf[e]; acc[6][e] += pb[2] * vf[e]; acc[7][e] += pb[3] * vf[e];
;           }
	v_cvt_f32_f16_sdwa v189, v22 dst_sel:DWORD dst_unused:UNUSED_PAD src0_sel:WORD_1
	v_cvt_f32_f16_e32 v188, v22
	v_pk_fma_f32 v[148:149], v[6:7], v[176:177], v[148:149] op_sel_hi:[0,1,1]
	s_waitcnt lgkmcnt(4)
	v_mov_b32_e32 v10, v45
	v_pk_fma_f32 v[148:149], v[10:11], v[178:179], v[148:149] op_sel_hi:[0,1,1]
	s_waitcnt lgkmcnt(2)
	v_mov_b32_e32 v22, v49
	v_pk_fma_f32 v[148:149], v[22:23], v[180:181], v[148:149] op_sel_hi:[0,1,1]
	s_waitcnt lgkmcnt(0)
	v_mov_b32_e32 v158, v53
	ds_read_b128 v[78:81], v172 offset:1280
	ds_read_b128 v[54:57], v172 offset:1296
	v_pk_fma_f32 v[190:191], v[158:159], v[188:189], v[148:149] op_sel_hi:[0,1,1]
	v_pk_fma_f32 v[148:149], v[58:59], v[174:175], v[154:155] op_sel_hi:[0,1,1]
	v_mov_b32_e32 v154, v61
	v_pk_fma_f32 v[152:153], v[58:59], v[174:175], v[152:153] op_sel:[1,0,0]
	v_pk_fma_f32 v[146:147], v[60:61], v[174:175], v[146:147] op_sel_hi:[0,1,1]
	v_pk_fma_f32 v[140:141], v[154:155], v[174:175], v[140:141] op_sel_hi:[0,1,1]
	v_mov_b32_e32 v194, v65
	v_pk_fma_f32 v[150:151], v[34:35], v[174:175], v[150:151] op_sel_hi:[0,1,1]
	v_pk_fma_f32 v[144:145], v[34:35], v[174:175], v[144:145] op_sel:[1,0,0]
	v_pk_fma_f32 v[138:139], v[36:37], v[174:175], v[138:139] op_sel_hi:[0,1,1]
	s_waitcnt vmcnt(10)
	v_cvt_f32_f16_sdwa v193, v26 dst_sel:DWORD dst_unused:UNUSED_PAD src0_sel:WORD_1
	v_cvt_f32_f16_e32 v192, v26
	v_pk_fma_f32 v[148:149], v[62:63], v[176:177], v[148:149] op_sel_hi:[0,1,1]
	v_pk_fma_f32 v[152:153], v[62:63], v[176:177], v[152:153] op_sel:[1,0,0]
	v_pk_fma_f32 v[146:147], v[64:65], v[176:177], v[146:147] op_sel_hi:[0,1,1]
	v_pk_fma_f32 v[140:141], v[194:195], v[176:177], v[140:141] op_sel_hi:[0,1,1]
	v_mov_b32_e32 v196, v69
	v_pk_fma_f32 v[150:151], v[38:39], v[176:177], v[150:151] op_sel_hi:[0,1,1]
	v_pk_fma_f32 v[144:145], v[38:39], v[176:177], v[144:145] op_sel:[1,0,0]
	v_pk_fma_f32 v[138:139], v[40:41], v[176:177], v[138:139] op_sel_hi:[0,1,1]
	v_cvt_f32_f16_sdwa v175, v3 dst_sel:DWORD dst_unused:UNUSED_PAD src0_sel:WORD_1
	v_cvt_f32_f16_e32 v174, v3
	v_pk_fma_f32 v[148:149], v[66:67], v[178:179], v[148:149] op_sel_hi:[0,1,1]
	v_pk_fma_f32 v[152:153], v[66:67], v[178:179], v[152:153] op_sel:[1,0,0]
	v_pk_fma_f32 v[146:147], v[68:69], v[178:179], v[146:147] op_sel_hi:[0,1,1]
	v_pk_fma_f32 v[140:141], v[196:197], v[178:179], v[140:141] op_sel_hi:[0,1,1]
	v_mov_b32_e32 v198, v73
	v_pk_fma_f32 v[150:151], v[42:43], v[178:179], v[150:151] op_sel_hi:[0,1,1]
	v_pk_fma_f32 v[144:145], v[42:43], v[178:179], v[144:145] op_sel:[1,0,0]
	v_pk_fma_f32 v[138:139], v[44:45], v[178:179], v[138:139] op_sel_hi:[0,1,1]
	v_cvt_f32_f16_sdwa v179, v7 dst_sel:DWORD dst_unused:UNUSED_PAD src0_sel:WORD_1
	v_cvt_f32_f16_e32 v178, v7
	v_pk_fma_f32 v[148:149], v[70:71], v[180:181], v[148:149] op_sel_hi:[0,1,1]
	v_pk_fma_f32 v[152:153], v[70:71], v[180:181], v[152:153] op_sel:[1,0,0]
	v_pk_fma_f32 v[146:147], v[72:73], v[180:181], v[146:147] op_sel_hi:[0,1,1]
	v_pk_fma_f32 v[140:141], v[198:199], v[180:181], v[140:141] op_sel_hi:[0,1,1]
	v_mov_b32_e32 v200, v77
	v_pk_fma_f32 v[150:151], v[46:47], v[180:181], v[150:151] op_sel_hi:[0,1,1]
	v_pk_fma_f32 v[144:145], v[46:47], v[180:181], v[144:145] op_sel:[1,0,0]
	v_pk_fma_f32 v[138:139], v[48:49], v[180:181], v[138:139] op_sel_hi:[0,1,1]
	v_cvt_f32_f16_sdwa v181, v11 dst_sel:DWORD dst_unused:UNUSED_PAD src0_sel:WORD_1
	v_cvt_f32_f16_e32 v180, v11
	v_pk_fma_f32 v[148:149], v[74:75], v[188:189], v[148:149] op_sel_hi:[0,1,1]
	v_pk_fma_f32 v[152:153], v[74:75], v[188:189], v[152:153] op_sel:[1,0,0]
	v_pk_fma_f32 v[146:147], v[76:77], v[188:189], v[146:147] op_sel_hi:[0,1,1]
	v_pk_fma_f32 v[140:141], v[200:201], v[188:189], v[140:141] op_sel_hi:[0,1,1]
	v_pk_fma_f32 v[150:151], v[50:51], v[188:189], v[150:151] op_sel_hi:[0,1,1]
	v_pk_fma_f32 v[144:145], v[50:51], v[188:189], v[144:145] op_sel:[1,0,0]
	v_pk_fma_f32 v[138:139], v[52:53], v[188:189], v[138:139] op_sel_hi:[0,1,1]
	s_waitcnt lgkmcnt(0)
	v_mov_b32_e32 v176, v57
	v_cvt_f32_f16_sdwa v189, v15 dst_sel:DWORD dst_unused:UNUSED_PAD src0_sel:WORD_1
	v_cvt_f32_f16_e32 v188, v15
	v_pk_fma_f32 v[2:3], v[56:57], v[192:193], v[138:139] op_sel_hi:[0,1,1]
	v_pk_fma_f32 v[138:139], v[176:177], v[192:193], v[190:191] op_sel_hi:[0,1,1]
	v_pk_fma_f32 v[132:133], v[156:157], v[174:175], v[132:133] op_sel_hi:[0,1,1]
	v_cvt_f32_f16_sdwa v191, v23 dst_sel:DWORD dst_unused:UNUSED_PAD src0_sel:WORD_1
	v_cvt_f32_f16_e32 v190, v23
	v_pk_fma_f32 v[14:15], v[6:7], v[178:179], v[132:133] op_sel_hi:[0,1,1]
	v_mov_b32_e32 v202, v81
	v_pk_fma_f32 v[14:15], v[10:11], v[180:181], v[14:15] op_sel_hi:[0,1,1]
	v_pk_fma_f32 v[148:149], v[78:79], v[192:193], v[148:149] op_sel_hi:[0,1,1]
	v_pk_fma_f32 v[152:153], v[78:79], v[192:193], v[152:153] op_sel:[1,0,0]
	v_pk_fma_f32 v[146:147], v[80:81], v[192:193], v[146:147] op_sel_hi:[0,1,1]
	v_pk_fma_f32 v[140:141], v[202:203], v[192:193], v[140:141] op_sel_hi:[0,1,1]
	v_pk_fma_f32 v[150:151], v[54:55], v[192:193], v[150:151] op_sel_hi:[0,1,1]
	v_pk_fma_f32 v[144:145], v[54:55], v[192:193], v[144:145] op_sel:[1,0,0]
	v_pk_fma_f32 v[14:15], v[22:23], v[188:189], v[14:15] op_sel_hi:[0,1,1]
	v_cvt_f32_f16_sdwa v193, v27 dst_sel:DWORD dst_unused:UNUSED_PAD src0_sel:WORD_1
	v_cvt_f32_f16_e32 v192, v27
	v_pk_fma_f32 v[26:27], v[58:59], v[174:175], v[134:135] op_sel:[1,0,0]
	v_pk_fma_f32 v[134:135], v[34:35], v[174:175], v[136:137] op_sel_hi:[0,1,1]
	v_cvt_f32_f16_sdwa v137, v4 dst_sel:DWORD dst_unused:UNUSED_PAD src0_sel:WORD_1
	v_cvt_f32_f16_e32 v136, v4
	v_pk_fma_f32 v[132:133], v[158:159], v[190:191], v[14:15] op_sel_hi:[0,1,1]
	v_pk_fma_f32 v[14:15], v[58:59], v[174:175], v[142:143] op_sel_hi:[0,1,1]
; __device__ __forceinline__ void dsa_item(const KP& p, int b, int tile, char* smem) {
;     ...
;         for (int i = 0; i < 8; ++i) {
;           const int pos = (g8 * 8 + i) * 8 + rs;
;           const f32x4 pa = *(const f32x4*)&pbuf[pos * 8];
;           const f32x4 pb = *(const f32x4*)&pbuf[pos * 8 + 4];
;           float vf[8];
; #pragma unroll
;           for (int e = 0; e < 8; ++e) vf[e] = (float)vv[i][e];
; #pragma unroll
;           for (int e = 0; e < 8; ++e) {
;             acc[0][e] += pa[0] * vf[e]; acc[1][e] += pa[1] * vf[e]; acc[2][e] += pa[2] * vf[e]; acc[3][e] += pa[3] * vf[e];
;             acc[4][e] += pb[0] * vf[e]; acc[5][e] += pb[1] * vf[e]; acc[6][e] += pb[2] * vf[e]; acc[7][e] += pb[3] * vf[e];
;           }
	v_cvt_f32_f16_sdwa v143, v8 dst_sel:DWORD dst_unused:UNUSED_PAD src0_sel:WORD_1
	v_cvt_f32_f16_e32 v142, v8
	v_pk_fma_f32 v[128:129], v[60:61], v[174:175], v[128:129] op_sel_hi:[0,1,1]
	v_pk_fma_f32 v[120:121], v[154:155], v[174:175], v[120:121] op_sel_hi:[0,1,1]
	v_pk_fma_f32 v[130:131], v[34:35], v[174:175], v[130:131] op_sel:[1,0,0]
	v_pk_fma_f32 v[122:123], v[36:37], v[174:175], v[122:123] op_sel_hi:[0,1,1]
	v_cvt_f32_f16_sdwa v175, v12 dst_sel:DWORD dst_unused:UNUSED_PAD src0_sel:WORD_1
	v_cvt_f32_f16_e32 v174, v12
	v_pk_fma_f32 v[14:15], v[62:63], v[178:179], v[14:15] op_sel_hi:[0,1,1]
	v_pk_fma_f32 v[26:27], v[62:63], v[178:179], v[26:27] op_sel:[1,0,0]
	v_pk_fma_f32 v[128:129], v[64:65], v[178:179], v[128:129] op_sel_hi:[0,1,1]
	v_pk_fma_f32 v[120:121], v[194:195], v[178:179], v[120:121] op_sel_hi:[0,1,1]
	v_pk_fma_f32 v[134:135], v[38:39], v[178:179], v[134:135] op_sel_hi:[0,1,1]
	v_pk_fma_f32 v[130:131], v[38:39], v[178:179], v[130:131] op_sel:[1,0,0]
	v_pk_fma_f32 v[122:123], v[40:41], v[178:179], v[122:123] op_sel_hi:[0,1,1]
	v_cvt_f32_f16_sdwa v179, v16 dst_sel:DWORD dst_unused:UNUSED_PAD src0_sel:WORD_1
	v_cvt_f32_f16_e32 v178, v16
	v_pk_fma_f32 v[14:15], v[66:67], v[180:181], v[14:15] op_sel_hi:[0,1,1]
	v_pk_fma_f32 v[26:27], v[66:67], v[180:181], v[26:27] op_sel:[1,0,0]
	v_pk_fma_f32 v[128:129], v[68:69], v[180:181], v[128:129] op_sel_hi:[0,1,1]
	v_pk_fma_f32 v[120:121], v[196:197], v[180:181], v[120:121] op_sel_hi:[0,1,1]
	v_pk_fma_f32 v[134:135], v[42:43], v[180:181], v[134:135] op_sel_hi:[0,1,1]
	v_pk_fma_f32 v[130:131], v[42:43], v[180:181], v[130:131] op_sel:[1,0,0]
	v_pk_fma_f32 v[122:123], v[44:45], v[180:181], v[122:123] op_sel_hi:[0,1,1]
	v_cvt_f32_f16_sdwa v181, v24 dst_sel:DWORD dst_unused:UNUSED_PAD src0_sel:WORD_1
	v_cvt_f32_f16_e32 v180, v24
	v_pk_fma_f32 v[106:107], v[36:37], v[136:137], v[106:107] op_sel_hi:[0,1,1]
	v_pk_fma_f32 v[14:15], v[70:71], v[188:189], v[14:15] op_sel_hi:[0,1,1]
	v_pk_fma_f32 v[26:27], v[70:71], v[188:189], v[26:27] op_sel:[1,0,0]
	v_pk_fma_f32 v[128:129], v[72:73], v[188:189], v[128:129] op_sel_hi:[0,1,1]
	v_pk_fma_f32 v[120:121], v[198:199], v[188:189], v[120:121] op_sel_hi:[0,1,1]
	v_pk_fma_f32 v[134:135], v[46:47], v[188:189], v[134:135] op_sel_hi:[0,1,1]
	v_pk_fma_f32 v[130:131], v[46:47], v[188:189], v[130:131] op_sel:[1,0,0]
	v_pk_fma_f32 v[122:123], v[48:49], v[188:189], v[122:123] op_sel_hi:[0,1,1]
	v_pk_fma_f32 v[114:115], v[156:157], v[136:137], v[114:115] op_sel_hi:[0,1,1]
	v_cvt_f32_f16_sdwa v189, v28 dst_sel:DWORD dst_unused:UNUSED_PAD src0_sel:WORD_1
	v_cvt_f32_f16_e32 v188, v28
	v_pk_fma_f32 v[124:125], v[58:59], v[136:137], v[124:125] op_sel_hi:[0,1,1]
	v_pk_fma_f32 v[116:117], v[58:59], v[136:137], v[116:117] op_sel:[1,0,0]
	v_pk_fma_f32 v[110:111], v[60:61], v[136:137], v[110:111] op_sel_hi:[0,1,1]
	v_pk_fma_f32 v[104:105], v[154:155], v[136:137], v[104:105] op_sel_hi:[0,1,1]
	v_pk_fma_f32 v[118:119], v[34:35], v[136:137], v[118:119] op_sel_hi:[0,1,1]
	v_pk_fma_f32 v[112:113], v[34:35], v[136:137], v[112:113] op_sel:[1,0,0]
	v_pk_fma_f32 v[106:107], v[40:41], v[142:143], v[106:107] op_sel_hi:[0,1,1]
	v_cvt_f32_f16_sdwa v137, v5 dst_sel:DWORD dst_unused:UNUSED_PAD src0_sel:WORD_1
	v_cvt_f32_f16_e32 v136, v5
	v_pk_fma_f32 v[106:107], v[44:45], v[174:175], v[106:107] op_sel_hi:[0,1,1]
	v_pk_fma_f32 v[106:107], v[48:49], v[178:179], v[106:107] op_sel_hi:[0,1,1]
	v_pk_fma_f32 v[4:5], v[52:53], v[180:181], v[106:107] op_sel_hi:[0,1,1]
	v_pk_fma_f32 v[106:107], v[56:57], v[188:189], v[4:5] op_sel_hi:[0,1,1]
	v_pk_fma_f32 v[4:5], v[156:157], v[136:137], v[98:99] op_sel_hi:[0,1,1]
	v_cvt_f32_f16_sdwa v99, v9 dst_sel:DWORD dst_unused:UNUSED_PAD src0_sel:WORD_1
	v_cvt_f32_f16_e32 v98, v9
	v_cvt_f32_f16_sdwa v9, v13 dst_sel:DWORD dst_unused:UNUSED_PAD src0_sel:WORD_1
	v_cvt_f32_f16_e32 v8, v13
	v_cvt_f32_f16_sdwa v13, v17 dst_sel:DWORD dst_unused:UNUSED_PAD src0_sel:WORD_1
	v_cvt_f32_f16_e32 v12, v17
	v_cvt_f32_f16_sdwa v17, v25 dst_sel:DWORD dst_unused:UNUSED_PAD src0_sel:WORD_1
	v_cvt_f32_f16_e32 v16, v25
	v_pk_fma_f32 v[4:5], v[6:7], v[98:99], v[4:5] op_sel_hi:[0,1,1]
	v_pk_fma_f32 v[114:115], v[6:7], v[142:143], v[114:115] op_sel_hi:[0,1,1]
	v_pk_fma_f32 v[4:5], v[10:11], v[8:9], v[4:5] op_sel_hi:[0,1,1]
	v_pk_fma_f32 v[114:115], v[10:11], v[174:175], v[114:115] op_sel_hi:[0,1,1]
	v_pk_fma_f32 v[4:5], v[22:23], v[12:13], v[4:5] op_sel_hi:[0,1,1]
	v_pk_fma_f32 v[114:115], v[22:23], v[178:179], v[114:115] op_sel_hi:[0,1,1]
	v_pk_fma_f32 v[22:23], v[158:159], v[16:17], v[4:5] op_sel_hi:[0,1,1]
	v_pk_fma_f32 v[4:5], v[58:59], v[136:137], v[108:109] op_sel_hi:[0,1,1]
	v_cvt_f32_f16_sdwa v25, v29 dst_sel:DWORD dst_unused:UNUSED_PAD src0_sel:WORD_1
	v_cvt_f32_f16_e32 v24, v29
	v_pk_fma_f32 v[4:5], v[62:63], v[98:99], v[4:5] op_sel_hi:[0,1,1]
	v_pk_fma_f32 v[4:5], v[66:67], v[8:9], v[4:5] op_sel_hi:[0,1,1]
	v_pk_fma_f32 v[4:5], v[70:71], v[12:13], v[4:5] op_sel_hi:[0,1,1]
	v_pk_fma_f32 v[4:5], v[74:75], v[16:17], v[4:5] op_sel_hi:[0,1,1]
	v_pk_fma_f32 v[28:29], v[78:79], v[24:25], v[4:5] op_sel_hi:[0,1,1]
	v_pk_fma_f32 v[4:5], v[58:59], v[136:137], v[100:101] op_sel:[1,0,0]
	v_pk_fma_f32 v[124:125], v[62:63], v[142:143], v[124:125] op_sel_hi:[0,1,1]
	v_pk_fma_f32 v[4:5], v[62:63], v[98:99], v[4:5] op_sel:[1,0,0]
	v_pk_fma_f32 v[116:117], v[62:63], v[142:143], v[116:117] op_sel:[1,0,0]
	v_pk_fma_f32 v[4:5], v[66:67], v[8:9], v[4:5] op_sel:[1,0,0]
	v_pk_fma_f32 v[110:111], v[64:65], v[142:143], v[110:111] op_sel_hi:[0,1,1]
	v_pk_fma_f32 v[4:5], v[70:71], v[12:13], v[4:5] op_sel:[1,0,0]
	v_pk_fma_f32 v[118:119], v[38:39], v[142:143], v[118:119] op_sel_hi:[0,1,1]
; __device__ __forceinline__ void dsa_item(const KP& p, int b, int tile, char* smem) {
;     ...
;         for (int i = 0; i < 8; ++i) {
;           const int pos = (g8 * 8 + i) * 8 + rs;
;           const f32x4 pa = *(const f32x4*)&pbuf[pos * 8];
;           const f32x4 pb = *(const f32x4*)&pbuf[pos * 8 + 4];
;           float vf[8];
; #pragma unroll
;           for (int e = 0; e < 8; ++e) vf[e] = (float)vv[i][e];
; #pragma unroll
;           for (int e = 0; e < 8; ++e) {
;             acc[0][e] += pa[0] * vf[e]; acc[1][e] += pa[1] * vf[e]; acc[2][e] += pa[2] * vf[e]; acc[3][e] += pa[3] * vf[e];
;             acc[4][e] += pb[0] * vf[e]; acc[5][e] += pb[1] * vf[e]; acc[6][e] += pb[2] * vf[e]; acc[7][e] += pb[3] * vf[e];
;           }
	v_pk_fma_f32 v[4:5], v[74:75], v[16:17], v[4:5] op_sel:[1,0,0]
	v_pk_fma_f32 v[112:113], v[38:39], v[142:143], v[112:113] op_sel:[1,0,0]
	v_pk_fma_f32 v[58:59], v[78:79], v[24:25], v[4:5] op_sel:[1,0,0]
	v_pk_fma_f32 v[4:5], v[60:61], v[136:137], v[94:95] op_sel_hi:[0,1,1]
	v_pk_fma_f32 v[4:5], v[64:65], v[98:99], v[4:5] op_sel_hi:[0,1,1]
	v_pk_fma_f32 v[4:5], v[68:69], v[8:9], v[4:5] op_sel_hi:[0,1,1]
	v_pk_fma_f32 v[4:5], v[72:73], v[12:13], v[4:5] op_sel_hi:[0,1,1]
	v_pk_fma_f32 v[4:5], v[76:77], v[16:17], v[4:5] op_sel_hi:[0,1,1]
	v_pk_fma_f32 v[60:61], v[80:81], v[24:25], v[4:5] op_sel_hi:[0,1,1]
	v_pk_fma_f32 v[4:5], v[154:155], v[136:137], v[90:91] op_sel_hi:[0,1,1]
	v_pk_fma_f32 v[4:5], v[194:195], v[98:99], v[4:5] op_sel_hi:[0,1,1]
	v_pk_fma_f32 v[4:5], v[196:197], v[8:9], v[4:5] op_sel_hi:[0,1,1]
	v_pk_fma_f32 v[4:5], v[198:199], v[12:13], v[4:5] op_sel_hi:[0,1,1]
	v_pk_fma_f32 v[4:5], v[200:201], v[16:17], v[4:5] op_sel_hi:[0,1,1]
	v_pk_fma_f32 v[62:63], v[202:203], v[24:25], v[4:5] op_sel_hi:[0,1,1]
	v_pk_fma_f32 v[4:5], v[34:35], v[136:137], v[102:103] op_sel_hi:[0,1,1]
	v_pk_fma_f32 v[4:5], v[38:39], v[98:99], v[4:5] op_sel_hi:[0,1,1]
	v_pk_fma_f32 v[4:5], v[42:43], v[8:9], v[4:5] op_sel_hi:[0,1,1]
	v_pk_fma_f32 v[4:5], v[46:47], v[12:13], v[4:5] op_sel_hi:[0,1,1]
	v_pk_fma_f32 v[4:5], v[50:51], v[16:17], v[4:5] op_sel_hi:[0,1,1]
	v_pk_fma_f32 v[64:65], v[54:55], v[24:25], v[4:5] op_sel_hi:[0,1,1]
	v_pk_fma_f32 v[4:5], v[34:35], v[136:137], v[96:97] op_sel:[1,0,0]
	v_pk_fma_f32 v[118:119], v[42:43], v[174:175], v[118:119] op_sel_hi:[0,1,1]
	v_pk_fma_f32 v[4:5], v[38:39], v[98:99], v[4:5] op_sel:[1,0,0]
	v_pk_fma_f32 v[112:113], v[42:43], v[174:175], v[112:113] op_sel:[1,0,0]
	v_pk_fma_f32 v[4:5], v[42:43], v[8:9], v[4:5] op_sel:[1,0,0]
	v_pk_fma_f32 v[118:119], v[46:47], v[178:179], v[118:119] op_sel_hi:[0,1,1]
	v_pk_fma_f32 v[4:5], v[46:47], v[12:13], v[4:5] op_sel:[1,0,0]
	v_pk_fma_f32 v[112:113], v[46:47], v[178:179], v[112:113] op_sel:[1,0,0]
	v_pk_fma_f32 v[4:5], v[50:51], v[16:17], v[4:5] op_sel:[1,0,0]
	s_waitcnt vmcnt(9)
	v_cvt_f32_f16_sdwa v43, v19 dst_sel:DWORD dst_unused:UNUSED_PAD src0_sel:WORD_1
	v_pk_fma_f32 v[34:35], v[54:55], v[24:25], v[4:5] op_sel:[1,0,0]
	v_pk_fma_f32 v[4:5], v[36:37], v[136:137], v[92:93] op_sel_hi:[0,1,1]
	v_pk_fma_f32 v[4:5], v[40:41], v[98:99], v[4:5] op_sel_hi:[0,1,1]
	v_pk_fma_f32 v[4:5], v[44:45], v[8:9], v[4:5] op_sel_hi:[0,1,1]
	v_pk_fma_f32 v[4:5], v[48:49], v[12:13], v[4:5] op_sel_hi:[0,1,1]
	v_pk_fma_f32 v[4:5], v[52:53], v[16:17], v[4:5] op_sel_hi:[0,1,1]
	v_pk_fma_f32 v[12:13], v[56:57], v[24:25], v[4:5] op_sel_hi:[0,1,1]
	ds_read_b128 v[4:7], v172 offset:1536
	ds_read_b128 v[8:11], v172 offset:1552
	v_pk_fma_f32 v[24:25], v[176:177], v[24:25], v[22:23] op_sel_hi:[0,1,1]
	v_cvt_f32_f16_sdwa v37, v18 dst_sel:DWORD dst_unused:UNUSED_PAD src0_sel:WORD_1
	v_cvt_f32_f16_e32 v36, v18
	v_cvt_f32_f16_e32 v42, v19
	v_cvt_f32_f16_sdwa v45, v20 dst_sel:DWORD dst_unused:UNUSED_PAD src0_sel:WORD_1
	v_cvt_f32_f16_e32 v44, v20
	v_cvt_f32_f16_sdwa v47, v21 dst_sel:DWORD dst_unused:UNUSED_PAD src0_sel:WORD_1
	v_cvt_f32_f16_e32 v46, v21
	ds_read_b128 v[16:19], v172 offset:1792
	ds_read_b128 v[20:23], v172 offset:1808
	s_waitcnt vmcnt(8)
	v_cvt_f32_f16_e32 v48, v30
	v_cvt_f32_f16_sdwa v49, v30 dst_sel:DWORD dst_unused:UNUSED_PAD src0_sel:WORD_1
	v_pk_fma_f32 v[124:125], v[66:67], v[174:175], v[124:125] op_sel_hi:[0,1,1]
	v_pk_fma_f32 v[116:117], v[66:67], v[174:175], v[116:117] op_sel:[1,0,0]
	v_pk_fma_f32 v[110:111], v[68:69], v[174:175], v[110:111] op_sel_hi:[0,1,1]
	v_pk_fma_f32 v[104:105], v[194:195], v[142:143], v[104:105] op_sel_hi:[0,1,1]
	v_cvt_f32_f16_e32 v30, v31
	v_cvt_f32_f16_sdwa v31, v31 dst_sel:DWORD dst_unused:UNUSED_PAD src0_sel:WORD_1
	v_pk_fma_f32 v[14:15], v[74:75], v[190:191], v[14:15] op_sel_hi:[0,1,1]
	v_pk_fma_f32 v[26:27], v[74:75], v[190:191], v[26:27] op_sel:[1,0,0]
	v_pk_fma_f32 v[128:129], v[76:77], v[190:191], v[128:129] op_sel_hi:[0,1,1]
	v_pk_fma_f32 v[134:135], v[50:51], v[190:191], v[134:135] op_sel_hi:[0,1,1]
	v_pk_fma_f32 v[130:131], v[50:51], v[190:191], v[130:131] op_sel:[1,0,0]
	v_pk_fma_f32 v[124:125], v[70:71], v[178:179], v[124:125] op_sel_hi:[0,1,1]
	v_pk_fma_f32 v[116:117], v[70:71], v[178:179], v[116:117] op_sel:[1,0,0]
	v_pk_fma_f32 v[110:111], v[72:73], v[178:179], v[110:111] op_sel_hi:[0,1,1]
	v_pk_fma_f32 v[104:105], v[196:197], v[174:175], v[104:105] op_sel_hi:[0,1,1]
	v_pk_fma_f32 v[118:119], v[50:51], v[180:181], v[118:119] op_sel_hi:[0,1,1]
	v_pk_fma_f32 v[112:113], v[50:51], v[180:181], v[112:113] op_sel:[1,0,0]
	v_cvt_f32_f16_e32 v50, v32
	v_cvt_f32_f16_sdwa v51, v32 dst_sel:DWORD dst_unused:UNUSED_PAD src0_sel:WORD_1
	v_pk_fma_f32 v[14:15], v[78:79], v[192:193], v[14:15] op_sel_hi:[0,1,1]
	v_pk_fma_f32 v[26:27], v[78:79], v[192:193], v[26:27] op_sel:[1,0,0]
	v_pk_fma_f32 v[128:129], v[80:81], v[192:193], v[128:129] op_sel_hi:[0,1,1]
	v_pk_fma_f32 v[120:121], v[200:201], v[190:191], v[120:121] op_sel_hi:[0,1,1]
	v_pk_fma_f32 v[122:123], v[52:53], v[190:191], v[122:123] op_sel_hi:[0,1,1]
	v_pk_fma_f32 v[124:125], v[74:75], v[180:181], v[124:125] op_sel_hi:[0,1,1]
	v_pk_fma_f32 v[116:117], v[74:75], v[180:181], v[116:117] op_sel:[1,0,0]
	v_pk_fma_f32 v[110:111], v[76:77], v[180:181], v[110:111] op_sel_hi:[0,1,1]
	v_pk_fma_f32 v[104:105], v[198:199], v[178:179], v[104:105] op_sel_hi:[0,1,1]
	s_waitcnt lgkmcnt(3)
	v_mov_b32_e32 v38, v7
	s_waitcnt lgkmcnt(2)
; __device__ __forceinline__ void dsa_item(const KP& p, int b, int tile, char* smem) {
;     ...
;       for (int g8 = 0; g8 < 4; ++g8) {
;         h8 vv[8];
; #pragma unroll
;         for (int i = 0; i < 8; ++i) {
;           const int pos = (g8 * 8 + i) * 8 + rs;
;           const int s = (pos < nsel) ? (int)sel[tk * 256 + pos] : 0;
;           vv[i] = *(const h8*)(ub + (size_t)s * NU + C_BV + dc * 8);
	v_mov_b32_e32 v40, v11
	v_cvt_f32_f16_e32 v32, v33
	v_cvt_f32_f16_sdwa v33, v33 dst_sel:DWORD dst_unused:UNUSED_PAD src0_sel:WORD_1
	v_pk_fma_f32 v[2:3], v[10:11], v[36:37], v[2:3] op_sel_hi:[0,1,1]
	v_pk_fma_f32 v[120:121], v[202:203], v[192:193], v[120:121] op_sel_hi:[0,1,1]
	v_pk_fma_f32 v[134:135], v[54:55], v[192:193], v[134:135] op_sel_hi:[0,1,1]
	v_pk_fma_f32 v[130:131], v[54:55], v[192:193], v[130:131] op_sel:[1,0,0]
	v_pk_fma_f32 v[122:123], v[56:57], v[192:193], v[122:123] op_sel_hi:[0,1,1]
	v_pk_fma_f32 v[132:133], v[176:177], v[192:193], v[132:133] op_sel_hi:[0,1,1]
	v_pk_fma_f32 v[114:115], v[158:159], v[180:181], v[114:115] op_sel_hi:[0,1,1]
	v_pk_fma_f32 v[124:125], v[78:79], v[188:189], v[124:125] op_sel_hi:[0,1,1]
	v_pk_fma_f32 v[116:117], v[78:79], v[188:189], v[116:117] op_sel:[1,0,0]
	v_pk_fma_f32 v[110:111], v[80:81], v[188:189], v[110:111] op_sel_hi:[0,1,1]
	v_pk_fma_f32 v[104:105], v[200:201], v[180:181], v[104:105] op_sel_hi:[0,1,1]
	v_pk_fma_f32 v[118:119], v[54:55], v[188:189], v[118:119] op_sel_hi:[0,1,1]
	v_pk_fma_f32 v[112:113], v[54:55], v[188:189], v[112:113] op_sel:[1,0,0]
	v_pk_fma_f32 v[52:53], v[4:5], v[36:37], v[148:149] op_sel_hi:[0,1,1]
	v_pk_fma_f32 v[54:55], v[4:5], v[36:37], v[152:153] op_sel:[1,0,0]
	v_pk_fma_f32 v[56:57], v[6:7], v[36:37], v[146:147] op_sel_hi:[0,1,1]
	v_pk_fma_f32 v[66:67], v[38:39], v[36:37], v[140:141] op_sel_hi:[0,1,1]
	v_pk_fma_f32 v[68:69], v[8:9], v[36:37], v[150:151] op_sel_hi:[0,1,1]
	v_pk_fma_f32 v[70:71], v[8:9], v[36:37], v[144:145] op_sel:[1,0,0]
	v_pk_fma_f32 v[36:37], v[40:41], v[36:37], v[138:139] op_sel_hi:[0,1,1]
	s_waitcnt lgkmcnt(1)
	v_mov_b32_e32 v72, v19
	s_waitcnt lgkmcnt(0)
	v_mov_b32_e32 v74, v23
	v_pk_fma_f32 v[138:139], v[22:23], v[48:49], v[2:3] op_sel_hi:[0,1,1]
	v_pk_fma_f32 v[2:3], v[4:5], v[42:43], v[14:15] op_sel_hi:[0,1,1]
	v_pk_fma_f32 v[14:15], v[4:5], v[42:43], v[26:27] op_sel:[1,0,0]
	v_pk_fma_f32 v[26:27], v[6:7], v[42:43], v[128:129] op_sel_hi:[0,1,1]
	v_pk_fma_f32 v[104:105], v[202:203], v[188:189], v[104:105] op_sel_hi:[0,1,1]
	v_pk_fma_f32 v[114:115], v[176:177], v[188:189], v[114:115] op_sel_hi:[0,1,1]
	v_pk_fma_f32 v[154:155], v[16:17], v[48:49], v[52:53] op_sel_hi:[0,1,1]
	v_pk_fma_f32 v[152:153], v[16:17], v[48:49], v[54:55] op_sel:[1,0,0]
	v_pk_fma_f32 v[146:147], v[18:19], v[48:49], v[56:57] op_sel_hi:[0,1,1]
	v_pk_fma_f32 v[140:141], v[72:73], v[48:49], v[66:67] op_sel_hi:[0,1,1]
	v_pk_fma_f32 v[150:151], v[20:21], v[48:49], v[68:69] op_sel_hi:[0,1,1]
	v_pk_fma_f32 v[144:145], v[20:21], v[48:49], v[70:71] op_sel:[1,0,0]
	v_pk_fma_f32 v[148:149], v[74:75], v[48:49], v[36:37] op_sel_hi:[0,1,1]
	v_pk_fma_f32 v[36:37], v[38:39], v[42:43], v[120:121] op_sel_hi:[0,1,1]
	v_pk_fma_f32 v[48:49], v[8:9], v[42:43], v[134:135] op_sel_hi:[0,1,1]
	v_pk_fma_f32 v[52:53], v[8:9], v[42:43], v[130:131] op_sel:[1,0,0]
	v_pk_fma_f32 v[54:55], v[10:11], v[42:43], v[122:123] op_sel_hi:[0,1,1]
	v_pk_fma_f32 v[42:43], v[40:41], v[42:43], v[132:133] op_sel_hi:[0,1,1]
	v_pk_fma_f32 v[142:143], v[16:17], v[30:31], v[2:3] op_sel_hi:[0,1,1]
	v_pk_fma_f32 v[134:135], v[16:17], v[30:31], v[14:15] op_sel:[1,0,0]
	v_pk_fma_f32 v[128:129], v[18:19], v[30:31], v[26:27] op_sel_hi:[0,1,1]
	v_pk_fma_f32 v[2:3], v[4:5], v[44:45], v[124:125] op_sel_hi:[0,1,1]
	v_pk_fma_f32 v[14:15], v[4:5], v[44:45], v[116:117] op_sel:[1,0,0]
	v_pk_fma_f32 v[26:27], v[6:7], v[44:45], v[110:111] op_sel_hi:[0,1,1]
	v_pk_fma_f32 v[120:121], v[72:73], v[30:31], v[36:37] op_sel_hi:[0,1,1]
	v_pk_fma_f32 v[136:137], v[20:21], v[30:31], v[48:49] op_sel_hi:[0,1,1]
	v_pk_fma_f32 v[130:131], v[20:21], v[30:31], v[52:53] op_sel:[1,0,0]
	v_pk_fma_f32 v[122:123], v[22:23], v[30:31], v[54:55] op_sel_hi:[0,1,1]
	v_pk_fma_f32 v[132:133], v[74:75], v[30:31], v[42:43] op_sel_hi:[0,1,1]
	v_pk_fma_f32 v[30:31], v[38:39], v[44:45], v[104:105] op_sel_hi:[0,1,1]
	v_pk_fma_f32 v[36:37], v[8:9], v[44:45], v[118:119] op_sel_hi:[0,1,1]
	v_pk_fma_f32 v[42:43], v[8:9], v[44:45], v[112:113] op_sel:[1,0,0]
	v_pk_fma_f32 v[48:49], v[10:11], v[44:45], v[106:107] op_sel_hi:[0,1,1]
	v_pk_fma_f32 v[44:45], v[40:41], v[44:45], v[114:115] op_sel_hi:[0,1,1]
	v_pk_fma_f32 v[124:125], v[16:17], v[50:51], v[2:3] op_sel_hi:[0,1,1]
	v_pk_fma_f32 v[116:117], v[16:17], v[50:51], v[14:15] op_sel:[1,0,0]
	v_pk_fma_f32 v[110:111], v[18:19], v[50:51], v[26:27] op_sel_hi:[0,1,1]
	v_pk_fma_f32 v[2:3], v[4:5], v[46:47], v[28:29] op_sel_hi:[0,1,1]
	v_pk_fma_f32 v[4:5], v[4:5], v[46:47], v[58:59] op_sel:[1,0,0]
	v_pk_fma_f32 v[6:7], v[6:7], v[46:47], v[60:61] op_sel_hi:[0,1,1]
	v_pk_fma_f32 v[14:15], v[38:39], v[46:47], v[62:63] op_sel_hi:[0,1,1]
	v_pk_fma_f32 v[26:27], v[8:9], v[46:47], v[64:65] op_sel_hi:[0,1,1]
	v_pk_fma_f32 v[8:9], v[8:9], v[46:47], v[34:35] op_sel:[1,0,0]
	v_pk_fma_f32 v[10:11], v[10:11], v[46:47], v[12:13] op_sel_hi:[0,1,1]
	v_pk_fma_f32 v[12:13], v[40:41], v[46:47], v[24:25] op_sel_hi:[0,1,1]
	v_pk_fma_f32 v[104:105], v[72:73], v[50:51], v[30:31] op_sel_hi:[0,1,1]
	v_pk_fma_f32 v[118:119], v[20:21], v[50:51], v[36:37] op_sel_hi:[0,1,1]
	v_pk_fma_f32 v[112:113], v[20:21], v[50:51], v[42:43] op_sel:[1,0,0]
	v_pk_fma_f32 v[106:107], v[22:23], v[50:51], v[48:49] op_sel_hi:[0,1,1]
	v_pk_fma_f32 v[114:115], v[74:75], v[50:51], v[44:45] op_sel_hi:[0,1,1]
	v_pk_fma_f32 v[108:109], v[16:17], v[32:33], v[2:3] op_sel_hi:[0,1,1]
	v_pk_fma_f32 v[100:101], v[16:17], v[32:33], v[4:5] op_sel:[1,0,0]
	v_pk_fma_f32 v[94:95], v[18:19], v[32:33], v[6:7] op_sel_hi:[0,1,1]
	v_pk_fma_f32 v[90:91], v[72:73], v[32:33], v[14:15] op_sel_hi:[0,1,1]
	v_pk_fma_f32 v[102:103], v[20:21], v[32:33], v[26:27] op_sel_hi:[0,1,1]
	v_pk_fma_f32 v[96:97], v[20:21], v[32:33], v[8:9] op_sel:[1,0,0]
	v_pk_fma_f32 v[92:93], v[22:23], v[32:33], v[10:11] op_sel_hi:[0,1,1]
	v_pk_fma_f32 v[98:99], v[74:75], v[32:33], v[12:13] op_sel_hi:[0,1,1]
	v_add_u32_e32 v172, 0x800, v172
	ds_read_u16 v2, v170 offset:256
	ds_read_u16 v6, v170 offset:272
	ds_read_u16 v10, v170 offset:288
	ds_read_u16 v14, v170 offset:304
	ds_read_u16 v22, v170 offset:320
	ds_read_u16 v26, v170 offset:336
	ds_read_u16 v18, v170 offset:352
	ds_read_u16 v30, v170 offset:368
	v_add_u32_e32 v34, 128, v165
	v_cmp_lt_i32_e32 vcc, v34, v85
	s_waitcnt lgkmcnt(7)
; __device__ __forceinline__ void dsa_item(const KP& p, int b, int tile, char* smem) {
;     ...
;         for (int i = 0; i < 8; ++i) {
;           const int pos = (g8 * 8 + i) * 8 + rs;
;           const int s = (pos < nsel) ? (int)sel[tk * 256 + pos] : 0;
;           vv[i] = *(const h8*)(ub + (size_t)s * NU + C_BV + dc * 8);
;         }
; #pragma unroll
;         for (int i = 0; i < 8; ++i) {
;           const int pos = (g8 * 8 + i) * 8 + rs;
;           const f32x4 pa = *(const f32x4*)&pbuf[pos * 8];
;           const f32x4 pb = *(const f32x4*)&pbuf[pos * 8 + 4];
;           float vf[8];
; #pragma unroll
;           for (int e = 0; e < 8; ++e) vf[e] = (float)vv[i][e];
; #pragma unroll
;           for (int e = 0; e < 8; ++e) {
;             acc[0][e] += pa[0] * vf[e]; acc[1][e] += pa[1] * vf[e]; acc[2][e] += pa[2] * vf[e]; acc[3][e] += pa[3] * vf[e];
;             acc[4][e] += pb[0] * vf[e]; acc[5][e] += pb[1] * vf[e]; acc[6][e] += pb[2] * vf[e]; acc[7][e] += pb[3] * vf[e];
;           }
	s_nop 0
	v_cndmask_b32_e32 v2, 0, v2, vcc
	v_mul_u32_u24_e32 v2, 0x1d00, v2
	v_lshl_add_u32 v2, v2, 1, v0
	global_load_dwordx4 v[2:5], v2, s[2:3]
	v_add_u32_e32 v35, 8, v34
	v_cmp_lt_i32_e32 vcc, v35, v85
	s_waitcnt lgkmcnt(6)
	s_nop 0
	v_cndmask_b32_e32 v6, 0, v6, vcc
	v_mul_u32_u24_e32 v6, 0x1d00, v6
	v_lshl_add_u32 v6, v6, 1, v0
	global_load_dwordx4 v[6:9], v6, s[2:3]
	v_add_u32_e32 v35, 16, v34
	v_cmp_lt_i32_e32 vcc, v35, v85
	s_waitcnt lgkmcnt(5)
	s_nop 0
	v_cndmask_b32_e32 v10, 0, v10, vcc
	v_mul_u32_u24_e32 v10, 0x1d00, v10
	v_lshl_add_u32 v10, v10, 1, v0
	global_load_dwordx4 v[10:13], v10, s[2:3]
	v_add_u32_e32 v35, 24, v34
	v_cmp_lt_i32_e32 vcc, v35, v85
	s_waitcnt lgkmcnt(4)
	s_nop 0
	v_cndmask_b32_e32 v14, 0, v14, vcc
	v_mul_u32_u24_e32 v14, 0x1d00, v14
	v_lshl_add_u32 v14, v14, 1, v0
	global_load_dwordx4 v[14:17], v14, s[2:3]
	v_add_u32_e32 v35, 32, v34
	v_cmp_lt_i32_e32 vcc, v35, v85
	s_waitcnt lgkmcnt(3)
	s_nop 0
	v_cndmask_b32_e32 v22, 0, v22, vcc
	v_mul_u32_u24_e32 v22, 0x1d00, v22
	v_lshl_add_u32 v22, v22, 1, v0
	global_load_dwordx4 v[22:25], v22, s[2:3]
	v_add_u32_e32 v35, 40, v34
	v_cmp_lt_i32_e32 vcc, v35, v85
	s_waitcnt lgkmcnt(2)
	s_nop 0
	v_cndmask_b32_e32 v26, 0, v26, vcc
	v_mul_u32_u24_e32 v26, 0x1d00, v26
	v_lshl_add_u32 v26, v26, 1, v0
	global_load_dwordx4 v[26:29], v26, s[2:3]
	v_add_u32_e32 v35, 48, v34
	v_cmp_lt_i32_e32 vcc, v35, v85
	s_waitcnt lgkmcnt(1)
	s_nop 0
	v_cndmask_b32_e32 v18, 0, v18, vcc
	v_mul_u32_u24_e32 v18, 0x1d00, v18
	v_lshl_add_u32 v18, v18, 1, v0
	global_load_dwordx4 v[18:21], v18, s[2:3]
	v_add_u32_e32 v35, 56, v34
	v_cmp_lt_i32_e32 vcc, v35, v85
	s_waitcnt lgkmcnt(0)
	s_nop 0
	v_cndmask_b32_e32 v30, 0, v30, vcc
	v_mul_u32_u24_e32 v30, 0x1d00, v30
	v_lshl_add_u32 v30, v30, 1, v0
	global_load_dwordx4 v[30:33], v30, s[2:3]
	s_waitcnt vmcnt(15)
	v_cvt_f32_f16_sdwa v175, v204 dst_sel:DWORD dst_unused:UNUSED_PAD src0_sel:WORD_1
	v_cvt_f32_f16_e32 v174, v204
	s_waitcnt vmcnt(14)
	v_cvt_f32_f16_sdwa v177, v208 dst_sel:DWORD dst_unused:UNUSED_PAD src0_sel:WORD_1
	v_cvt_f32_f16_e32 v176, v208
	ds_read_b128 v[58:61], v172
	ds_read_b128 v[34:37], v172 offset:16
	ds_read_b128 v[62:65], v172 offset:256
	ds_read_b128 v[38:41], v172 offset:272
	ds_read_b128 v[66:69], v172 offset:512
	ds_read_b128 v[42:45], v172 offset:528
	ds_read_b128 v[70:73], v172 offset:768
	ds_read_b128 v[46:49], v172 offset:784
	ds_read_b128 v[74:77], v172 offset:1024
	ds_read_b128 v[50:53], v172 offset:1040
	s_waitcnt vmcnt(13)
	v_cvt_f32_f16_sdwa v179, v212 dst_sel:DWORD dst_unused:UNUSED_PAD src0_sel:WORD_1
	v_cvt_f32_f16_e32 v178, v212
	s_waitcnt lgkmcnt(8)
	v_mov_b32_e32 v156, v37
	s_waitcnt vmcnt(12)
	v_cvt_f32_f16_sdwa v181, v216 dst_sel:DWORD dst_unused:UNUSED_PAD src0_sel:WORD_1
	v_cvt_f32_f16_e32 v180, v216
	v_pk_fma_f32 v[148:149], v[156:157], v[174:175], v[148:149] op_sel_hi:[0,1,1]
	s_waitcnt lgkmcnt(6)
	v_mov_b32_e32 v208, v41
	s_waitcnt vmcnt(11)
	v_cvt_f32_f16_sdwa v189, v224 dst_sel:DWORD dst_unused:UNUSED_PAD src0_sel:WORD_1
	v_cvt_f32_f16_e32 v188, v224
	v_pk_fma_f32 v[148:149], v[208:209], v[176:177], v[148:149] op_sel_hi:[0,1,1]
	s_waitcnt lgkmcnt(4)
	v_mov_b32_e32 v212, v45
	v_pk_fma_f32 v[148:149], v[212:213], v[178:179], v[148:149] op_sel_hi:[0,1,1]
	s_waitcnt lgkmcnt(2)
	v_mov_b32_e32 v224, v49
	v_pk_fma_f32 v[148:149], v[224:225], v[180:181], v[148:149] op_sel_hi:[0,1,1]
	s_waitcnt lgkmcnt(0)
	v_mov_b32_e32 v158, v53
	ds_read_b128 v[78:81], v172 offset:1280
	ds_read_b128 v[54:57], v172 offset:1296
	v_pk_fma_f32 v[190:191], v[158:159], v[188:189], v[148:149] op_sel_hi:[0,1,1]
	v_pk_fma_f32 v[148:149], v[58:59], v[174:175], v[154:155] op_sel_hi:[0,1,1]
	v_mov_b32_e32 v154, v61
	v_pk_fma_f32 v[152:153], v[58:59], v[174:175], v[152:153] op_sel:[1,0,0]
	v_pk_fma_f32 v[146:147], v[60:61], v[174:175], v[146:147] op_sel_hi:[0,1,1]
	v_pk_fma_f32 v[140:141], v[154:155], v[174:175], v[140:141] op_sel_hi:[0,1,1]
	v_mov_b32_e32 v194, v65
	v_pk_fma_f32 v[150:151], v[34:35], v[174:175], v[150:151] op_sel_hi:[0,1,1]
	v_pk_fma_f32 v[144:145], v[34:35], v[174:175], v[144:145] op_sel:[1,0,0]
	v_pk_fma_f32 v[138:139], v[36:37], v[174:175], v[138:139] op_sel_hi:[0,1,1]
	s_waitcnt vmcnt(10)
	v_cvt_f32_f16_sdwa v193, v228 dst_sel:DWORD dst_unused:UNUSED_PAD src0_sel:WORD_1
	v_cvt_f32_f16_e32 v192, v228
	v_pk_fma_f32 v[148:149], v[62:63], v[176:177], v[148:149] op_sel_hi:[0,1,1]
	v_pk_fma_f32 v[152:153], v[62:63], v[176:177], v[152:153] op_sel:[1,0,0]
	v_pk_fma_f32 v[146:147], v[64:65], v[176:177], v[146:147] op_sel_hi:[0,1,1]
	v_pk_fma_f32 v[140:141], v[194:195], v[176:177], v[140:141] op_sel_hi:[0,1,1]
	v_mov_b32_e32 v196, v69
	v_pk_fma_f32 v[150:151], v[38:39], v[176:177], v[150:151] op_sel_hi:[0,1,1]
	v_pk_fma_f32 v[144:145], v[38:39], v[176:177], v[144:145] op_sel:[1,0,0]
	v_pk_fma_f32 v[138:139], v[40:41], v[176:177], v[138:139] op_sel_hi:[0,1,1]
	v_cvt_f32_f16_sdwa v175, v205 dst_sel:DWORD dst_unused:UNUSED_PAD src0_sel:WORD_1
	v_cvt_f32_f16_e32 v174, v205
	v_pk_fma_f32 v[148:149], v[66:67], v[178:179], v[148:149] op_sel_hi:[0,1,1]
	v_pk_fma_f32 v[152:153], v[66:67], v[178:179], v[152:153] op_sel:[1,0,0]
	v_pk_fma_f32 v[146:147], v[68:69], v[178:179], v[146:147] op_sel_hi:[0,1,1]
	v_pk_fma_f32 v[140:141], v[196:197], v[178:179], v[140:141] op_sel_hi:[0,1,1]
	v_mov_b32_e32 v198, v73
	v_pk_fma_f32 v[150:151], v[42:43], v[178:179], v[150:151] op_sel_hi:[0,1,1]
	v_pk_fma_f32 v[144:145], v[42:43], v[178:179], v[144:145] op_sel:[1,0,0]
	v_pk_fma_f32 v[138:139], v[44:45], v[178:179], v[138:139] op_sel_hi:[0,1,1]
	v_cvt_f32_f16_sdwa v179, v209 dst_sel:DWORD dst_unused:UNUSED_PAD src0_sel:WORD_1
	v_cvt_f32_f16_e32 v178, v209
	v_pk_fma_f32 v[148:149], v[70:71], v[180:181], v[148:149] op_sel_hi:[0,1,1]
	v_pk_fma_f32 v[152:153], v[70:71], v[180:181], v[152:153] op_sel:[1,0,0]
	v_pk_fma_f32 v[146:147], v[72:73], v[180:181], v[146:147] op_sel_hi:[0,1,1]
	v_pk_fma_f32 v[140:141], v[198:199], v[180:181], v[140:141] op_sel_hi:[0,1,1]
	v_mov_b32_e32 v200, v77
	v_pk_fma_f32 v[150:151], v[46:47], v[180:181], v[150:151] op_sel_hi:[0,1,1]
	v_pk_fma_f32 v[144:145], v[46:47], v[180:181], v[144:145] op_sel:[1,0,0]
	v_pk_fma_f32 v[138:139], v[48:49], v[180:181], v[138:139] op_sel_hi:[0,1,1]
	v_cvt_f32_f16_sdwa v181, v213 dst_sel:DWORD dst_unused:UNUSED_PAD src0_sel:WORD_1
	v_cvt_f32_f16_e32 v180, v213
	v_pk_fma_f32 v[148:149], v[74:75], v[188:189], v[148:149] op_sel_hi:[0,1,1]
	v_pk_fma_f32 v[152:153], v[74:75], v[188:189], v[152:153] op_sel:[1,0,0]
	v_pk_fma_f32 v[146:147], v[76:77], v[188:189], v[146:147] op_sel_hi:[0,1,1]
	v_pk_fma_f32 v[140:141], v[200:201], v[188:189], v[140:141] op_sel_hi:[0,1,1]
	v_pk_fma_f32 v[150:151], v[50:51], v[188:189], v[150:151] op_sel_hi:[0,1,1]
	v_pk_fma_f32 v[144:145], v[50:51], v[188:189], v[144:145] op_sel:[1,0,0]
	v_pk_fma_f32 v[138:139], v[52:53], v[188:189], v[138:139] op_sel_hi:[0,1,1]
	s_waitcnt lgkmcnt(0)
; __device__ __forceinline__ void dsa_item(const KP& p, int b, int tile, char* smem) {
;     ...
;         for (int i = 0; i < 8; ++i) {
;           const int pos = (g8 * 8 + i) * 8 + rs;
;           const f32x4 pa = *(const f32x4*)&pbuf[pos * 8];
;           const f32x4 pb = *(const f32x4*)&pbuf[pos * 8 + 4];
;           float vf[8];
; #pragma unroll
;           for (int e = 0; e < 8; ++e) vf[e] = (float)vv[i][e];
; #pragma unroll
;           for (int e = 0; e < 8; ++e) {
;             acc[0][e] += pa[0] * vf[e]; acc[1][e] += pa[1] * vf[e]; acc[2][e] += pa[2] * vf[e]; acc[3][e] += pa[3] * vf[e];
;             acc[4][e] += pb[0] * vf[e]; acc[5][e] += pb[1] * vf[e]; acc[6][e] += pb[2] * vf[e]; acc[7][e] += pb[3] * vf[e];
;           }
	v_mov_b32_e32 v176, v57
	v_cvt_f32_f16_sdwa v189, v217 dst_sel:DWORD dst_unused:UNUSED_PAD src0_sel:WORD_1
	v_cvt_f32_f16_e32 v188, v217
	v_pk_fma_f32 v[204:205], v[56:57], v[192:193], v[138:139] op_sel_hi:[0,1,1]
	v_pk_fma_f32 v[138:139], v[176:177], v[192:193], v[190:191] op_sel_hi:[0,1,1]
	v_pk_fma_f32 v[132:133], v[156:157], v[174:175], v[132:133] op_sel_hi:[0,1,1]
	v_cvt_f32_f16_sdwa v191, v225 dst_sel:DWORD dst_unused:UNUSED_PAD src0_sel:WORD_1
	v_cvt_f32_f16_e32 v190, v225
	v_pk_fma_f32 v[216:217], v[208:209], v[178:179], v[132:133] op_sel_hi:[0,1,1]
	v_mov_b32_e32 v202, v81
	v_pk_fma_f32 v[216:217], v[212:213], v[180:181], v[216:217] op_sel_hi:[0,1,1]
	v_pk_fma_f32 v[148:149], v[78:79], v[192:193], v[148:149] op_sel_hi:[0,1,1]
	v_pk_fma_f32 v[152:153], v[78:79], v[192:193], v[152:153] op_sel:[1,0,0]
	v_pk_fma_f32 v[146:147], v[80:81], v[192:193], v[146:147] op_sel_hi:[0,1,1]
	v_pk_fma_f32 v[140:141], v[202:203], v[192:193], v[140:141] op_sel_hi:[0,1,1]
	v_pk_fma_f32 v[150:151], v[54:55], v[192:193], v[150:151] op_sel_hi:[0,1,1]
	v_pk_fma_f32 v[144:145], v[54:55], v[192:193], v[144:145] op_sel:[1,0,0]
	v_pk_fma_f32 v[216:217], v[224:225], v[188:189], v[216:217] op_sel_hi:[0,1,1]
	v_cvt_f32_f16_sdwa v193, v229 dst_sel:DWORD dst_unused:UNUSED_PAD src0_sel:WORD_1
	v_cvt_f32_f16_e32 v192, v229
	v_pk_fma_f32 v[228:229], v[58:59], v[174:175], v[134:135] op_sel:[1,0,0]
	v_pk_fma_f32 v[134:135], v[34:35], v[174:175], v[136:137] op_sel_hi:[0,1,1]
	v_cvt_f32_f16_sdwa v137, v206 dst_sel:DWORD dst_unused:UNUSED_PAD src0_sel:WORD_1
	v_cvt_f32_f16_e32 v136, v206
	v_pk_fma_f32 v[132:133], v[158:159], v[190:191], v[216:217] op_sel_hi:[0,1,1]
	v_pk_fma_f32 v[216:217], v[58:59], v[174:175], v[142:143] op_sel_hi:[0,1,1]
	v_cvt_f32_f16_sdwa v143, v210 dst_sel:DWORD dst_unused:UNUSED_PAD src0_sel:WORD_1
	v_cvt_f32_f16_e32 v142, v210
	v_pk_fma_f32 v[128:129], v[60:61], v[174:175], v[128:129] op_sel_hi:[0,1,1]
	v_pk_fma_f32 v[120:121], v[154:155], v[174:175], v[120:121] op_sel_hi:[0,1,1]
	v_pk_fma_f32 v[130:131], v[34:35], v[174:175], v[130:131] op_sel:[1,0,0]
	v_pk_fma_f32 v[122:123], v[36:37], v[174:175], v[122:123] op_sel_hi:[0,1,1]
	v_cvt_f32_f16_sdwa v175, v214 dst_sel:DWORD dst_unused:UNUSED_PAD src0_sel:WORD_1
	v_cvt_f32_f16_e32 v174, v214
	v_pk_fma_f32 v[216:217], v[62:63], v[178:179], v[216:217] op_sel_hi:[0,1,1]
	v_pk_fma_f32 v[228:229], v[62:63], v[178:179], v[228:229] op_sel:[1,0,0]
	v_pk_fma_f32 v[128:129], v[64:65], v[178:179], v[128:129] op_sel_hi:[0,1,1]
	v_pk_fma_f32 v[120:121], v[194:195], v[178:179], v[120:121] op_sel_hi:[0,1,1]
	v_pk_fma_f32 v[134:135], v[38:39], v[178:179], v[134:135] op_sel_hi:[0,1,1]
	v_pk_fma_f32 v[130:131], v[38:39], v[178:179], v[130:131] op_sel:[1,0,0]
	v_pk_fma_f32 v[122:123], v[40:41], v[178:179], v[122:123] op_sel_hi:[0,1,1]
	v_cvt_f32_f16_sdwa v179, v218 dst_sel:DWORD dst_unused:UNUSED_PAD src0_sel:WORD_1
	v_cvt_f32_f16_e32 v178, v218
	v_pk_fma_f32 v[216:217], v[66:67], v[180:181], v[216:217] op_sel_hi:[0,1,1]
	v_pk_fma_f32 v[228:229], v[66:67], v[180:181], v[228:229] op_sel:[1,0,0]
	v_pk_fma_f32 v[128:129], v[68:69], v[180:181], v[128:129] op_sel_hi:[0,1,1]
	v_pk_fma_f32 v[120:121], v[196:197], v[180:181], v[120:121] op_sel_hi:[0,1,1]
	v_pk_fma_f32 v[134:135], v[42:43], v[180:181], v[134:135] op_sel_hi:[0,1,1]
	v_pk_fma_f32 v[130:131], v[42:43], v[180:181], v[130:131] op_sel:[1,0,0]
	v_pk_fma_f32 v[122:123], v[44:45], v[180:181], v[122:123] op_sel_hi:[0,1,1]
	v_cvt_f32_f16_sdwa v181, v226 dst_sel:DWORD dst_unused:UNUSED_PAD src0_sel:WORD_1
	v_cvt_f32_f16_e32 v180, v226
	v_pk_fma_f32 v[106:107], v[36:37], v[136:137], v[106:107] op_sel_hi:[0,1,1]
	v_pk_fma_f32 v[216:217], v[70:71], v[188:189], v[216:217] op_sel_hi:[0,1,1]
	v_pk_fma_f32 v[228:229], v[70:71], v[188:189], v[228:229] op_sel:[1,0,0]
	v_pk_fma_f32 v[128:129], v[72:73], v[188:189], v[128:129] op_sel_hi:[0,1,1]
	v_pk_fma_f32 v[120:121], v[198:199], v[188:189], v[120:121] op_sel_hi:[0,1,1]
	v_pk_fma_f32 v[134:135], v[46:47], v[188:189], v[134:135] op_sel_hi:[0,1,1]
	v_pk_fma_f32 v[130:131], v[46:47], v[188:189], v[130:131] op_sel:[1,0,0]
	v_pk_fma_f32 v[122:123], v[48:49], v[188:189], v[122:123] op_sel_hi:[0,1,1]
	v_pk_fma_f32 v[114:115], v[156:157], v[136:137], v[114:115] op_sel_hi:[0,1,1]
	v_cvt_f32_f16_sdwa v189, v230 dst_sel:DWORD dst_unused:UNUSED_PAD src0_sel:WORD_1
	v_cvt_f32_f16_e32 v188, v230
	v_pk_fma_f32 v[124:125], v[58:59], v[136:137], v[124:125] op_sel_hi:[0,1,1]
	v_pk_fma_f32 v[116:117], v[58:59], v[136:137], v[116:117] op_sel:[1,0,0]
	v_pk_fma_f32 v[110:111], v[60:61], v[136:137], v[110:111] op_sel_hi:[0,1,1]
	v_pk_fma_f32 v[104:105], v[154:155], v[136:137], v[104:105] op_sel_hi:[0,1,1]
	v_pk_fma_f32 v[118:119], v[34:35], v[136:137], v[118:119] op_sel_hi:[0,1,1]
	v_pk_fma_f32 v[112:113], v[34:35], v[136:137], v[112:113] op_sel:[1,0,0]
	v_pk_fma_f32 v[106:107], v[40:41], v[142:143], v[106:107] op_sel_hi:[0,1,1]
	v_cvt_f32_f16_sdwa v137, v207 dst_sel:DWORD dst_unused:UNUSED_PAD src0_sel:WORD_1
	v_cvt_f32_f16_e32 v136, v207
	v_pk_fma_f32 v[106:107], v[44:45], v[174:175], v[106:107] op_sel_hi:[0,1,1]
	v_pk_fma_f32 v[106:107], v[48:49], v[178:179], v[106:107] op_sel_hi:[0,1,1]
	v_pk_fma_f32 v[206:207], v[52:53], v[180:181], v[106:107] op_sel_hi:[0,1,1]
	v_pk_fma_f32 v[106:107], v[56:57], v[188:189], v[206:207] op_sel_hi:[0,1,1]
	v_pk_fma_f32 v[206:207], v[156:157], v[136:137], v[98:99] op_sel_hi:[0,1,1]
	v_cvt_f32_f16_sdwa v99, v211 dst_sel:DWORD dst_unused:UNUSED_PAD src0_sel:WORD_1
	v_cvt_f32_f16_e32 v98, v211
	v_cvt_f32_f16_sdwa v211, v215 dst_sel:DWORD dst_unused:UNUSED_PAD src0_sel:WORD_1
	v_cvt_f32_f16_e32 v210, v215
; __device__ __forceinline__ void dsa_item(const KP& p, int b, int tile, char* smem) {
;     ...
;         for (int i = 0; i < 8; ++i) {
;           const int pos = (g8 * 8 + i) * 8 + rs;
;           const f32x4 pa = *(const f32x4*)&pbuf[pos * 8];
;           const f32x4 pb = *(const f32x4*)&pbuf[pos * 8 + 4];
;           float vf[8];
; #pragma unroll
;           for (int e = 0; e < 8; ++e) vf[e] = (float)vv[i][e];
; #pragma unroll
;           for (int e = 0; e < 8; ++e) {
;             acc[0][e] += pa[0] * vf[e]; acc[1][e] += pa[1] * vf[e]; acc[2][e] += pa[2] * vf[e]; acc[3][e] += pa[3] * vf[e];
;             acc[4][e] += pb[0] * vf[e]; acc[5][e] += pb[1] * vf[e]; acc[6][e] += pb[2] * vf[e]; acc[7][e] += pb[3] * vf[e];
;           }
	v_cvt_f32_f16_sdwa v215, v219 dst_sel:DWORD dst_unused:UNUSED_PAD src0_sel:WORD_1
	v_cvt_f32_f16_e32 v214, v219
	v_cvt_f32_f16_sdwa v219, v227 dst_sel:DWORD dst_unused:UNUSED_PAD src0_sel:WORD_1
	v_cvt_f32_f16_e32 v218, v227
	v_pk_fma_f32 v[206:207], v[208:209], v[98:99], v[206:207] op_sel_hi:[0,1,1]
	v_pk_fma_f32 v[114:115], v[208:209], v[142:143], v[114:115] op_sel_hi:[0,1,1]
	v_pk_fma_f32 v[206:207], v[212:213], v[210:211], v[206:207] op_sel_hi:[0,1,1]
	v_pk_fma_f32 v[114:115], v[212:213], v[174:175], v[114:115] op_sel_hi:[0,1,1]
	v_pk_fma_f32 v[206:207], v[224:225], v[214:215], v[206:207] op_sel_hi:[0,1,1]
	v_pk_fma_f32 v[114:115], v[224:225], v[178:179], v[114:115] op_sel_hi:[0,1,1]
	v_pk_fma_f32 v[224:225], v[158:159], v[218:219], v[206:207] op_sel_hi:[0,1,1]
	v_pk_fma_f32 v[206:207], v[58:59], v[136:137], v[108:109] op_sel_hi:[0,1,1]
	v_cvt_f32_f16_sdwa v227, v231 dst_sel:DWORD dst_unused:UNUSED_PAD src0_sel:WORD_1
	v_cvt_f32_f16_e32 v226, v231
	v_pk_fma_f32 v[206:207], v[62:63], v[98:99], v[206:207] op_sel_hi:[0,1,1]
	v_pk_fma_f32 v[206:207], v[66:67], v[210:211], v[206:207] op_sel_hi:[0,1,1]
	v_pk_fma_f32 v[206:207], v[70:71], v[214:215], v[206:207] op_sel_hi:[0,1,1]
	v_pk_fma_f32 v[206:207], v[74:75], v[218:219], v[206:207] op_sel_hi:[0,1,1]
	v_pk_fma_f32 v[230:231], v[78:79], v[226:227], v[206:207] op_sel_hi:[0,1,1]
	v_pk_fma_f32 v[206:207], v[58:59], v[136:137], v[100:101] op_sel:[1,0,0]
	v_pk_fma_f32 v[124:125], v[62:63], v[142:143], v[124:125] op_sel_hi:[0,1,1]
	v_pk_fma_f32 v[206:207], v[62:63], v[98:99], v[206:207] op_sel:[1,0,0]
	v_pk_fma_f32 v[116:117], v[62:63], v[142:143], v[116:117] op_sel:[1,0,0]
	v_pk_fma_f32 v[206:207], v[66:67], v[210:211], v[206:207] op_sel:[1,0,0]
	v_pk_fma_f32 v[110:111], v[64:65], v[142:143], v[110:111] op_sel_hi:[0,1,1]
	v_pk_fma_f32 v[206:207], v[70:71], v[214:215], v[206:207] op_sel:[1,0,0]
	v_pk_fma_f32 v[118:119], v[38:39], v[142:143], v[118:119] op_sel_hi:[0,1,1]
	v_pk_fma_f32 v[206:207], v[74:75], v[218:219], v[206:207] op_sel:[1,0,0]
	v_pk_fma_f32 v[112:113], v[38:39], v[142:143], v[112:113] op_sel:[1,0,0]
	v_pk_fma_f32 v[58:59], v[78:79], v[226:227], v[206:207] op_sel:[1,0,0]
	v_pk_fma_f32 v[206:207], v[60:61], v[136:137], v[94:95] op_sel_hi:[0,1,1]
	v_pk_fma_f32 v[206:207], v[64:65], v[98:99], v[206:207] op_sel_hi:[0,1,1]
	v_pk_fma_f32 v[206:207], v[68:69], v[210:211], v[206:207] op_sel_hi:[0,1,1]
	v_pk_fma_f32 v[206:207], v[72:73], v[214:215], v[206:207] op_sel_hi:[0,1,1]
	v_pk_fma_f32 v[206:207], v[76:77], v[218:219], v[206:207] op_sel_hi:[0,1,1]
	v_pk_fma_f32 v[60:61], v[80:81], v[226:227], v[206:207] op_sel_hi:[0,1,1]
	v_pk_fma_f32 v[206:207], v[154:155], v[136:137], v[90:91] op_sel_hi:[0,1,1]
	v_pk_fma_f32 v[206:207], v[194:195], v[98:99], v[206:207] op_sel_hi:[0,1,1]
	v_pk_fma_f32 v[206:207], v[196:197], v[210:211], v[206:207] op_sel_hi:[0,1,1]
	v_pk_fma_f32 v[206:207], v[198:199], v[214:215], v[206:207] op_sel_hi:[0,1,1]
	v_pk_fma_f32 v[206:207], v[200:201], v[218:219], v[206:207] op_sel_hi:[0,1,1]
	v_pk_fma_f32 v[62:63], v[202:203], v[226:227], v[206:207] op_sel_hi:[0,1,1]
	v_pk_fma_f32 v[206:207], v[34:35], v[136:137], v[102:103] op_sel_hi:[0,1,1]
	v_pk_fma_f32 v[206:207], v[38:39], v[98:99], v[206:207] op_sel_hi:[0,1,1]
	v_pk_fma_f32 v[206:207], v[42:43], v[210:211], v[206:207] op_sel_hi:[0,1,1]
	v_pk_fma_f32 v[206:207], v[46:47], v[214:215], v[206:207] op_sel_hi:[0,1,1]
	v_pk_fma_f32 v[206:207], v[50:51], v[218:219], v[206:207] op_sel_hi:[0,1,1]
	v_pk_fma_f32 v[64:65], v[54:55], v[226:227], v[206:207] op_sel_hi:[0,1,1]
	v_pk_fma_f32 v[206:207], v[34:35], v[136:137], v[96:97] op_sel:[1,0,0]
	v_pk_fma_f32 v[118:119], v[42:43], v[174:175], v[118:119] op_sel_hi:[0,1,1]
	v_pk_fma_f32 v[206:207], v[38:39], v[98:99], v[206:207] op_sel:[1,0,0]
	v_pk_fma_f32 v[112:113], v[42:43], v[174:175], v[112:113] op_sel:[1,0,0]
	v_pk_fma_f32 v[206:207], v[42:43], v[210:211], v[206:207] op_sel:[1,0,0]
	v_pk_fma_f32 v[118:119], v[46:47], v[178:179], v[118:119] op_sel_hi:[0,1,1]
	v_pk_fma_f32 v[206:207], v[46:47], v[214:215], v[206:207] op_sel:[1,0,0]
	v_pk_fma_f32 v[112:113], v[46:47], v[178:179], v[112:113] op_sel:[1,0,0]
	v_pk_fma_f32 v[206:207], v[50:51], v[218:219], v[206:207] op_sel:[1,0,0]
	s_waitcnt vmcnt(9)
	v_cvt_f32_f16_sdwa v43, v221 dst_sel:DWORD dst_unused:UNUSED_PAD src0_sel:WORD_1
	v_pk_fma_f32 v[34:35], v[54:55], v[226:227], v[206:207] op_sel:[1,0,0]
	v_pk_fma_f32 v[206:207], v[36:37], v[136:137], v[92:93] op_sel_hi:[0,1,1]
	v_pk_fma_f32 v[206:207], v[40:41], v[98:99], v[206:207] op_sel_hi:[0,1,1]
	v_pk_fma_f32 v[206:207], v[44:45], v[210:211], v[206:207] op_sel_hi:[0,1,1]
	v_pk_fma_f32 v[206:207], v[48:49], v[214:215], v[206:207] op_sel_hi:[0,1,1]
	v_pk_fma_f32 v[206:207], v[52:53], v[218:219], v[206:207] op_sel_hi:[0,1,1]
	v_pk_fma_f32 v[214:215], v[56:57], v[226:227], v[206:207] op_sel_hi:[0,1,1]
	ds_read_b128 v[206:209], v172 offset:1536
	ds_read_b128 v[210:213], v172 offset:1552
	v_pk_fma_f32 v[226:227], v[176:177], v[226:227], v[224:225] op_sel_hi:[0,1,1]
	v_cvt_f32_f16_sdwa v37, v220 dst_sel:DWORD dst_unused:UNUSED_PAD src0_sel:WORD_1
	v_cvt_f32_f16_e32 v36, v220
	v_cvt_f32_f16_e32 v42, v221
	v_cvt_f32_f16_sdwa v45, v222 dst_sel:DWORD dst_unused:UNUSED_PAD src0_sel:WORD_1
	v_cvt_f32_f16_e32 v44, v222
	v_cvt_f32_f16_sdwa v47, v223 dst_sel:DWORD dst_unused:UNUSED_PAD src0_sel:WORD_1
	v_cvt_f32_f16_e32 v46, v223
	ds_read_b128 v[218:221], v172 offset:1792
	ds_read_b128 v[222:225], v172 offset:1808
	s_waitcnt vmcnt(8)
; __device__ __forceinline__ void dsa_item(const KP& p, int b, int tile, char* smem) {
;     ...
;         for (int i = 0; i < 8; ++i) {
;           const int pos = (g8 * 8 + i) * 8 + rs;
;           const f32x4 pa = *(const f32x4*)&pbuf[pos * 8];
;           const f32x4 pb = *(const f32x4*)&pbuf[pos * 8 + 4];
;           float vf[8];
; #pragma unroll
;           for (int e = 0; e < 8; ++e) vf[e] = (float)vv[i][e];
; #pragma unroll
;           for (int e = 0; e < 8; ++e) {
;             acc[0][e] += pa[0] * vf[e]; acc[1][e] += pa[1] * vf[e]; acc[2][e] += pa[2] * vf[e]; acc[3][e] += pa[3] * vf[e];
;             acc[4][e] += pb[0] * vf[e]; acc[5][e] += pb[1] * vf[e]; acc[6][e] += pb[2] * vf[e]; acc[7][e] += pb[3] * vf[e];
;           }
	v_cvt_f32_f16_e32 v48, v232
	v_cvt_f32_f16_sdwa v49, v232 dst_sel:DWORD dst_unused:UNUSED_PAD src0_sel:WORD_1
	v_pk_fma_f32 v[124:125], v[66:67], v[174:175], v[124:125] op_sel_hi:[0,1,1]
	v_pk_fma_f32 v[116:117], v[66:67], v[174:175], v[116:117] op_sel:[1,0,0]
	v_pk_fma_f32 v[110:111], v[68:69], v[174:175], v[110:111] op_sel_hi:[0,1,1]
	v_pk_fma_f32 v[104:105], v[194:195], v[142:143], v[104:105] op_sel_hi:[0,1,1]
	v_cvt_f32_f16_e32 v232, v233
	v_cvt_f32_f16_sdwa v233, v233 dst_sel:DWORD dst_unused:UNUSED_PAD src0_sel:WORD_1
	v_pk_fma_f32 v[216:217], v[74:75], v[190:191], v[216:217] op_sel_hi:[0,1,1]
	v_pk_fma_f32 v[228:229], v[74:75], v[190:191], v[228:229] op_sel:[1,0,0]
	v_pk_fma_f32 v[128:129], v[76:77], v[190:191], v[128:129] op_sel_hi:[0,1,1]
	v_pk_fma_f32 v[134:135], v[50:51], v[190:191], v[134:135] op_sel_hi:[0,1,1]
	v_pk_fma_f32 v[130:131], v[50:51], v[190:191], v[130:131] op_sel:[1,0,0]
	v_pk_fma_f32 v[124:125], v[70:71], v[178:179], v[124:125] op_sel_hi:[0,1,1]
	v_pk_fma_f32 v[116:117], v[70:71], v[178:179], v[116:117] op_sel:[1,0,0]
	v_pk_fma_f32 v[110:111], v[72:73], v[178:179], v[110:111] op_sel_hi:[0,1,1]
	v_pk_fma_f32 v[104:105], v[196:197], v[174:175], v[104:105] op_sel_hi:[0,1,1]
	v_pk_fma_f32 v[118:119], v[50:51], v[180:181], v[118:119] op_sel_hi:[0,1,1]
	v_pk_fma_f32 v[112:113], v[50:51], v[180:181], v[112:113] op_sel:[1,0,0]
	v_cvt_f32_f16_e32 v50, v234
	v_cvt_f32_f16_sdwa v51, v234 dst_sel:DWORD dst_unused:UNUSED_PAD src0_sel:WORD_1
	v_pk_fma_f32 v[216:217], v[78:79], v[192:193], v[216:217] op_sel_hi:[0,1,1]
	v_pk_fma_f32 v[228:229], v[78:79], v[192:193], v[228:229] op_sel:[1,0,0]
	v_pk_fma_f32 v[128:129], v[80:81], v[192:193], v[128:129] op_sel_hi:[0,1,1]
	v_pk_fma_f32 v[120:121], v[200:201], v[190:191], v[120:121] op_sel_hi:[0,1,1]
	v_pk_fma_f32 v[122:123], v[52:53], v[190:191], v[122:123] op_sel_hi:[0,1,1]
	v_pk_fma_f32 v[124:125], v[74:75], v[180:181], v[124:125] op_sel_hi:[0,1,1]
	v_pk_fma_f32 v[116:117], v[74:75], v[180:181], v[116:117] op_sel:[1,0,0]
	v_pk_fma_f32 v[110:111], v[76:77], v[180:181], v[110:111] op_sel_hi:[0,1,1]
	v_pk_fma_f32 v[104:105], v[198:199], v[178:179], v[104:105] op_sel_hi:[0,1,1]
	s_waitcnt lgkmcnt(3)
	v_mov_b32_e32 v38, v209
	s_waitcnt lgkmcnt(2)
	v_mov_b32_e32 v40, v213
	v_cvt_f32_f16_e32 v234, v235
	v_cvt_f32_f16_sdwa v235, v235 dst_sel:DWORD dst_unused:UNUSED_PAD src0_sel:WORD_1
	v_pk_fma_f32 v[204:205], v[212:213], v[36:37], v[204:205] op_sel_hi:[0,1,1]
	v_pk_fma_f32 v[120:121], v[202:203], v[192:193], v[120:121] op_sel_hi:[0,1,1]
	v_pk_fma_f32 v[134:135], v[54:55], v[192:193], v[134:135] op_sel_hi:[0,1,1]
	v_pk_fma_f32 v[130:131], v[54:55], v[192:193], v[130:131] op_sel:[1,0,0]
	v_pk_fma_f32 v[122:123], v[56:57], v[192:193], v[122:123] op_sel_hi:[0,1,1]
	v_pk_fma_f32 v[132:133], v[176:177], v[192:193], v[132:133] op_sel_hi:[0,1,1]
	v_pk_fma_f32 v[114:115], v[158:159], v[180:181], v[114:115] op_sel_hi:[0,1,1]
	v_pk_fma_f32 v[124:125], v[78:79], v[188:189], v[124:125] op_sel_hi:[0,1,1]
	v_pk_fma_f32 v[116:117], v[78:79], v[188:189], v[116:117] op_sel:[1,0,0]
	v_pk_fma_f32 v[110:111], v[80:81], v[188:189], v[110:111] op_sel_hi:[0,1,1]
	v_pk_fma_f32 v[104:105], v[200:201], v[180:181], v[104:105] op_sel_hi:[0,1,1]
	v_pk_fma_f32 v[118:119], v[54:55], v[188:189], v[118:119] op_sel_hi:[0,1,1]
	v_pk_fma_f32 v[112:113], v[54:55], v[188:189], v[112:113] op_sel:[1,0,0]
	v_pk_fma_f32 v[52:53], v[206:207], v[36:37], v[148:149] op_sel_hi:[0,1,1]
	v_pk_fma_f32 v[54:55], v[206:207], v[36:37], v[152:153] op_sel:[1,0,0]
	v_pk_fma_f32 v[56:57], v[208:209], v[36:37], v[146:147] op_sel_hi:[0,1,1]
	v_pk_fma_f32 v[66:67], v[38:39], v[36:37], v[140:141] op_sel_hi:[0,1,1]
	v_pk_fma_f32 v[68:69], v[210:211], v[36:37], v[150:151] op_sel_hi:[0,1,1]
	v_pk_fma_f32 v[70:71], v[210:211], v[36:37], v[144:145] op_sel:[1,0,0]
	v_pk_fma_f32 v[36:37], v[40:41], v[36:37], v[138:139] op_sel_hi:[0,1,1]
	s_waitcnt lgkmcnt(1)
	v_mov_b32_e32 v72, v221
	s_waitcnt lgkmcnt(0)
	v_mov_b32_e32 v74, v225
	v_pk_fma_f32 v[138:139], v[224:225], v[48:49], v[204:205] op_sel_hi:[0,1,1]
	v_pk_fma_f32 v[204:205], v[206:207], v[42:43], v[216:217] op_sel_hi:[0,1,1]
	v_pk_fma_f32 v[216:217], v[206:207], v[42:43], v[228:229] op_sel:[1,0,0]
	v_pk_fma_f32 v[228:229], v[208:209], v[42:43], v[128:129] op_sel_hi:[0,1,1]
	v_pk_fma_f32 v[104:105], v[202:203], v[188:189], v[104:105] op_sel_hi:[0,1,1]
	v_pk_fma_f32 v[114:115], v[176:177], v[188:189], v[114:115] op_sel_hi:[0,1,1]
	v_pk_fma_f32 v[154:155], v[218:219], v[48:49], v[52:53] op_sel_hi:[0,1,1]
	v_pk_fma_f32 v[152:153], v[218:219], v[48:49], v[54:55] op_sel:[1,0,0]
	v_pk_fma_f32 v[146:147], v[220:221], v[48:49], v[56:57] op_sel_hi:[0,1,1]
	v_pk_fma_f32 v[140:141], v[72:73], v[48:49], v[66:67] op_sel_hi:[0,1,1]
	v_pk_fma_f32 v[150:151], v[222:223], v[48:49], v[68:69] op_sel_hi:[0,1,1]
	v_pk_fma_f32 v[144:145], v[222:223], v[48:49], v[70:71] op_sel:[1,0,0]
	v_pk_fma_f32 v[148:149], v[74:75], v[48:49], v[36:37] op_sel_hi:[0,1,1]
	v_pk_fma_f32 v[36:37], v[38:39], v[42:43], v[120:121] op_sel_hi:[0,1,1]
	v_pk_fma_f32 v[48:49], v[210:211], v[42:43], v[134:135] op_sel_hi:[0,1,1]
	v_pk_fma_f32 v[52:53], v[210:211], v[42:43], v[130:131] op_sel:[1,0,0]
	v_pk_fma_f32 v[54:55], v[212:213], v[42:43], v[122:123] op_sel_hi:[0,1,1]
	v_pk_fma_f32 v[42:43], v[40:41], v[42:43], v[132:133] op_sel_hi:[0,1,1]
	v_pk_fma_f32 v[142:143], v[218:219], v[232:233], v[204:205] op_sel_hi:[0,1,1]
	v_pk_fma_f32 v[134:135], v[218:219], v[232:233], v[216:217] op_sel:[1,0,0]
	v_pk_fma_f32 v[128:129], v[220:221], v[232:233], v[228:229] op_sel_hi:[0,1,1]
	v_pk_fma_f32 v[204:205], v[206:207], v[44:45], v[124:125] op_sel_hi:[0,1,1]
; __device__ __forceinline__ void dsa_item(const KP& p, int b, int tile, char* smem) {
;     ...
;       for (int g8 = 0; g8 < 4; ++g8) {
;         h8 vv[8];
; #pragma unroll
;         for (int i = 0; i < 8; ++i) {
;           const int pos = (g8 * 8 + i) * 8 + rs;
;           const int s = (pos < nsel) ? (int)sel[tk * 256 + pos] : 0;
;           vv[i] = *(const h8*)(ub + (size_t)s * NU + C_BV + dc * 8);
;         }
; #pragma unroll
;         for (int i = 0; i < 8; ++i) {
;           const int pos = (g8 * 8 + i) * 8 + rs;
;           const f32x4 pa = *(const f32x4*)&pbuf[pos * 8];
;           const f32x4 pb = *(const f32x4*)&pbuf[pos * 8 + 4];
;           float vf[8];
; #pragma unroll
;           for (int e = 0; e < 8; ++e) vf[e] = (float)vv[i][e];
; #pragma unroll
;           for (int e = 0; e < 8; ++e) {
;             acc[0][e] += pa[0] * vf[e]; acc[1][e] += pa[1] * vf[e]; acc[2][e] += pa[2] * vf[e]; acc[3][e] += pa[3] * vf[e];
;             acc[4][e] += pb[0] * vf[e]; acc[5][e] += pb[1] * vf[e]; acc[6][e] += pb[2] * vf[e]; acc[7][e] += pb[3] * vf[e];
;           }
	v_pk_fma_f32 v[216:217], v[206:207], v[44:45], v[116:117] op_sel:[1,0,0]
	v_pk_fma_f32 v[228:229], v[208:209], v[44:45], v[110:111] op_sel_hi:[0,1,1]
	v_pk_fma_f32 v[120:121], v[72:73], v[232:233], v[36:37] op_sel_hi:[0,1,1]
	v_pk_fma_f32 v[136:137], v[222:223], v[232:233], v[48:49] op_sel_hi:[0,1,1]
	v_pk_fma_f32 v[130:131], v[222:223], v[232:233], v[52:53] op_sel:[1,0,0]
	v_pk_fma_f32 v[122:123], v[224:225], v[232:233], v[54:55] op_sel_hi:[0,1,1]
	v_pk_fma_f32 v[132:133], v[74:75], v[232:233], v[42:43] op_sel_hi:[0,1,1]
	v_pk_fma_f32 v[232:233], v[38:39], v[44:45], v[104:105] op_sel_hi:[0,1,1]
	v_pk_fma_f32 v[36:37], v[210:211], v[44:45], v[118:119] op_sel_hi:[0,1,1]
	v_pk_fma_f32 v[42:43], v[210:211], v[44:45], v[112:113] op_sel:[1,0,0]
	v_pk_fma_f32 v[48:49], v[212:213], v[44:45], v[106:107] op_sel_hi:[0,1,1]
	v_pk_fma_f32 v[44:45], v[40:41], v[44:45], v[114:115] op_sel_hi:[0,1,1]
	v_pk_fma_f32 v[124:125], v[218:219], v[50:51], v[204:205] op_sel_hi:[0,1,1]
	v_pk_fma_f32 v[116:117], v[218:219], v[50:51], v[216:217] op_sel:[1,0,0]
	v_pk_fma_f32 v[110:111], v[220:221], v[50:51], v[228:229] op_sel_hi:[0,1,1]
	v_pk_fma_f32 v[204:205], v[206:207], v[46:47], v[230:231] op_sel_hi:[0,1,1]
	v_pk_fma_f32 v[206:207], v[206:207], v[46:47], v[58:59] op_sel:[1,0,0]
	v_pk_fma_f32 v[208:209], v[208:209], v[46:47], v[60:61] op_sel_hi:[0,1,1]
	v_pk_fma_f32 v[216:217], v[38:39], v[46:47], v[62:63] op_sel_hi:[0,1,1]
	v_pk_fma_f32 v[228:229], v[210:211], v[46:47], v[64:65] op_sel_hi:[0,1,1]
	v_pk_fma_f32 v[210:211], v[210:211], v[46:47], v[34:35] op_sel:[1,0,0]
	v_pk_fma_f32 v[212:213], v[212:213], v[46:47], v[214:215] op_sel_hi:[0,1,1]
	v_pk_fma_f32 v[214:215], v[40:41], v[46:47], v[226:227] op_sel_hi:[0,1,1]
	v_pk_fma_f32 v[104:105], v[72:73], v[50:51], v[232:233] op_sel_hi:[0,1,1]
	v_pk_fma_f32 v[118:119], v[222:223], v[50:51], v[36:37] op_sel_hi:[0,1,1]
	v_pk_fma_f32 v[112:113], v[222:223], v[50:51], v[42:43] op_sel:[1,0,0]
	v_pk_fma_f32 v[106:107], v[224:225], v[50:51], v[48:49] op_sel_hi:[0,1,1]
	v_pk_fma_f32 v[114:115], v[74:75], v[50:51], v[44:45] op_sel_hi:[0,1,1]
	v_pk_fma_f32 v[108:109], v[218:219], v[234:235], v[204:205] op_sel_hi:[0,1,1]
	v_pk_fma_f32 v[100:101], v[218:219], v[234:235], v[206:207] op_sel:[1,0,0]
	v_pk_fma_f32 v[94:95], v[220:221], v[234:235], v[208:209] op_sel_hi:[0,1,1]
	v_pk_fma_f32 v[90:91], v[72:73], v[234:235], v[216:217] op_sel_hi:[0,1,1]
	v_pk_fma_f32 v[102:103], v[222:223], v[234:235], v[228:229] op_sel_hi:[0,1,1]
	v_pk_fma_f32 v[96:97], v[222:223], v[234:235], v[210:211] op_sel:[1,0,0]
	v_pk_fma_f32 v[92:93], v[224:225], v[234:235], v[212:213] op_sel_hi:[0,1,1]
	v_pk_fma_f32 v[98:99], v[74:75], v[234:235], v[214:215] op_sel_hi:[0,1,1]
	v_add_u32_e32 v172, 0x800, v172
	ds_read_u16 v204, v170 offset:384
	ds_read_u16 v208, v170 offset:400
	ds_read_u16 v212, v170 offset:416
	ds_read_u16 v216, v170 offset:432
	ds_read_u16 v224, v170 offset:448
	ds_read_u16 v228, v170 offset:464
	ds_read_u16 v220, v170 offset:480
	ds_read_u16 v232, v170 offset:496
	v_add_u32_e32 v34, 192, v165
	v_cmp_lt_i32_e32 vcc, v34, v85
	s_waitcnt lgkmcnt(7)
	s_nop 0
	v_cndmask_b32_e32 v204, 0, v204, vcc
	v_mul_u32_u24_e32 v204, 0x1d00, v204
	v_lshl_add_u32 v204, v204, 1, v0
	global_load_dwordx4 v[204:207], v204, s[2:3]
	v_add_u32_e32 v35, 8, v34
	v_cmp_lt_i32_e32 vcc, v35, v85
	s_waitcnt lgkmcnt(6)
	s_nop 0
	v_cndmask_b32_e32 v208, 0, v208, vcc
	v_mul_u32_u24_e32 v208, 0x1d00, v208
	v_lshl_add_u32 v208, v208, 1, v0
	global_load_dwordx4 v[208:211], v208, s[2:3]
	v_add_u32_e32 v35, 16, v34
	v_cmp_lt_i32_e32 vcc, v35, v85
	s_waitcnt lgkmcnt(5)
	s_nop 0
	v_cndmask_b32_e32 v212, 0, v212, vcc
	v_mul_u32_u24_e32 v212, 0x1d00, v212
	v_lshl_add_u32 v212, v212, 1, v0
	global_load_dwordx4 v[212:215], v212, s[2:3]
	v_add_u32_e32 v35, 24, v34
	v_cmp_lt_i32_e32 vcc, v35, v85
	s_waitcnt lgkmcnt(4)
	s_nop 0
	v_cndmask_b32_e32 v216, 0, v216, vcc
	v_mul_u32_u24_e32 v216, 0x1d00, v216
	v_lshl_add_u32 v216, v216, 1, v0
	global_load_dwordx4 v[216:219], v216, s[2:3]
	v_add_u32_e32 v35, 32, v34
	v_cmp_lt_i32_e32 vcc, v35, v85
	s_waitcnt lgkmcnt(3)
	s_nop 0
	v_cndmask_b32_e32 v224, 0, v224, vcc
	v_mul_u32_u24_e32 v224, 0x1d00, v224
	v_lshl_add_u32 v224, v224, 1, v0
	global_load_dwordx4 v[224:227], v224, s[2:3]
	v_add_u32_e32 v35, 40, v34
	v_cmp_lt_i32_e32 vcc, v35, v85
	s_waitcnt lgkmcnt(2)
	s_nop 0
	v_cndmask_b32_e32 v228, 0, v228, vcc
	v_mul_u32_u24_e32 v228, 0x1d00, v228
	v_lshl_add_u32 v228, v228, 1, v0
	global_load_dwordx4 v[228:231], v228, s[2:3]
	v_add_u32_e32 v35, 48, v34
	v_cmp_lt_i32_e32 vcc, v35, v85
	s_waitcnt lgkmcnt(1)
	s_nop 0
	v_cndmask_b32_e32 v220, 0, v220, vcc
	v_mul_u32_u24_e32 v220, 0x1d00, v220
	v_lshl_add_u32 v220, v220, 1, v0
	global_load_dwordx4 v[220:223], v220, s[2:3]
	v_add_u32_e32 v35, 56, v34
	v_cmp_lt_i32_e32 vcc, v35, v85
	s_waitcnt lgkmcnt(0)
	s_nop 0
	v_cndmask_b32_e32 v232, 0, v232, vcc
	v_mul_u32_u24_e32 v232, 0x1d00, v232
	v_lshl_add_u32 v232, v232, 1, v0
	global_load_dwordx4 v[232:235], v232, s[2:3]
	s_waitcnt vmcnt(15)
	v_cvt_f32_f16_sdwa v175, v2 dst_sel:DWORD dst_unused:UNUSED_PAD src0_sel:WORD_1
	v_cvt_f32_f16_e32 v174, v2
	s_waitcnt vmcnt(14)
	v_cvt_f32_f16_sdwa v177, v6 dst_sel:DWORD dst_unused:UNUSED_PAD src0_sel:WORD_1
	v_cvt_f32_f16_e32 v176, v6
	ds_read_b128 v[58:61], v172
	ds_read_b128 v[34:37], v172 offset:16
	ds_read_b128 v[62:65], v172 offset:256
	ds_read_b128 v[38:41], v172 offset:272
	ds_read_b128 v[66:69], v172 offset:512
	ds_read_b128 v[42:45], v172 offset:528
	ds_read_b128 v[70:73], v172 offset:768
	ds_read_b128 v[46:49], v172 offset:784
	ds_read_b128 v[74:77], v172 offset:1024
	ds_read_b128 v[50:53], v172 offset:1040
	s_waitcnt vmcnt(13)
; __device__ __forceinline__ void dsa_item(const KP& p, int b, int tile, char* smem) {
;     ...
;         for (int i = 0; i < 8; ++i) {
;           const int pos = (g8 * 8 + i) * 8 + rs;
;           const f32x4 pa = *(const f32x4*)&pbuf[pos * 8];
;           const f32x4 pb = *(const f32x4*)&pbuf[pos * 8 + 4];
;           float vf[8];
; #pragma unroll
;           for (int e = 0; e < 8; ++e) vf[e] = (float)vv[i][e];
; #pragma unroll
;           for (int e = 0; e < 8; ++e) {
;             acc[0][e] += pa[0] * vf[e]; acc[1][e] += pa[1] * vf[e]; acc[2][e] += pa[2] * vf[e]; acc[3][e] += pa[3] * vf[e];
;             acc[4][e] += pb[0] * vf[e]; acc[5][e] += pb[1] * vf[e]; acc[6][e] += pb[2] * vf[e]; acc[7][e] += pb[3] * vf[e];
;           }
	v_cvt_f32_f16_sdwa v179, v10 dst_sel:DWORD dst_unused:UNUSED_PAD src0_sel:WORD_1
	v_cvt_f32_f16_e32 v178, v10
	s_waitcnt lgkmcnt(8)
	v_mov_b32_e32 v156, v37
	s_waitcnt vmcnt(12)
	v_cvt_f32_f16_sdwa v181, v14 dst_sel:DWORD dst_unused:UNUSED_PAD src0_sel:WORD_1
	v_cvt_f32_f16_e32 v180, v14
	v_pk_fma_f32 v[148:149], v[156:157], v[174:175], v[148:149] op_sel_hi:[0,1,1]
	s_waitcnt lgkmcnt(6)
	v_mov_b32_e32 v6, v41
	s_waitcnt vmcnt(11)
	v_cvt_f32_f16_sdwa v189, v22 dst_sel:DWORD dst_unused:UNUSED_PAD src0_sel:WORD_1
	v_cvt_f32_f16_e32 v188, v22
	v_pk_fma_f32 v[148:149], v[6:7], v[176:177], v[148:149] op_sel_hi:[0,1,1]
	s_waitcnt lgkmcnt(4)
	v_mov_b32_e32 v10, v45
	v_pk_fma_f32 v[148:149], v[10:11], v[178:179], v[148:149] op_sel_hi:[0,1,1]
	s_waitcnt lgkmcnt(2)
	v_mov_b32_e32 v22, v49
	v_pk_fma_f32 v[148:149], v[22:23], v[180:181], v[148:149] op_sel_hi:[0,1,1]
	s_waitcnt lgkmcnt(0)
	v_mov_b32_e32 v158, v53
	ds_read_b128 v[78:81], v172 offset:1280
	ds_read_b128 v[54:57], v172 offset:1296
	v_pk_fma_f32 v[190:191], v[158:159], v[188:189], v[148:149] op_sel_hi:[0,1,1]
	v_pk_fma_f32 v[148:149], v[58:59], v[174:175], v[154:155] op_sel_hi:[0,1,1]
	v_mov_b32_e32 v154, v61
	v_pk_fma_f32 v[152:153], v[58:59], v[174:175], v[152:153] op_sel:[1,0,0]
	v_pk_fma_f32 v[146:147], v[60:61], v[174:175], v[146:147] op_sel_hi:[0,1,1]
	v_pk_fma_f32 v[140:141], v[154:155], v[174:175], v[140:141] op_sel_hi:[0,1,1]
	v_mov_b32_e32 v194, v65
	v_pk_fma_f32 v[150:151], v[34:35], v[174:175], v[150:151] op_sel_hi:[0,1,1]
	v_pk_fma_f32 v[144:145], v[34:35], v[174:175], v[144:145] op_sel:[1,0,0]
	v_pk_fma_f32 v[138:139], v[36:37], v[174:175], v[138:139] op_sel_hi:[0,1,1]
	s_waitcnt vmcnt(10)
	v_cvt_f32_f16_sdwa v193, v26 dst_sel:DWORD dst_unused:UNUSED_PAD src0_sel:WORD_1
	v_cvt_f32_f16_e32 v192, v26
	v_pk_fma_f32 v[148:149], v[62:63], v[176:177], v[148:149] op_sel_hi:[0,1,1]
	v_pk_fma_f32 v[152:153], v[62:63], v[176:177], v[152:153] op_sel:[1,0,0]
	v_pk_fma_f32 v[146:147], v[64:65], v[176:177], v[146:147] op_sel_hi:[0,1,1]
	v_pk_fma_f32 v[140:141], v[194:195], v[176:177], v[140:141] op_sel_hi:[0,1,1]
	v_mov_b32_e32 v196, v69
	v_pk_fma_f32 v[150:151], v[38:39], v[176:177], v[150:151] op_sel_hi:[0,1,1]
	v_pk_fma_f32 v[144:145], v[38:39], v[176:177], v[144:145] op_sel:[1,0,0]
	v_pk_fma_f32 v[138:139], v[40:41], v[176:177], v[138:139] op_sel_hi:[0,1,1]
	v_cvt_f32_f16_sdwa v175, v3 dst_sel:DWORD dst_unused:UNUSED_PAD src0_sel:WORD_1
	v_cvt_f32_f16_e32 v174, v3
	v_pk_fma_f32 v[148:149], v[66:67], v[178:179], v[148:149] op_sel_hi:[0,1,1]
	v_pk_fma_f32 v[152:153], v[66:67], v[178:179], v[152:153] op_sel:[1,0,0]
	v_pk_fma_f32 v[146:147], v[68:69], v[178:179], v[146:147] op_sel_hi:[0,1,1]
	v_pk_fma_f32 v[140:141], v[196:197], v[178:179], v[140:141] op_sel_hi:[0,1,1]
	v_mov_b32_e32 v198, v73
	v_pk_fma_f32 v[150:151], v[42:43], v[178:179], v[150:151] op_sel_hi:[0,1,1]
	v_pk_fma_f32 v[144:145], v[42:43], v[178:179], v[144:145] op_sel:[1,0,0]
	v_pk_fma_f32 v[138:139], v[44:45], v[178:179], v[138:139] op_sel_hi:[0,1,1]
	v_cvt_f32_f16_sdwa v179, v7 dst_sel:DWORD dst_unused:UNUSED_PAD src0_sel:WORD_1
	v_cvt_f32_f16_e32 v178, v7
	v_pk_fma_f32 v[148:149], v[70:71], v[180:181], v[148:149] op_sel_hi:[0,1,1]
	v_pk_fma_f32 v[152:153], v[70:71], v[180:181], v[152:153] op_sel:[1,0,0]
	v_pk_fma_f32 v[146:147], v[72:73], v[180:181], v[146:147] op_sel_hi:[0,1,1]
	v_pk_fma_f32 v[140:141], v[198:199], v[180:181], v[140:141] op_sel_hi:[0,1,1]
	v_mov_b32_e32 v200, v77
	v_pk_fma_f32 v[150:151], v[46:47], v[180:181], v[150:151] op_sel_hi:[0,1,1]
	v_pk_fma_f32 v[144:145], v[46:47], v[180:181], v[144:145] op_sel:[1,0,0]
	v_pk_fma_f32 v[138:139], v[48:49], v[180:181], v[138:139] op_sel_hi:[0,1,1]
	v_cvt_f32_f16_sdwa v181, v11 dst_sel:DWORD dst_unused:UNUSED_PAD src0_sel:WORD_1
	v_cvt_f32_f16_e32 v180, v11
	v_pk_fma_f32 v[148:149], v[74:75], v[188:189], v[148:149] op_sel_hi:[0,1,1]
	v_pk_fma_f32 v[152:153], v[74:75], v[188:189], v[152:153] op_sel:[1,0,0]
	v_pk_fma_f32 v[146:147], v[76:77], v[188:189], v[146:147] op_sel_hi:[0,1,1]
	v_pk_fma_f32 v[140:141], v[200:201], v[188:189], v[140:141] op_sel_hi:[0,1,1]
	v_pk_fma_f32 v[150:151], v[50:51], v[188:189], v[150:151] op_sel_hi:[0,1,1]
	v_pk_fma_f32 v[144:145], v[50:51], v[188:189], v[144:145] op_sel:[1,0,0]
	v_pk_fma_f32 v[138:139], v[52:53], v[188:189], v[138:139] op_sel_hi:[0,1,1]
	s_waitcnt lgkmcnt(0)
; __device__ __forceinline__ void dsa_item(const KP& p, int b, int tile, char* smem) {
;     ...
;         for (int i = 0; i < 8; ++i) {
;           const int pos = (g8 * 8 + i) * 8 + rs;
;           const f32x4 pa = *(const f32x4*)&pbuf[pos * 8];
;           const f32x4 pb = *(const f32x4*)&pbuf[pos * 8 + 4];
;           float vf[8];
; #pragma unroll
;           for (int e = 0; e < 8; ++e) vf[e] = (float)vv[i][e];
; #pragma unroll
;           for (int e = 0; e < 8; ++e) {
;             acc[0][e] += pa[0] * vf[e]; acc[1][e] += pa[1] * vf[e]; acc[2][e] += pa[2] * vf[e]; acc[3][e] += pa[3] * vf[e];
;             acc[4][e] += pb[0] * vf[e]; acc[5][e] += pb[1] * vf[e]; acc[6][e] += pb[2] * vf[e]; acc[7][e] += pb[3] * vf[e];
;           }
	v_mov_b32_e32 v176, v57
	v_cvt_f32_f16_sdwa v189, v15 dst_sel:DWORD dst_unused:UNUSED_PAD src0_sel:WORD_1
	v_cvt_f32_f16_e32 v188, v15
	v_pk_fma_f32 v[2:3], v[56:57], v[192:193], v[138:139] op_sel_hi:[0,1,1]
	v_pk_fma_f32 v[138:139], v[176:177], v[192:193], v[190:191] op_sel_hi:[0,1,1]
	v_pk_fma_f32 v[132:133], v[156:157], v[174:175], v[132:133] op_sel_hi:[0,1,1]
	v_cvt_f32_f16_sdwa v191, v23 dst_sel:DWORD dst_unused:UNUSED_PAD src0_sel:WORD_1
	v_cvt_f32_f16_e32 v190, v23
	v_pk_fma_f32 v[14:15], v[6:7], v[178:179], v[132:133] op_sel_hi:[0,1,1]
	v_mov_b32_e32 v202, v81
	v_pk_fma_f32 v[14:15], v[10:11], v[180:181], v[14:15] op_sel_hi:[0,1,1]
	v_pk_fma_f32 v[148:149], v[78:79], v[192:193], v[148:149] op_sel_hi:[0,1,1]
	v_pk_fma_f32 v[152:153], v[78:79], v[192:193], v[152:153] op_sel:[1,0,0]
	v_pk_fma_f32 v[146:147], v[80:81], v[192:193], v[146:147] op_sel_hi:[0,1,1]
	v_pk_fma_f32 v[140:141], v[202:203], v[192:193], v[140:141] op_sel_hi:[0,1,1]
	v_pk_fma_f32 v[150:151], v[54:55], v[192:193], v[150:151] op_sel_hi:[0,1,1]
	v_pk_fma_f32 v[144:145], v[54:55], v[192:193], v[144:145] op_sel:[1,0,0]
	v_pk_fma_f32 v[14:15], v[22:23], v[188:189], v[14:15] op_sel_hi:[0,1,1]
	v_cvt_f32_f16_sdwa v193, v27 dst_sel:DWORD dst_unused:UNUSED_PAD src0_sel:WORD_1
	v_cvt_f32_f16_e32 v192, v27
	v_pk_fma_f32 v[26:27], v[58:59], v[174:175], v[134:135] op_sel:[1,0,0]
	v_pk_fma_f32 v[134:135], v[34:35], v[174:175], v[136:137] op_sel_hi:[0,1,1]
	v_cvt_f32_f16_sdwa v137, v4 dst_sel:DWORD dst_unused:UNUSED_PAD src0_sel:WORD_1
	v_cvt_f32_f16_e32 v136, v4
	v_pk_fma_f32 v[132:133], v[158:159], v[190:191], v[14:15] op_sel_hi:[0,1,1]
	v_pk_fma_f32 v[14:15], v[58:59], v[174:175], v[142:143] op_sel_hi:[0,1,1]
	v_cvt_f32_f16_sdwa v143, v8 dst_sel:DWORD dst_unused:UNUSED_PAD src0_sel:WORD_1
	v_cvt_f32_f16_e32 v142, v8
	v_pk_fma_f32 v[128:129], v[60:61], v[174:175], v[128:129] op_sel_hi:[0,1,1]
	v_pk_fma_f32 v[120:121], v[154:155], v[174:175], v[120:121] op_sel_hi:[0,1,1]
	v_pk_fma_f32 v[130:131], v[34:35], v[174:175], v[130:131] op_sel:[1,0,0]
	v_pk_fma_f32 v[122:123], v[36:37], v[174:175], v[122:123] op_sel_hi:[0,1,1]
	v_cvt_f32_f16_sdwa v175, v12 dst_sel:DWORD dst_unused:UNUSED_PAD src0_sel:WORD_1
	v_cvt_f32_f16_e32 v174, v12
	v_pk_fma_f32 v[14:15], v[62:63], v[178:179], v[14:15] op_sel_hi:[0,1,1]
	v_pk_fma_f32 v[26:27], v[62:63], v[178:179], v[26:27] op_sel:[1,0,0]
	v_pk_fma_f32 v[128:129], v[64:65], v[178:179], v[128:129] op_sel_hi:[0,1,1]
	v_pk_fma_f32 v[120:121], v[194:195], v[178:179], v[120:121] op_sel_hi:[0,1,1]
	v_pk_fma_f32 v[134:135], v[38:39], v[178:179], v[134:135] op_sel_hi:[0,1,1]
	v_pk_fma_f32 v[130:131], v[38:39], v[178:179], v[130:131] op_sel:[1,0,0]
	v_pk_fma_f32 v[122:123], v[40:41], v[178:179], v[122:123] op_sel_hi:[0,1,1]
	v_cvt_f32_f16_sdwa v179, v16 dst_sel:DWORD dst_unused:UNUSED_PAD src0_sel:WORD_1
	v_cvt_f32_f16_e32 v178, v16
	v_pk_fma_f32 v[14:15], v[66:67], v[180:181], v[14:15] op_sel_hi:[0,1,1]
	v_pk_fma_f32 v[26:27], v[66:67], v[180:181], v[26:27] op_sel:[1,0,0]
	v_pk_fma_f32 v[128:129], v[68:69], v[180:181], v[128:129] op_sel_hi:[0,1,1]
	v_pk_fma_f32 v[120:121], v[196:197], v[180:181], v[120:121] op_sel_hi:[0,1,1]
	v_pk_fma_f32 v[134:135], v[42:43], v[180:181], v[134:135] op_sel_hi:[0,1,1]
	v_pk_fma_f32 v[130:131], v[42:43], v[180:181], v[130:131] op_sel:[1,0,0]
	v_pk_fma_f32 v[122:123], v[44:45], v[180:181], v[122:123] op_sel_hi:[0,1,1]
	v_cvt_f32_f16_sdwa v181, v24 dst_sel:DWORD dst_unused:UNUSED_PAD src0_sel:WORD_1
	v_cvt_f32_f16_e32 v180, v24
	v_pk_fma_f32 v[106:107], v[36:37], v[136:137], v[106:107] op_sel_hi:[0,1,1]
	v_pk_fma_f32 v[14:15], v[70:71], v[188:189], v[14:15] op_sel_hi:[0,1,1]
	v_pk_fma_f32 v[26:27], v[70:71], v[188:189], v[26:27] op_sel:[1,0,0]
	v_pk_fma_f32 v[128:129], v[72:73], v[188:189], v[128:129] op_sel_hi:[0,1,1]
	v_pk_fma_f32 v[120:121], v[198:199], v[188:189], v[120:121] op_sel_hi:[0,1,1]
	v_pk_fma_f32 v[134:135], v[46:47], v[188:189], v[134:135] op_sel_hi:[0,1,1]
	v_pk_fma_f32 v[130:131], v[46:47], v[188:189], v[130:131] op_sel:[1,0,0]
	v_pk_fma_f32 v[122:123], v[48:49], v[188:189], v[122:123] op_sel_hi:[0,1,1]
	v_pk_fma_f32 v[114:115], v[156:157], v[136:137], v[114:115] op_sel_hi:[0,1,1]
	v_cvt_f32_f16_sdwa v189, v28 dst_sel:DWORD dst_unused:UNUSED_PAD src0_sel:WORD_1
	v_cvt_f32_f16_e32 v188, v28
	v_pk_fma_f32 v[124:125], v[58:59], v[136:137], v[124:125] op_sel_hi:[0,1,1]
	v_pk_fma_f32 v[116:117], v[58:59], v[136:137], v[116:117] op_sel:[1,0,0]
	v_pk_fma_f32 v[110:111], v[60:61], v[136:137], v[110:111] op_sel_hi:[0,1,1]
	v_pk_fma_f32 v[104:105], v[154:155], v[136:137], v[104:105] op_sel_hi:[0,1,1]
	v_pk_fma_f32 v[118:119], v[34:35], v[136:137], v[118:119] op_sel_hi:[0,1,1]
	v_pk_fma_f32 v[112:113], v[34:35], v[136:137], v[112:113] op_sel:[1,0,0]
	v_pk_fma_f32 v[106:107], v[40:41], v[142:143], v[106:107] op_sel_hi:[0,1,1]
	v_cvt_f32_f16_sdwa v137, v5 dst_sel:DWORD dst_unused:UNUSED_PAD src0_sel:WORD_1
	v_cvt_f32_f16_e32 v136, v5
	v_pk_fma_f32 v[106:107], v[44:45], v[174:175], v[106:107] op_sel_hi:[0,1,1]
	v_pk_fma_f32 v[106:107], v[48:49], v[178:179], v[106:107] op_sel_hi:[0,1,1]
	v_pk_fma_f32 v[4:5], v[52:53], v[180:181], v[106:107] op_sel_hi:[0,1,1]
	v_pk_fma_f32 v[106:107], v[56:57], v[188:189], v[4:5] op_sel_hi:[0,1,1]
	v_pk_fma_f32 v[4:5], v[156:157], v[136:137], v[98:99] op_sel_hi:[0,1,1]
	v_cvt_f32_f16_sdwa v99, v9 dst_sel:DWORD dst_unused:UNUSED_PAD src0_sel:WORD_1
	v_cvt_f32_f16_e32 v98, v9
	v_cvt_f32_f16_sdwa v9, v13 dst_sel:DWORD dst_unused:UNUSED_PAD src0_sel:WORD_1
	v_cvt_f32_f16_e32 v8, v13
	v_cvt_f32_f16_sdwa v13, v17 dst_sel:DWORD dst_unused:UNUSED_PAD src0_sel:WORD_1
	v_cvt_f32_f16_e32 v12, v17
; __device__ __forceinline__ void dsa_item(const KP& p, int b, int tile, char* smem) {
;     ...
;         for (int i = 0; i < 8; ++i) {
;           const int pos = (g8 * 8 + i) * 8 + rs;
;           const f32x4 pa = *(const f32x4*)&pbuf[pos * 8];
;           const f32x4 pb = *(const f32x4*)&pbuf[pos * 8 + 4];
;           float vf[8];
; #pragma unroll
;           for (int e = 0; e < 8; ++e) vf[e] = (float)vv[i][e];
; #pragma unroll
;           for (int e = 0; e < 8; ++e) {
;             acc[0][e] += pa[0] * vf[e]; acc[1][e] += pa[1] * vf[e]; acc[2][e] += pa[2] * vf[e]; acc[3][e] += pa[3] * vf[e];
;             acc[4][e] += pb[0] * vf[e]; acc[5][e] += pb[1] * vf[e]; acc[6][e] += pb[2] * vf[e]; acc[7][e] += pb[3] * vf[e];
;           }
	v_cvt_f32_f16_sdwa v17, v25 dst_sel:DWORD dst_unused:UNUSED_PAD src0_sel:WORD_1
	v_cvt_f32_f16_e32 v16, v25
	v_pk_fma_f32 v[4:5], v[6:7], v[98:99], v[4:5] op_sel_hi:[0,1,1]
	v_pk_fma_f32 v[114:115], v[6:7], v[142:143], v[114:115] op_sel_hi:[0,1,1]
	v_pk_fma_f32 v[4:5], v[10:11], v[8:9], v[4:5] op_sel_hi:[0,1,1]
	v_pk_fma_f32 v[114:115], v[10:11], v[174:175], v[114:115] op_sel_hi:[0,1,1]
	v_pk_fma_f32 v[4:5], v[22:23], v[12:13], v[4:5] op_sel_hi:[0,1,1]
	v_pk_fma_f32 v[114:115], v[22:23], v[178:179], v[114:115] op_sel_hi:[0,1,1]
	v_pk_fma_f32 v[22:23], v[158:159], v[16:17], v[4:5] op_sel_hi:[0,1,1]
	v_pk_fma_f32 v[4:5], v[58:59], v[136:137], v[108:109] op_sel_hi:[0,1,1]
	v_cvt_f32_f16_sdwa v25, v29 dst_sel:DWORD dst_unused:UNUSED_PAD src0_sel:WORD_1
	v_cvt_f32_f16_e32 v24, v29
	v_pk_fma_f32 v[4:5], v[62:63], v[98:99], v[4:5] op_sel_hi:[0,1,1]
	v_pk_fma_f32 v[4:5], v[66:67], v[8:9], v[4:5] op_sel_hi:[0,1,1]
	v_pk_fma_f32 v[4:5], v[70:71], v[12:13], v[4:5] op_sel_hi:[0,1,1]
	v_pk_fma_f32 v[4:5], v[74:75], v[16:17], v[4:5] op_sel_hi:[0,1,1]
	v_pk_fma_f32 v[28:29], v[78:79], v[24:25], v[4:5] op_sel_hi:[0,1,1]
	v_pk_fma_f32 v[4:5], v[58:59], v[136:137], v[100:101] op_sel:[1,0,0]
	v_pk_fma_f32 v[124:125], v[62:63], v[142:143], v[124:125] op_sel_hi:[0,1,1]
	v_pk_fma_f32 v[4:5], v[62:63], v[98:99], v[4:5] op_sel:[1,0,0]
	v_pk_fma_f32 v[116:117], v[62:63], v[142:143], v[116:117] op_sel:[1,0,0]
	v_pk_fma_f32 v[4:5], v[66:67], v[8:9], v[4:5] op_sel:[1,0,0]
	v_pk_fma_f32 v[110:111], v[64:65], v[142:143], v[110:111] op_sel_hi:[0,1,1]
	v_pk_fma_f32 v[4:5], v[70:71], v[12:13], v[4:5] op_sel:[1,0,0]
	v_pk_fma_f32 v[118:119], v[38:39], v[142:143], v[118:119] op_sel_hi:[0,1,1]
	v_pk_fma_f32 v[4:5], v[74:75], v[16:17], v[4:5] op_sel:[1,0,0]
	v_pk_fma_f32 v[112:113], v[38:39], v[142:143], v[112:113] op_sel:[1,0,0]
	v_pk_fma_f32 v[58:59], v[78:79], v[24:25], v[4:5] op_sel:[1,0,0]
	v_pk_fma_f32 v[4:5], v[60:61], v[136:137], v[94:95] op_sel_hi:[0,1,1]
	v_pk_fma_f32 v[4:5], v[64:65], v[98:99], v[4:5] op_sel_hi:[0,1,1]
	v_pk_fma_f32 v[4:5], v[68:69], v[8:9], v[4:5] op_sel_hi:[0,1,1]
	v_pk_fma_f32 v[4:5], v[72:73], v[12:13], v[4:5] op_sel_hi:[0,1,1]
	v_pk_fma_f32 v[4:5], v[76:77], v[16:17], v[4:5] op_sel_hi:[0,1,1]
	v_pk_fma_f32 v[60:61], v[80:81], v[24:25], v[4:5] op_sel_hi:[0,1,1]
	v_pk_fma_f32 v[4:5], v[154:155], v[136:137], v[90:91] op_sel_hi:[0,1,1]
	v_pk_fma_f32 v[4:5], v[194:195], v[98:99], v[4:5] op_sel_hi:[0,1,1]
	v_pk_fma_f32 v[4:5], v[196:197], v[8:9], v[4:5] op_sel_hi:[0,1,1]
	v_pk_fma_f32 v[4:5], v[198:199], v[12:13], v[4:5] op_sel_hi:[0,1,1]
	v_pk_fma_f32 v[4:5], v[200:201], v[16:17], v[4:5] op_sel_hi:[0,1,1]
	v_pk_fma_f32 v[62:63], v[202:203], v[24:25], v[4:5] op_sel_hi:[0,1,1]
	v_pk_fma_f32 v[4:5], v[34:35], v[136:137], v[102:103] op_sel_hi:[0,1,1]
	v_pk_fma_f32 v[4:5], v[38:39], v[98:99], v[4:5] op_sel_hi:[0,1,1]
	v_pk_fma_f32 v[4:5], v[42:43], v[8:9], v[4:5] op_sel_hi:[0,1,1]
	v_pk_fma_f32 v[4:5], v[46:47], v[12:13], v[4:5] op_sel_hi:[0,1,1]
	v_pk_fma_f32 v[4:5], v[50:51], v[16:17], v[4:5] op_sel_hi:[0,1,1]
	v_pk_fma_f32 v[64:65], v[54:55], v[24:25], v[4:5] op_sel_hi:[0,1,1]
	v_pk_fma_f32 v[4:5], v[34:35], v[136:137], v[96:97] op_sel:[1,0,0]
	v_pk_fma_f32 v[118:119], v[42:43], v[174:175], v[118:119] op_sel_hi:[0,1,1]
	v_pk_fma_f32 v[4:5], v[38:39], v[98:99], v[4:5] op_sel:[1,0,0]
	v_pk_fma_f32 v[112:113], v[42:43], v[174:175], v[112:113] op_sel:[1,0,0]
	v_pk_fma_f32 v[4:5], v[42:43], v[8:9], v[4:5] op_sel:[1,0,0]
	v_pk_fma_f32 v[118:119], v[46:47], v[178:179], v[118:119] op_sel_hi:[0,1,1]
	v_pk_fma_f32 v[4:5], v[46:47], v[12:13], v[4:5] op_sel:[1,0,0]
	v_pk_fma_f32 v[112:113], v[46:47], v[178:179], v[112:113] op_sel:[1,0,0]
	v_pk_fma_f32 v[4:5], v[50:51], v[16:17], v[4:5] op_sel:[1,0,0]
	s_waitcnt vmcnt(9)
	v_cvt_f32_f16_sdwa v43, v19 dst_sel:DWORD dst_unused:UNUSED_PAD src0_sel:WORD_1
	v_pk_fma_f32 v[34:35], v[54:55], v[24:25], v[4:5] op_sel:[1,0,0]
	v_pk_fma_f32 v[4:5], v[36:37], v[136:137], v[92:93] op_sel_hi:[0,1,1]
	v_pk_fma_f32 v[4:5], v[40:41], v[98:99], v[4:5] op_sel_hi:[0,1,1]
	v_pk_fma_f32 v[4:5], v[44:45], v[8:9], v[4:5] op_sel_hi:[0,1,1]
	v_pk_fma_f32 v[4:5], v[48:49], v[12:13], v[4:5] op_sel_hi:[0,1,1]
	v_pk_fma_f32 v[4:5], v[52:53], v[16:17], v[4:5] op_sel_hi:[0,1,1]
	v_pk_fma_f32 v[12:13], v[56:57], v[24:25], v[4:5] op_sel_hi:[0,1,1]
	ds_read_b128 v[4:7], v172 offset:1536
	ds_read_b128 v[8:11], v172 offset:1552
	v_pk_fma_f32 v[24:25], v[176:177], v[24:25], v[22:23] op_sel_hi:[0,1,1]
	v_cvt_f32_f16_sdwa v37, v18 dst_sel:DWORD dst_unused:UNUSED_PAD src0_sel:WORD_1
	v_cvt_f32_f16_e32 v36, v18
	v_cvt_f32_f16_e32 v42, v19
	v_cvt_f32_f16_sdwa v45, v20 dst_sel:DWORD dst_unused:UNUSED_PAD src0_sel:WORD_1
	v_cvt_f32_f16_e32 v44, v20
	v_cvt_f32_f16_sdwa v47, v21 dst_sel:DWORD dst_unused:UNUSED_PAD src0_sel:WORD_1
	v_cvt_f32_f16_e32 v46, v21
	ds_read_b128 v[16:19], v172 offset:1792
	ds_read_b128 v[20:23], v172 offset:1808
	s_waitcnt vmcnt(8)
; __device__ __forceinline__ void dsa_item(const KP& p, int b, int tile, char* smem) {
;     ...
;         for (int i = 0; i < 8; ++i) {
;           const int pos = (g8 * 8 + i) * 8 + rs;
;           const f32x4 pa = *(const f32x4*)&pbuf[pos * 8];
;           const f32x4 pb = *(const f32x4*)&pbuf[pos * 8 + 4];
;           float vf[8];
; #pragma unroll
;           for (int e = 0; e < 8; ++e) vf[e] = (float)vv[i][e];
; #pragma unroll
;           for (int e = 0; e < 8; ++e) {
;             acc[0][e] += pa[0] * vf[e]; acc[1][e] += pa[1] * vf[e]; acc[2][e] += pa[2] * vf[e]; acc[3][e] += pa[3] * vf[e];
;             acc[4][e] += pb[0] * vf[e]; acc[5][e] += pb[1] * vf[e]; acc[6][e] += pb[2] * vf[e]; acc[7][e] += pb[3] * vf[e];
;           }
	v_cvt_f32_f16_e32 v48, v30
	v_cvt_f32_f16_sdwa v49, v30 dst_sel:DWORD dst_unused:UNUSED_PAD src0_sel:WORD_1
	v_pk_fma_f32 v[124:125], v[66:67], v[174:175], v[124:125] op_sel_hi:[0,1,1]
	v_pk_fma_f32 v[116:117], v[66:67], v[174:175], v[116:117] op_sel:[1,0,0]
	v_pk_fma_f32 v[110:111], v[68:69], v[174:175], v[110:111] op_sel_hi:[0,1,1]
	v_pk_fma_f32 v[104:105], v[194:195], v[142:143], v[104:105] op_sel_hi:[0,1,1]
	v_cvt_f32_f16_e32 v30, v31
	v_cvt_f32_f16_sdwa v31, v31 dst_sel:DWORD dst_unused:UNUSED_PAD src0_sel:WORD_1
	v_pk_fma_f32 v[14:15], v[74:75], v[190:191], v[14:15] op_sel_hi:[0,1,1]
	v_pk_fma_f32 v[26:27], v[74:75], v[190:191], v[26:27] op_sel:[1,0,0]
	v_pk_fma_f32 v[128:129], v[76:77], v[190:191], v[128:129] op_sel_hi:[0,1,1]
	v_pk_fma_f32 v[134:135], v[50:51], v[190:191], v[134:135] op_sel_hi:[0,1,1]
	v_pk_fma_f32 v[130:131], v[50:51], v[190:191], v[130:131] op_sel:[1,0,0]
	v_pk_fma_f32 v[124:125], v[70:71], v[178:179], v[124:125] op_sel_hi:[0,1,1]
	v_pk_fma_f32 v[116:117], v[70:71], v[178:179], v[116:117] op_sel:[1,0,0]
	v_pk_fma_f32 v[110:111], v[72:73], v[178:179], v[110:111] op_sel_hi:[0,1,1]
	v_pk_fma_f32 v[104:105], v[196:197], v[174:175], v[104:105] op_sel_hi:[0,1,1]
	v_pk_fma_f32 v[118:119], v[50:51], v[180:181], v[118:119] op_sel_hi:[0,1,1]
	v_pk_fma_f32 v[112:113], v[50:51], v[180:181], v[112:113] op_sel:[1,0,0]
	v_cvt_f32_f16_e32 v50, v32
	v_cvt_f32_f16_sdwa v51, v32 dst_sel:DWORD dst_unused:UNUSED_PAD src0_sel:WORD_1
	v_pk_fma_f32 v[14:15], v[78:79], v[192:193], v[14:15] op_sel_hi:[0,1,1]
	v_pk_fma_f32 v[26:27], v[78:79], v[192:193], v[26:27] op_sel:[1,0,0]
	v_pk_fma_f32 v[128:129], v[80:81], v[192:193], v[128:129] op_sel_hi:[0,1,1]
	v_pk_fma_f32 v[120:121], v[200:201], v[190:191], v[120:121] op_sel_hi:[0,1,1]
	v_pk_fma_f32 v[122:123], v[52:53], v[190:191], v[122:123] op_sel_hi:[0,1,1]
	v_pk_fma_f32 v[124:125], v[74:75], v[180:181], v[124:125] op_sel_hi:[0,1,1]
	v_pk_fma_f32 v[116:117], v[74:75], v[180:181], v[116:117] op_sel:[1,0,0]
	v_pk_fma_f32 v[110:111], v[76:77], v[180:181], v[110:111] op_sel_hi:[0,1,1]
	v_pk_fma_f32 v[104:105], v[198:199], v[178:179], v[104:105] op_sel_hi:[0,1,1]
	s_waitcnt lgkmcnt(3)
	v_mov_b32_e32 v38, v7
	s_waitcnt lgkmcnt(2)
	v_mov_b32_e32 v40, v11
	v_cvt_f32_f16_e32 v32, v33
	v_cvt_f32_f16_sdwa v33, v33 dst_sel:DWORD dst_unused:UNUSED_PAD src0_sel:WORD_1
	v_pk_fma_f32 v[2:3], v[10:11], v[36:37], v[2:3] op_sel_hi:[0,1,1]
	v_pk_fma_f32 v[120:121], v[202:203], v[192:193], v[120:121] op_sel_hi:[0,1,1]
	v_pk_fma_f32 v[134:135], v[54:55], v[192:193], v[134:135] op_sel_hi:[0,1,1]
	v_pk_fma_f32 v[130:131], v[54:55], v[192:193], v[130:131] op_sel:[1,0,0]
	v_pk_fma_f32 v[122:123], v[56:57], v[192:193], v[122:123] op_sel_hi:[0,1,1]
	v_pk_fma_f32 v[132:133], v[176:177], v[192:193], v[132:133] op_sel_hi:[0,1,1]
	v_pk_fma_f32 v[114:115], v[158:159], v[180:181], v[114:115] op_sel_hi:[0,1,1]
	v_pk_fma_f32 v[124:125], v[78:79], v[188:189], v[124:125] op_sel_hi:[0,1,1]
	v_pk_fma_f32 v[116:117], v[78:79], v[188:189], v[116:117] op_sel:[1,0,0]
	v_pk_fma_f32 v[110:111], v[80:81], v[188:189], v[110:111] op_sel_hi:[0,1,1]
	v_pk_fma_f32 v[104:105], v[200:201], v[180:181], v[104:105] op_sel_hi:[0,1,1]
	v_pk_fma_f32 v[118:119], v[54:55], v[188:189], v[118:119] op_sel_hi:[0,1,1]
	v_pk_fma_f32 v[112:113], v[54:55], v[188:189], v[112:113] op_sel:[1,0,0]
	v_pk_fma_f32 v[52:53], v[4:5], v[36:37], v[148:149] op_sel_hi:[0,1,1]
	v_pk_fma_f32 v[54:55], v[4:5], v[36:37], v[152:153] op_sel:[1,0,0]
	v_pk_fma_f32 v[56:57], v[6:7], v[36:37], v[146:147] op_sel_hi:[0,1,1]
	v_pk_fma_f32 v[66:67], v[38:39], v[36:37], v[140:141] op_sel_hi:[0,1,1]
	v_pk_fma_f32 v[68:69], v[8:9], v[36:37], v[150:151] op_sel_hi:[0,1,1]
	v_pk_fma_f32 v[70:71], v[8:9], v[36:37], v[144:145] op_sel:[1,0,0]
	v_pk_fma_f32 v[36:37], v[40:41], v[36:37], v[138:139] op_sel_hi:[0,1,1]
	s_waitcnt lgkmcnt(1)
	v_mov_b32_e32 v72, v19
	s_waitcnt lgkmcnt(0)
	v_mov_b32_e32 v74, v23
	v_pk_fma_f32 v[138:139], v[22:23], v[48:49], v[2:3] op_sel_hi:[0,1,1]
	v_pk_fma_f32 v[2:3], v[4:5], v[42:43], v[14:15] op_sel_hi:[0,1,1]
	v_pk_fma_f32 v[14:15], v[4:5], v[42:43], v[26:27] op_sel:[1,0,0]
	v_pk_fma_f32 v[26:27], v[6:7], v[42:43], v[128:129] op_sel_hi:[0,1,1]
	v_pk_fma_f32 v[104:105], v[202:203], v[188:189], v[104:105] op_sel_hi:[0,1,1]
	v_pk_fma_f32 v[114:115], v[176:177], v[188:189], v[114:115] op_sel_hi:[0,1,1]
	v_pk_fma_f32 v[154:155], v[16:17], v[48:49], v[52:53] op_sel_hi:[0,1,1]
	v_pk_fma_f32 v[152:153], v[16:17], v[48:49], v[54:55] op_sel:[1,0,0]
	v_pk_fma_f32 v[146:147], v[18:19], v[48:49], v[56:57] op_sel_hi:[0,1,1]
	v_pk_fma_f32 v[140:141], v[72:73], v[48:49], v[66:67] op_sel_hi:[0,1,1]
	v_pk_fma_f32 v[150:151], v[20:21], v[48:49], v[68:69] op_sel_hi:[0,1,1]
	v_pk_fma_f32 v[144:145], v[20:21], v[48:49], v[70:71] op_sel:[1,0,0]
	v_pk_fma_f32 v[148:149], v[74:75], v[48:49], v[36:37] op_sel_hi:[0,1,1]
	v_pk_fma_f32 v[36:37], v[38:39], v[42:43], v[120:121] op_sel_hi:[0,1,1]
	v_pk_fma_f32 v[48:49], v[8:9], v[42:43], v[134:135] op_sel_hi:[0,1,1]
	v_pk_fma_f32 v[52:53], v[8:9], v[42:43], v[130:131] op_sel:[1,0,0]
	v_pk_fma_f32 v[54:55], v[10:11], v[42:43], v[122:123] op_sel_hi:[0,1,1]
	v_pk_fma_f32 v[42:43], v[40:41], v[42:43], v[132:133] op_sel_hi:[0,1,1]
	v_pk_fma_f32 v[142:143], v[16:17], v[30:31], v[2:3] op_sel_hi:[0,1,1]
	v_pk_fma_f32 v[134:135], v[16:17], v[30:31], v[14:15] op_sel:[1,0,0]
	v_pk_fma_f32 v[128:129], v[18:19], v[30:31], v[26:27] op_sel_hi:[0,1,1]
	v_pk_fma_f32 v[2:3], v[4:5], v[44:45], v[124:125] op_sel_hi:[0,1,1]
	v_pk_fma_f32 v[14:15], v[4:5], v[44:45], v[116:117] op_sel:[1,0,0]
	v_pk_fma_f32 v[26:27], v[6:7], v[44:45], v[110:111] op_sel_hi:[0,1,1]
; __device__ __forceinline__ void dsa_item(const KP& p, int b, int tile, char* smem) {
;     ...
;         for (int i = 0; i < 8; ++i) {
;           const int pos = (g8 * 8 + i) * 8 + rs;
;           const f32x4 pa = *(const f32x4*)&pbuf[pos * 8];
;           const f32x4 pb = *(const f32x4*)&pbuf[pos * 8 + 4];
;           float vf[8];
; #pragma unroll
;           for (int e = 0; e < 8; ++e) vf[e] = (float)vv[i][e];
; #pragma unroll
;           for (int e = 0; e < 8; ++e) {
;             acc[0][e] += pa[0] * vf[e]; acc[1][e] += pa[1] * vf[e]; acc[2][e] += pa[2] * vf[e]; acc[3][e] += pa[3] * vf[e];
;             acc[4][e] += pb[0] * vf[e]; acc[5][e] += pb[1] * vf[e]; acc[6][e] += pb[2] * vf[e]; acc[7][e] += pb[3] * vf[e];
;           }
	v_pk_fma_f32 v[120:121], v[72:73], v[30:31], v[36:37] op_sel_hi:[0,1,1]
	v_pk_fma_f32 v[136:137], v[20:21], v[30:31], v[48:49] op_sel_hi:[0,1,1]
	v_pk_fma_f32 v[130:131], v[20:21], v[30:31], v[52:53] op_sel:[1,0,0]
	v_pk_fma_f32 v[122:123], v[22:23], v[30:31], v[54:55] op_sel_hi:[0,1,1]
	v_pk_fma_f32 v[132:133], v[74:75], v[30:31], v[42:43] op_sel_hi:[0,1,1]
	v_pk_fma_f32 v[30:31], v[38:39], v[44:45], v[104:105] op_sel_hi:[0,1,1]
	v_pk_fma_f32 v[36:37], v[8:9], v[44:45], v[118:119] op_sel_hi:[0,1,1]
	v_pk_fma_f32 v[42:43], v[8:9], v[44:45], v[112:113] op_sel:[1,0,0]
	v_pk_fma_f32 v[48:49], v[10:11], v[44:45], v[106:107] op_sel_hi:[0,1,1]
	v_pk_fma_f32 v[44:45], v[40:41], v[44:45], v[114:115] op_sel_hi:[0,1,1]
	v_pk_fma_f32 v[124:125], v[16:17], v[50:51], v[2:3] op_sel_hi:[0,1,1]
	v_pk_fma_f32 v[116:117], v[16:17], v[50:51], v[14:15] op_sel:[1,0,0]
	v_pk_fma_f32 v[110:111], v[18:19], v[50:51], v[26:27] op_sel_hi:[0,1,1]
	v_pk_fma_f32 v[2:3], v[4:5], v[46:47], v[28:29] op_sel_hi:[0,1,1]
	v_pk_fma_f32 v[4:5], v[4:5], v[46:47], v[58:59] op_sel:[1,0,0]
	v_pk_fma_f32 v[6:7], v[6:7], v[46:47], v[60:61] op_sel_hi:[0,1,1]
	v_pk_fma_f32 v[14:15], v[38:39], v[46:47], v[62:63] op_sel_hi:[0,1,1]
	v_pk_fma_f32 v[26:27], v[8:9], v[46:47], v[64:65] op_sel_hi:[0,1,1]
	v_pk_fma_f32 v[8:9], v[8:9], v[46:47], v[34:35] op_sel:[1,0,0]
	v_pk_fma_f32 v[10:11], v[10:11], v[46:47], v[12:13] op_sel_hi:[0,1,1]
	v_pk_fma_f32 v[12:13], v[40:41], v[46:47], v[24:25] op_sel_hi:[0,1,1]
	v_pk_fma_f32 v[104:105], v[72:73], v[50:51], v[30:31] op_sel_hi:[0,1,1]
	v_pk_fma_f32 v[118:119], v[20:21], v[50:51], v[36:37] op_sel_hi:[0,1,1]
	v_pk_fma_f32 v[112:113], v[20:21], v[50:51], v[42:43] op_sel:[1,0,0]
	v_pk_fma_f32 v[106:107], v[22:23], v[50:51], v[48:49] op_sel_hi:[0,1,1]
	v_pk_fma_f32 v[114:115], v[74:75], v[50:51], v[44:45] op_sel_hi:[0,1,1]
	v_pk_fma_f32 v[108:109], v[16:17], v[32:33], v[2:3] op_sel_hi:[0,1,1]
	v_pk_fma_f32 v[100:101], v[16:17], v[32:33], v[4:5] op_sel:[1,0,0]
	v_pk_fma_f32 v[94:95], v[18:19], v[32:33], v[6:7] op_sel_hi:[0,1,1]
	v_pk_fma_f32 v[90:91], v[72:73], v[32:33], v[14:15] op_sel_hi:[0,1,1]
	v_pk_fma_f32 v[102:103], v[20:21], v[32:33], v[26:27] op_sel_hi:[0,1,1]
	v_pk_fma_f32 v[96:97], v[20:21], v[32:33], v[8:9] op_sel:[1,0,0]
	v_pk_fma_f32 v[92:93], v[22:23], v[32:33], v[10:11] op_sel_hi:[0,1,1]
	v_pk_fma_f32 v[98:99], v[74:75], v[32:33], v[12:13] op_sel_hi:[0,1,1]
	v_add_u32_e32 v172, 0x800, v172
	s_waitcnt vmcnt(7)
	v_cvt_f32_f16_sdwa v175, v204 dst_sel:DWORD dst_unused:UNUSED_PAD src0_sel:WORD_1
	v_cvt_f32_f16_e32 v174, v204
	s_waitcnt vmcnt(6)
	v_cvt_f32_f16_sdwa v177, v208 dst_sel:DWORD dst_unused:UNUSED_PAD src0_sel:WORD_1
	v_cvt_f32_f16_e32 v176, v208
	ds_read_b128 v[58:61], v172
	ds_read_b128 v[34:37], v172 offset:16
	ds_read_b128 v[62:65], v172 offset:256
	ds_read_b128 v[38:41], v172 offset:272
	ds_read_b128 v[66:69], v172 offset:512
	ds_read_b128 v[42:45], v172 offset:528
	ds_read_b128 v[70:73], v172 offset:768
	ds_read_b128 v[46:49], v172 offset:784
	ds_read_b128 v[74:77], v172 offset:1024
	ds_read_b128 v[50:53], v172 offset:1040
	s_waitcnt vmcnt(5)
	v_cvt_f32_f16_sdwa v179, v212 dst_sel:DWORD dst_unused:UNUSED_PAD src0_sel:WORD_1
	v_cvt_f32_f16_e32 v178, v212
	s_waitcnt lgkmcnt(8)
	v_mov_b32_e32 v156, v37
	s_waitcnt vmcnt(4)
	v_cvt_f32_f16_sdwa v181, v216 dst_sel:DWORD dst_unused:UNUSED_PAD src0_sel:WORD_1
	v_cvt_f32_f16_e32 v180, v216
	v_pk_fma_f32 v[148:149], v[156:157], v[174:175], v[148:149] op_sel_hi:[0,1,1]
	s_waitcnt lgkmcnt(6)
	v_mov_b32_e32 v208, v41
	s_waitcnt vmcnt(3)
	v_cvt_f32_f16_sdwa v189, v224 dst_sel:DWORD dst_unused:UNUSED_PAD src0_sel:WORD_1
	v_cvt_f32_f16_e32 v188, v224
	v_pk_fma_f32 v[148:149], v[208:209], v[176:177], v[148:149] op_sel_hi:[0,1,1]
	s_waitcnt lgkmcnt(4)
	v_mov_b32_e32 v212, v45
	v_pk_fma_f32 v[148:149], v[212:213], v[178:179], v[148:149] op_sel_hi:[0,1,1]
	s_waitcnt lgkmcnt(2)
	v_mov_b32_e32 v224, v49
	v_pk_fma_f32 v[148:149], v[224:225], v[180:181], v[148:149] op_sel_hi:[0,1,1]
	s_waitcnt lgkmcnt(0)
	v_mov_b32_e32 v158, v53
	ds_read_b128 v[78:81], v172 offset:1280
	ds_read_b128 v[54:57], v172 offset:1296
	v_pk_fma_f32 v[190:191], v[158:159], v[188:189], v[148:149] op_sel_hi:[0,1,1]
	v_pk_fma_f32 v[148:149], v[58:59], v[174:175], v[154:155] op_sel_hi:[0,1,1]
	v_mov_b32_e32 v154, v61
	v_pk_fma_f32 v[152:153], v[58:59], v[174:175], v[152:153] op_sel:[1,0,0]
	v_pk_fma_f32 v[146:147], v[60:61], v[174:175], v[146:147] op_sel_hi:[0,1,1]
	v_pk_fma_f32 v[140:141], v[154:155], v[174:175], v[140:141] op_sel_hi:[0,1,1]
	v_mov_b32_e32 v194, v65
	v_pk_fma_f32 v[150:151], v[34:35], v[174:175], v[150:151] op_sel_hi:[0,1,1]
	v_pk_fma_f32 v[144:145], v[34:35], v[174:175], v[144:145] op_sel:[1,0,0]
	v_pk_fma_f32 v[138:139], v[36:37], v[174:175], v[138:139] op_sel_hi:[0,1,1]
	s_waitcnt vmcnt(2)
; __device__ __forceinline__ void dsa_item(const KP& p, int b, int tile, char* smem) {
;     ...
;         for (int i = 0; i < 8; ++i) {
;           const int pos = (g8 * 8 + i) * 8 + rs;
;           const f32x4 pa = *(const f32x4*)&pbuf[pos * 8];
;           const f32x4 pb = *(const f32x4*)&pbuf[pos * 8 + 4];
;           float vf[8];
; #pragma unroll
;           for (int e = 0; e < 8; ++e) vf[e] = (float)vv[i][e];
; #pragma unroll
;           for (int e = 0; e < 8; ++e) {
;             acc[0][e] += pa[0] * vf[e]; acc[1][e] += pa[1] * vf[e]; acc[2][e] += pa[2] * vf[e]; acc[3][e] += pa[3] * vf[e];
;             acc[4][e] += pb[0] * vf[e]; acc[5][e] += pb[1] * vf[e]; acc[6][e] += pb[2] * vf[e]; acc[7][e] += pb[3] * vf[e];
;           }
	v_cvt_f32_f16_sdwa v193, v228 dst_sel:DWORD dst_unused:UNUSED_PAD src0_sel:WORD_1
	v_cvt_f32_f16_e32 v192, v228
	v_pk_fma_f32 v[148:149], v[62:63], v[176:177], v[148:149] op_sel_hi:[0,1,1]
	v_pk_fma_f32 v[152:153], v[62:63], v[176:177], v[152:153] op_sel:[1,0,0]
	v_pk_fma_f32 v[146:147], v[64:65], v[176:177], v[146:147] op_sel_hi:[0,1,1]
	v_pk_fma_f32 v[140:141], v[194:195], v[176:177], v[140:141] op_sel_hi:[0,1,1]
	v_mov_b32_e32 v196, v69
	v_pk_fma_f32 v[150:151], v[38:39], v[176:177], v[150:151] op_sel_hi:[0,1,1]
	v_pk_fma_f32 v[144:145], v[38:39], v[176:177], v[144:145] op_sel:[1,0,0]
	v_pk_fma_f32 v[138:139], v[40:41], v[176:177], v[138:139] op_sel_hi:[0,1,1]
	v_cvt_f32_f16_sdwa v175, v205 dst_sel:DWORD dst_unused:UNUSED_PAD src0_sel:WORD_1
	v_cvt_f32_f16_e32 v174, v205
	v_pk_fma_f32 v[148:149], v[66:67], v[178:179], v[148:149] op_sel_hi:[0,1,1]
	v_pk_fma_f32 v[152:153], v[66:67], v[178:179], v[152:153] op_sel:[1,0,0]
	v_pk_fma_f32 v[146:147], v[68:69], v[178:179], v[146:147] op_sel_hi:[0,1,1]
	v_pk_fma_f32 v[140:141], v[196:197], v[178:179], v[140:141] op_sel_hi:[0,1,1]
	v_mov_b32_e32 v198, v73
	v_pk_fma_f32 v[150:151], v[42:43], v[178:179], v[150:151] op_sel_hi:[0,1,1]
	v_pk_fma_f32 v[144:145], v[42:43], v[178:179], v[144:145] op_sel:[1,0,0]
	v_pk_fma_f32 v[138:139], v[44:45], v[178:179], v[138:139] op_sel_hi:[0,1,1]
	v_cvt_f32_f16_sdwa v179, v209 dst_sel:DWORD dst_unused:UNUSED_PAD src0_sel:WORD_1
	v_cvt_f32_f16_e32 v178, v209
	v_pk_fma_f32 v[148:149], v[70:71], v[180:181], v[148:149] op_sel_hi:[0,1,1]
	v_pk_fma_f32 v[152:153], v[70:71], v[180:181], v[152:153] op_sel:[1,0,0]
	v_pk_fma_f32 v[146:147], v[72:73], v[180:181], v[146:147] op_sel_hi:[0,1,1]
	v_pk_fma_f32 v[140:141], v[198:199], v[180:181], v[140:141] op_sel_hi:[0,1,1]
	v_mov_b32_e32 v200, v77
	v_pk_fma_f32 v[150:151], v[46:47], v[180:181], v[150:151] op_sel_hi:[0,1,1]
	v_pk_fma_f32 v[144:145], v[46:47], v[180:181], v[144:145] op_sel:[1,0,0]
	v_pk_fma_f32 v[138:139], v[48:49], v[180:181], v[138:139] op_sel_hi:[0,1,1]
	v_cvt_f32_f16_sdwa v181, v213 dst_sel:DWORD dst_unused:UNUSED_PAD src0_sel:WORD_1
	v_cvt_f32_f16_e32 v180, v213
	v_pk_fma_f32 v[148:149], v[74:75], v[188:189], v[148:149] op_sel_hi:[0,1,1]
	v_pk_fma_f32 v[152:153], v[74:75], v[188:189], v[152:153] op_sel:[1,0,0]
	v_pk_fma_f32 v[146:147], v[76:77], v[188:189], v[146:147] op_sel_hi:[0,1,1]
	v_pk_fma_f32 v[140:141], v[200:201], v[188:189], v[140:141] op_sel_hi:[0,1,1]
	v_pk_fma_f32 v[150:151], v[50:51], v[188:189], v[150:151] op_sel_hi:[0,1,1]
	v_pk_fma_f32 v[144:145], v[50:51], v[188:189], v[144:145] op_sel:[1,0,0]
	v_pk_fma_f32 v[138:139], v[52:53], v[188:189], v[138:139] op_sel_hi:[0,1,1]
	s_waitcnt lgkmcnt(0)
	v_mov_b32_e32 v176, v57
	v_cvt_f32_f16_sdwa v189, v217 dst_sel:DWORD dst_unused:UNUSED_PAD src0_sel:WORD_1
	v_cvt_f32_f16_e32 v188, v217
	v_pk_fma_f32 v[204:205], v[56:57], v[192:193], v[138:139] op_sel_hi:[0,1,1]
	v_pk_fma_f32 v[138:139], v[176:177], v[192:193], v[190:191] op_sel_hi:[0,1,1]
	v_pk_fma_f32 v[132:133], v[156:157], v[174:175], v[132:133] op_sel_hi:[0,1,1]
	v_cvt_f32_f16_sdwa v191, v225 dst_sel:DWORD dst_unused:UNUSED_PAD src0_sel:WORD_1
	v_cvt_f32_f16_e32 v190, v225
	v_pk_fma_f32 v[216:217], v[208:209], v[178:179], v[132:133] op_sel_hi:[0,1,1]
	v_mov_b32_e32 v202, v81
	v_pk_fma_f32 v[216:217], v[212:213], v[180:181], v[216:217] op_sel_hi:[0,1,1]
	v_pk_fma_f32 v[148:149], v[78:79], v[192:193], v[148:149] op_sel_hi:[0,1,1]
	v_pk_fma_f32 v[152:153], v[78:79], v[192:193], v[152:153] op_sel:[1,0,0]
	v_pk_fma_f32 v[146:147], v[80:81], v[192:193], v[146:147] op_sel_hi:[0,1,1]
	v_pk_fma_f32 v[140:141], v[202:203], v[192:193], v[140:141] op_sel_hi:[0,1,1]
	v_pk_fma_f32 v[150:151], v[54:55], v[192:193], v[150:151] op_sel_hi:[0,1,1]
	v_pk_fma_f32 v[144:145], v[54:55], v[192:193], v[144:145] op_sel:[1,0,0]
	v_pk_fma_f32 v[216:217], v[224:225], v[188:189], v[216:217] op_sel_hi:[0,1,1]
	v_cvt_f32_f16_sdwa v193, v229 dst_sel:DWORD dst_unused:UNUSED_PAD src0_sel:WORD_1
	v_cvt_f32_f16_e32 v192, v229
	v_pk_fma_f32 v[228:229], v[58:59], v[174:175], v[134:135] op_sel:[1,0,0]
	v_pk_fma_f32 v[134:135], v[34:35], v[174:175], v[136:137] op_sel_hi:[0,1,1]
	v_cvt_f32_f16_sdwa v137, v206 dst_sel:DWORD dst_unused:UNUSED_PAD src0_sel:WORD_1
	v_cvt_f32_f16_e32 v136, v206
	v_pk_fma_f32 v[132:133], v[158:159], v[190:191], v[216:217] op_sel_hi:[0,1,1]
	v_pk_fma_f32 v[216:217], v[58:59], v[174:175], v[142:143] op_sel_hi:[0,1,1]
	v_cvt_f32_f16_sdwa v143, v210 dst_sel:DWORD dst_unused:UNUSED_PAD src0_sel:WORD_1
	v_cvt_f32_f16_e32 v142, v210
	v_pk_fma_f32 v[128:129], v[60:61], v[174:175], v[128:129] op_sel_hi:[0,1,1]
	v_pk_fma_f32 v[120:121], v[154:155], v[174:175], v[120:121] op_sel_hi:[0,1,1]
	v_pk_fma_f32 v[130:131], v[34:35], v[174:175], v[130:131] op_sel:[1,0,0]
	v_pk_fma_f32 v[122:123], v[36:37], v[174:175], v[122:123] op_sel_hi:[0,1,1]
	v_cvt_f32_f16_sdwa v175, v214 dst_sel:DWORD dst_unused:UNUSED_PAD src0_sel:WORD_1
	v_cvt_f32_f16_e32 v174, v214
	v_pk_fma_f32 v[216:217], v[62:63], v[178:179], v[216:217] op_sel_hi:[0,1,1]
	v_pk_fma_f32 v[228:229], v[62:63], v[178:179], v[228:229] op_sel:[1,0,0]
	v_pk_fma_f32 v[128:129], v[64:65], v[178:179], v[128:129] op_sel_hi:[0,1,1]
	v_pk_fma_f32 v[120:121], v[194:195], v[178:179], v[120:121] op_sel_hi:[0,1,1]
	v_pk_fma_f32 v[134:135], v[38:39], v[178:179], v[134:135] op_sel_hi:[0,1,1]
	v_pk_fma_f32 v[130:131], v[38:39], v[178:179], v[130:131] op_sel:[1,0,0]
	v_pk_fma_f32 v[122:123], v[40:41], v[178:179], v[122:123] op_sel_hi:[0,1,1]
	v_cvt_f32_f16_sdwa v179, v218 dst_sel:DWORD dst_unused:UNUSED_PAD src0_sel:WORD_1
	v_cvt_f32_f16_e32 v178, v218
; __device__ __forceinline__ void dsa_item(const KP& p, int b, int tile, char* smem) {
;     ...
;         for (int i = 0; i < 8; ++i) {
;           const int pos = (g8 * 8 + i) * 8 + rs;
;           const f32x4 pa = *(const f32x4*)&pbuf[pos * 8];
;           const f32x4 pb = *(const f32x4*)&pbuf[pos * 8 + 4];
;           float vf[8];
; #pragma unroll
;           for (int e = 0; e < 8; ++e) vf[e] = (float)vv[i][e];
; #pragma unroll
;           for (int e = 0; e < 8; ++e) {
;             acc[0][e] += pa[0] * vf[e]; acc[1][e] += pa[1] * vf[e]; acc[2][e] += pa[2] * vf[e]; acc[3][e] += pa[3] * vf[e];
;             acc[4][e] += pb[0] * vf[e]; acc[5][e] += pb[1] * vf[e]; acc[6][e] += pb[2] * vf[e]; acc[7][e] += pb[3] * vf[e];
;           }
	v_pk_fma_f32 v[216:217], v[66:67], v[180:181], v[216:217] op_sel_hi:[0,1,1]
	v_pk_fma_f32 v[228:229], v[66:67], v[180:181], v[228:229] op_sel:[1,0,0]
	v_pk_fma_f32 v[128:129], v[68:69], v[180:181], v[128:129] op_sel_hi:[0,1,1]
	v_pk_fma_f32 v[120:121], v[196:197], v[180:181], v[120:121] op_sel_hi:[0,1,1]
	v_pk_fma_f32 v[134:135], v[42:43], v[180:181], v[134:135] op_sel_hi:[0,1,1]
	v_pk_fma_f32 v[130:131], v[42:43], v[180:181], v[130:131] op_sel:[1,0,0]
	v_pk_fma_f32 v[122:123], v[44:45], v[180:181], v[122:123] op_sel_hi:[0,1,1]
	v_cvt_f32_f16_sdwa v181, v226 dst_sel:DWORD dst_unused:UNUSED_PAD src0_sel:WORD_1
	v_cvt_f32_f16_e32 v180, v226
	v_pk_fma_f32 v[106:107], v[36:37], v[136:137], v[106:107] op_sel_hi:[0,1,1]
	v_pk_fma_f32 v[216:217], v[70:71], v[188:189], v[216:217] op_sel_hi:[0,1,1]
	v_pk_fma_f32 v[228:229], v[70:71], v[188:189], v[228:229] op_sel:[1,0,0]
	v_pk_fma_f32 v[128:129], v[72:73], v[188:189], v[128:129] op_sel_hi:[0,1,1]
	v_pk_fma_f32 v[120:121], v[198:199], v[188:189], v[120:121] op_sel_hi:[0,1,1]
	v_pk_fma_f32 v[134:135], v[46:47], v[188:189], v[134:135] op_sel_hi:[0,1,1]
	v_pk_fma_f32 v[130:131], v[46:47], v[188:189], v[130:131] op_sel:[1,0,0]
	v_pk_fma_f32 v[122:123], v[48:49], v[188:189], v[122:123] op_sel_hi:[0,1,1]
	v_pk_fma_f32 v[114:115], v[156:157], v[136:137], v[114:115] op_sel_hi:[0,1,1]
	v_cvt_f32_f16_sdwa v189, v230 dst_sel:DWORD dst_unused:UNUSED_PAD src0_sel:WORD_1
	v_cvt_f32_f16_e32 v188, v230
	v_pk_fma_f32 v[124:125], v[58:59], v[136:137], v[124:125] op_sel_hi:[0,1,1]
	v_pk_fma_f32 v[116:117], v[58:59], v[136:137], v[116:117] op_sel:[1,0,0]
	v_pk_fma_f32 v[110:111], v[60:61], v[136:137], v[110:111] op_sel_hi:[0,1,1]
	v_pk_fma_f32 v[104:105], v[154:155], v[136:137], v[104:105] op_sel_hi:[0,1,1]
	v_pk_fma_f32 v[118:119], v[34:35], v[136:137], v[118:119] op_sel_hi:[0,1,1]
	v_pk_fma_f32 v[112:113], v[34:35], v[136:137], v[112:113] op_sel:[1,0,0]
	v_pk_fma_f32 v[106:107], v[40:41], v[142:143], v[106:107] op_sel_hi:[0,1,1]
	v_cvt_f32_f16_sdwa v137, v207 dst_sel:DWORD dst_unused:UNUSED_PAD src0_sel:WORD_1
	v_cvt_f32_f16_e32 v136, v207
	v_pk_fma_f32 v[106:107], v[44:45], v[174:175], v[106:107] op_sel_hi:[0,1,1]
	v_pk_fma_f32 v[106:107], v[48:49], v[178:179], v[106:107] op_sel_hi:[0,1,1]
	v_pk_fma_f32 v[206:207], v[52:53], v[180:181], v[106:107] op_sel_hi:[0,1,1]
	v_pk_fma_f32 v[106:107], v[56:57], v[188:189], v[206:207] op_sel_hi:[0,1,1]
	v_pk_fma_f32 v[206:207], v[156:157], v[136:137], v[98:99] op_sel_hi:[0,1,1]
	v_cvt_f32_f16_sdwa v99, v211 dst_sel:DWORD dst_unused:UNUSED_PAD src0_sel:WORD_1
	v_cvt_f32_f16_e32 v98, v211
	v_cvt_f32_f16_sdwa v211, v215 dst_sel:DWORD dst_unused:UNUSED_PAD src0_sel:WORD_1
	v_cvt_f32_f16_e32 v210, v215
	v_cvt_f32_f16_sdwa v215, v219 dst_sel:DWORD dst_unused:UNUSED_PAD src0_sel:WORD_1
	v_cvt_f32_f16_e32 v214, v219
	v_cvt_f32_f16_sdwa v219, v227 dst_sel:DWORD dst_unused:UNUSED_PAD src0_sel:WORD_1
	v_cvt_f32_f16_e32 v218, v227
	v_pk_fma_f32 v[206:207], v[208:209], v[98:99], v[206:207] op_sel_hi:[0,1,1]
	v_pk_fma_f32 v[114:115], v[208:209], v[142:143], v[114:115] op_sel_hi:[0,1,1]
	v_pk_fma_f32 v[206:207], v[212:213], v[210:211], v[206:207] op_sel_hi:[0,1,1]
	v_pk_fma_f32 v[114:115], v[212:213], v[174:175], v[114:115] op_sel_hi:[0,1,1]
	v_pk_fma_f32 v[206:207], v[224:225], v[214:215], v[206:207] op_sel_hi:[0,1,1]
	v_pk_fma_f32 v[114:115], v[224:225], v[178:179], v[114:115] op_sel_hi:[0,1,1]
	v_pk_fma_f32 v[224:225], v[158:159], v[218:219], v[206:207] op_sel_hi:[0,1,1]
	v_pk_fma_f32 v[206:207], v[58:59], v[136:137], v[108:109] op_sel_hi:[0,1,1]
	v_cvt_f32_f16_sdwa v227, v231 dst_sel:DWORD dst_unused:UNUSED_PAD src0_sel:WORD_1
	v_cvt_f32_f16_e32 v226, v231
	v_pk_fma_f32 v[206:207], v[62:63], v[98:99], v[206:207] op_sel_hi:[0,1,1]
	v_pk_fma_f32 v[206:207], v[66:67], v[210:211], v[206:207] op_sel_hi:[0,1,1]
	v_pk_fma_f32 v[206:207], v[70:71], v[214:215], v[206:207] op_sel_hi:[0,1,1]
	v_pk_fma_f32 v[206:207], v[74:75], v[218:219], v[206:207] op_sel_hi:[0,1,1]
	v_pk_fma_f32 v[230:231], v[78:79], v[226:227], v[206:207] op_sel_hi:[0,1,1]
	v_pk_fma_f32 v[206:207], v[58:59], v[136:137], v[100:101] op_sel:[1,0,0]
	v_pk_fma_f32 v[124:125], v[62:63], v[142:143], v[124:125] op_sel_hi:[0,1,1]
	v_pk_fma_f32 v[206:207], v[62:63], v[98:99], v[206:207] op_sel:[1,0,0]
	v_pk_fma_f32 v[116:117], v[62:63], v[142:143], v[116:117] op_sel:[1,0,0]
	v_pk_fma_f32 v[206:207], v[66:67], v[210:211], v[206:207] op_sel:[1,0,0]
	v_pk_fma_f32 v[110:111], v[64:65], v[142:143], v[110:111] op_sel_hi:[0,1,1]
	v_pk_fma_f32 v[206:207], v[70:71], v[214:215], v[206:207] op_sel:[1,0,0]
	v_pk_fma_f32 v[118:119], v[38:39], v[142:143], v[118:119] op_sel_hi:[0,1,1]
	v_pk_fma_f32 v[206:207], v[74:75], v[218:219], v[206:207] op_sel:[1,0,0]
	v_pk_fma_f32 v[112:113], v[38:39], v[142:143], v[112:113] op_sel:[1,0,0]
	v_pk_fma_f32 v[58:59], v[78:79], v[226:227], v[206:207] op_sel:[1,0,0]
	v_pk_fma_f32 v[206:207], v[60:61], v[136:137], v[94:95] op_sel_hi:[0,1,1]
	v_pk_fma_f32 v[206:207], v[64:65], v[98:99], v[206:207] op_sel_hi:[0,1,1]
	v_pk_fma_f32 v[206:207], v[68:69], v[210:211], v[206:207] op_sel_hi:[0,1,1]
	v_pk_fma_f32 v[206:207], v[72:73], v[214:215], v[206:207] op_sel_hi:[0,1,1]
	v_pk_fma_f32 v[206:207], v[76:77], v[218:219], v[206:207] op_sel_hi:[0,1,1]
	v_pk_fma_f32 v[60:61], v[80:81], v[226:227], v[206:207] op_sel_hi:[0,1,1]
	v_pk_fma_f32 v[206:207], v[154:155], v[136:137], v[90:91] op_sel_hi:[0,1,1]
	v_pk_fma_f32 v[206:207], v[194:195], v[98:99], v[206:207] op_sel_hi:[0,1,1]
	v_pk_fma_f32 v[206:207], v[196:197], v[210:211], v[206:207] op_sel_hi:[0,1,1]
	v_pk_fma_f32 v[206:207], v[198:199], v[214:215], v[206:207] op_sel_hi:[0,1,1]
	v_pk_fma_f32 v[206:207], v[200:201], v[218:219], v[206:207] op_sel_hi:[0,1,1]
	v_pk_fma_f32 v[62:63], v[202:203], v[226:227], v[206:207] op_sel_hi:[0,1,1]
	v_pk_fma_f32 v[206:207], v[34:35], v[136:137], v[102:103] op_sel_hi:[0,1,1]
	v_pk_fma_f32 v[206:207], v[38:39], v[98:99], v[206:207] op_sel_hi:[0,1,1]
	v_pk_fma_f32 v[206:207], v[42:43], v[210:211], v[206:207] op_sel_hi:[0,1,1]
	v_pk_fma_f32 v[206:207], v[46:47], v[214:215], v[206:207] op_sel_hi:[0,1,1]
	v_pk_fma_f32 v[206:207], v[50:51], v[218:219], v[206:207] op_sel_hi:[0,1,1]
	v_pk_fma_f32 v[64:65], v[54:55], v[226:227], v[206:207] op_sel_hi:[0,1,1]
	v_pk_fma_f32 v[206:207], v[34:35], v[136:137], v[96:97] op_sel:[1,0,0]
	v_pk_fma_f32 v[118:119], v[42:43], v[174:175], v[118:119] op_sel_hi:[0,1,1]
	v_pk_fma_f32 v[206:207], v[38:39], v[98:99], v[206:207] op_sel:[1,0,0]
	v_pk_fma_f32 v[112:113], v[42:43], v[174:175], v[112:113] op_sel:[1,0,0]
	v_pk_fma_f32 v[206:207], v[42:43], v[210:211], v[206:207] op_sel:[1,0,0]
	v_pk_fma_f32 v[118:119], v[46:47], v[178:179], v[118:119] op_sel_hi:[0,1,1]
	v_pk_fma_f32 v[206:207], v[46:47], v[214:215], v[206:207] op_sel:[1,0,0]
	v_pk_fma_f32 v[112:113], v[46:47], v[178:179], v[112:113] op_sel:[1,0,0]
	v_pk_fma_f32 v[206:207], v[50:51], v[218:219], v[206:207] op_sel:[1,0,0]
	s_waitcnt vmcnt(1)
; __device__ __forceinline__ void dsa_item(const KP& p, int b, int tile, char* smem) {
;     ...
;         for (int i = 0; i < 8; ++i) {
;           const int pos = (g8 * 8 + i) * 8 + rs;
;           const f32x4 pa = *(const f32x4*)&pbuf[pos * 8];
;           const f32x4 pb = *(const f32x4*)&pbuf[pos * 8 + 4];
;           float vf[8];
; #pragma unroll
;           for (int e = 0; e < 8; ++e) vf[e] = (float)vv[i][e];
; #pragma unroll
;           for (int e = 0; e < 8; ++e) {
;             acc[0][e] += pa[0] * vf[e]; acc[1][e] += pa[1] * vf[e]; acc[2][e] += pa[2] * vf[e]; acc[3][e] += pa[3] * vf[e];
;             acc[4][e] += pb[0] * vf[e]; acc[5][e] += pb[1] * vf[e]; acc[6][e] += pb[2] * vf[e]; acc[7][e] += pb[3] * vf[e];
;           }
	v_cvt_f32_f16_sdwa v43, v221 dst_sel:DWORD dst_unused:UNUSED_PAD src0_sel:WORD_1
	v_pk_fma_f32 v[34:35], v[54:55], v[226:227], v[206:207] op_sel:[1,0,0]
	v_pk_fma_f32 v[206:207], v[36:37], v[136:137], v[92:93] op_sel_hi:[0,1,1]
	v_pk_fma_f32 v[206:207], v[40:41], v[98:99], v[206:207] op_sel_hi:[0,1,1]
	v_pk_fma_f32 v[206:207], v[44:45], v[210:211], v[206:207] op_sel_hi:[0,1,1]
	v_pk_fma_f32 v[206:207], v[48:49], v[214:215], v[206:207] op_sel_hi:[0,1,1]
	v_pk_fma_f32 v[206:207], v[52:53], v[218:219], v[206:207] op_sel_hi:[0,1,1]
	v_pk_fma_f32 v[214:215], v[56:57], v[226:227], v[206:207] op_sel_hi:[0,1,1]
	ds_read_b128 v[206:209], v172 offset:1536
	ds_read_b128 v[210:213], v172 offset:1552
	v_pk_fma_f32 v[226:227], v[176:177], v[226:227], v[224:225] op_sel_hi:[0,1,1]
	v_cvt_f32_f16_sdwa v37, v220 dst_sel:DWORD dst_unused:UNUSED_PAD src0_sel:WORD_1
	v_cvt_f32_f16_e32 v36, v220
	v_cvt_f32_f16_e32 v42, v221
	v_cvt_f32_f16_sdwa v45, v222 dst_sel:DWORD dst_unused:UNUSED_PAD src0_sel:WORD_1
	v_cvt_f32_f16_e32 v44, v222
	v_cvt_f32_f16_sdwa v47, v223 dst_sel:DWORD dst_unused:UNUSED_PAD src0_sel:WORD_1
	v_cvt_f32_f16_e32 v46, v223
	ds_read_b128 v[218:221], v172 offset:1792
	ds_read_b128 v[222:225], v172 offset:1808
	s_waitcnt vmcnt(0)
	v_cvt_f32_f16_e32 v48, v232
	v_cvt_f32_f16_sdwa v49, v232 dst_sel:DWORD dst_unused:UNUSED_PAD src0_sel:WORD_1
	v_pk_fma_f32 v[124:125], v[66:67], v[174:175], v[124:125] op_sel_hi:[0,1,1]
	v_pk_fma_f32 v[116:117], v[66:67], v[174:175], v[116:117] op_sel:[1,0,0]
	v_pk_fma_f32 v[110:111], v[68:69], v[174:175], v[110:111] op_sel_hi:[0,1,1]
	v_pk_fma_f32 v[104:105], v[194:195], v[142:143], v[104:105] op_sel_hi:[0,1,1]
	v_cvt_f32_f16_e32 v232, v233
	v_cvt_f32_f16_sdwa v233, v233 dst_sel:DWORD dst_unused:UNUSED_PAD src0_sel:WORD_1
	v_pk_fma_f32 v[216:217], v[74:75], v[190:191], v[216:217] op_sel_hi:[0,1,1]
	v_pk_fma_f32 v[228:229], v[74:75], v[190:191], v[228:229] op_sel:[1,0,0]
	v_pk_fma_f32 v[128:129], v[76:77], v[190:191], v[128:129] op_sel_hi:[0,1,1]
	v_pk_fma_f32 v[134:135], v[50:51], v[190:191], v[134:135] op_sel_hi:[0,1,1]
	v_pk_fma_f32 v[130:131], v[50:51], v[190:191], v[130:131] op_sel:[1,0,0]
	v_pk_fma_f32 v[124:125], v[70:71], v[178:179], v[124:125] op_sel_hi:[0,1,1]
	v_pk_fma_f32 v[116:117], v[70:71], v[178:179], v[116:117] op_sel:[1,0,0]
	v_pk_fma_f32 v[110:111], v[72:73], v[178:179], v[110:111] op_sel_hi:[0,1,1]
	v_pk_fma_f32 v[104:105], v[196:197], v[174:175], v[104:105] op_sel_hi:[0,1,1]
	v_pk_fma_f32 v[118:119], v[50:51], v[180:181], v[118:119] op_sel_hi:[0,1,1]
	v_pk_fma_f32 v[112:113], v[50:51], v[180:181], v[112:113] op_sel:[1,0,0]
	v_cvt_f32_f16_e32 v50, v234
	v_cvt_f32_f16_sdwa v51, v234 dst_sel:DWORD dst_unused:UNUSED_PAD src0_sel:WORD_1
	v_pk_fma_f32 v[216:217], v[78:79], v[192:193], v[216:217] op_sel_hi:[0,1,1]
	v_pk_fma_f32 v[228:229], v[78:79], v[192:193], v[228:229] op_sel:[1,0,0]
	v_pk_fma_f32 v[128:129], v[80:81], v[192:193], v[128:129] op_sel_hi:[0,1,1]
	v_pk_fma_f32 v[120:121], v[200:201], v[190:191], v[120:121] op_sel_hi:[0,1,1]
	v_pk_fma_f32 v[122:123], v[52:53], v[190:191], v[122:123] op_sel_hi:[0,1,1]
	v_pk_fma_f32 v[124:125], v[74:75], v[180:181], v[124:125] op_sel_hi:[0,1,1]
	v_pk_fma_f32 v[116:117], v[74:75], v[180:181], v[116:117] op_sel:[1,0,0]
	v_pk_fma_f32 v[110:111], v[76:77], v[180:181], v[110:111] op_sel_hi:[0,1,1]
	v_pk_fma_f32 v[104:105], v[198:199], v[178:179], v[104:105] op_sel_hi:[0,1,1]
	s_waitcnt lgkmcnt(3)
	v_mov_b32_e32 v38, v209
	s_waitcnt lgkmcnt(2)
	v_mov_b32_e32 v40, v213
	v_cvt_f32_f16_e32 v234, v235
	v_cvt_f32_f16_sdwa v235, v235 dst_sel:DWORD dst_unused:UNUSED_PAD src0_sel:WORD_1
	v_pk_fma_f32 v[204:205], v[212:213], v[36:37], v[204:205] op_sel_hi:[0,1,1]
	v_pk_fma_f32 v[120:121], v[202:203], v[192:193], v[120:121] op_sel_hi:[0,1,1]
	v_pk_fma_f32 v[134:135], v[54:55], v[192:193], v[134:135] op_sel_hi:[0,1,1]
	v_pk_fma_f32 v[130:131], v[54:55], v[192:193], v[130:131] op_sel:[1,0,0]
	v_pk_fma_f32 v[122:123], v[56:57], v[192:193], v[122:123] op_sel_hi:[0,1,1]
	v_pk_fma_f32 v[132:133], v[176:177], v[192:193], v[132:133] op_sel_hi:[0,1,1]
	v_pk_fma_f32 v[114:115], v[158:159], v[180:181], v[114:115] op_sel_hi:[0,1,1]
	v_pk_fma_f32 v[124:125], v[78:79], v[188:189], v[124:125] op_sel_hi:[0,1,1]
	v_pk_fma_f32 v[116:117], v[78:79], v[188:189], v[116:117] op_sel:[1,0,0]
	v_pk_fma_f32 v[110:111], v[80:81], v[188:189], v[110:111] op_sel_hi:[0,1,1]
	v_pk_fma_f32 v[104:105], v[200:201], v[180:181], v[104:105] op_sel_hi:[0,1,1]
	v_pk_fma_f32 v[118:119], v[54:55], v[188:189], v[118:119] op_sel_hi:[0,1,1]
	v_pk_fma_f32 v[112:113], v[54:55], v[188:189], v[112:113] op_sel:[1,0,0]
	v_pk_fma_f32 v[52:53], v[206:207], v[36:37], v[148:149] op_sel_hi:[0,1,1]
	v_pk_fma_f32 v[54:55], v[206:207], v[36:37], v[152:153] op_sel:[1,0,0]
	v_pk_fma_f32 v[56:57], v[208:209], v[36:37], v[146:147] op_sel_hi:[0,1,1]
	v_pk_fma_f32 v[66:67], v[38:39], v[36:37], v[140:141] op_sel_hi:[0,1,1]
	v_pk_fma_f32 v[68:69], v[210:211], v[36:37], v[150:151] op_sel_hi:[0,1,1]
	v_pk_fma_f32 v[70:71], v[210:211], v[36:37], v[144:145] op_sel:[1,0,0]
	v_pk_fma_f32 v[36:37], v[40:41], v[36:37], v[138:139] op_sel_hi:[0,1,1]
	s_waitcnt lgkmcnt(1)
;   __device__ __forceinline__ const float* x() const { return (const float*)(const __attribute__((address_space(1))) float*)kp[0]; }
; template <class F>
; __device__ __forceinline__ void xcd_schedule(int* q, int xcc, int ngroups, int gsize, char* smem, F f) {
;     ...
;     for (;;) {
;       if (threadIdx.x == 0) *s_item = atomicAdd(&q[y], 1);
;       __syncthreads();
;       const int i = __builtin_amdgcn_readfirstlane(*s_item);
;       __syncthreads();
; __device__ __forceinline__ void dsa_item(const KP& p, int b, int tile, char* smem) {
;     ...
;         for (int i = 0; i < 8; ++i) {
;           const int pos = (g8 * 8 + i) * 8 + rs;
;           const f32x4 pa = *(const f32x4*)&pbuf[pos * 8];
;           const f32x4 pb = *(const f32x4*)&pbuf[pos * 8 + 4];
;           float vf[8];
; #pragma unroll
;           for (int e = 0; e < 8; ++e) vf[e] = (float)vv[i][e];
; #pragma unroll
;           for (int e = 0; e < 8; ++e) {
;             acc[0][e] += pa[0] * vf[e]; acc[1][e] += pa[1] * vf[e]; acc[2][e] += pa[2] * vf[e]; acc[3][e] += pa[3] * vf[e];
;             acc[4][e] += pb[0] * vf[e]; acc[5][e] += pb[1] * vf[e]; acc[6][e] += pb[2] * vf[e]; acc[7][e] += pb[3] * vf[e];
;           }
;         }
	v_mov_b32_e32 v72, v221
	s_waitcnt lgkmcnt(0)
	v_mov_b32_e32 v74, v225
	v_pk_fma_f32 v[138:139], v[224:225], v[48:49], v[204:205] op_sel_hi:[0,1,1]
	v_pk_fma_f32 v[204:205], v[206:207], v[42:43], v[216:217] op_sel_hi:[0,1,1]
	v_pk_fma_f32 v[216:217], v[206:207], v[42:43], v[228:229] op_sel:[1,0,0]
	v_pk_fma_f32 v[228:229], v[208:209], v[42:43], v[128:129] op_sel_hi:[0,1,1]
	v_pk_fma_f32 v[104:105], v[202:203], v[188:189], v[104:105] op_sel_hi:[0,1,1]
	v_pk_fma_f32 v[114:115], v[176:177], v[188:189], v[114:115] op_sel_hi:[0,1,1]
	v_pk_fma_f32 v[154:155], v[218:219], v[48:49], v[52:53] op_sel_hi:[0,1,1]
	v_pk_fma_f32 v[152:153], v[218:219], v[48:49], v[54:55] op_sel:[1,0,0]
	v_pk_fma_f32 v[146:147], v[220:221], v[48:49], v[56:57] op_sel_hi:[0,1,1]
	v_pk_fma_f32 v[140:141], v[72:73], v[48:49], v[66:67] op_sel_hi:[0,1,1]
	v_pk_fma_f32 v[150:151], v[222:223], v[48:49], v[68:69] op_sel_hi:[0,1,1]
	v_pk_fma_f32 v[144:145], v[222:223], v[48:49], v[70:71] op_sel:[1,0,0]
	v_pk_fma_f32 v[148:149], v[74:75], v[48:49], v[36:37] op_sel_hi:[0,1,1]
	v_pk_fma_f32 v[36:37], v[38:39], v[42:43], v[120:121] op_sel_hi:[0,1,1]
	v_pk_fma_f32 v[48:49], v[210:211], v[42:43], v[134:135] op_sel_hi:[0,1,1]
	v_pk_fma_f32 v[52:53], v[210:211], v[42:43], v[130:131] op_sel:[1,0,0]
	v_pk_fma_f32 v[54:55], v[212:213], v[42:43], v[122:123] op_sel_hi:[0,1,1]
	v_pk_fma_f32 v[42:43], v[40:41], v[42:43], v[132:133] op_sel_hi:[0,1,1]
	v_pk_fma_f32 v[142:143], v[218:219], v[232:233], v[204:205] op_sel_hi:[0,1,1]
	v_pk_fma_f32 v[134:135], v[218:219], v[232:233], v[216:217] op_sel:[1,0,0]
	v_pk_fma_f32 v[128:129], v[220:221], v[232:233], v[228:229] op_sel_hi:[0,1,1]
	v_pk_fma_f32 v[204:205], v[206:207], v[44:45], v[124:125] op_sel_hi:[0,1,1]
	v_pk_fma_f32 v[216:217], v[206:207], v[44:45], v[116:117] op_sel:[1,0,0]
	v_pk_fma_f32 v[228:229], v[208:209], v[44:45], v[110:111] op_sel_hi:[0,1,1]
	v_pk_fma_f32 v[120:121], v[72:73], v[232:233], v[36:37] op_sel_hi:[0,1,1]
	v_pk_fma_f32 v[136:137], v[222:223], v[232:233], v[48:49] op_sel_hi:[0,1,1]
	v_pk_fma_f32 v[130:131], v[222:223], v[232:233], v[52:53] op_sel:[1,0,0]
	v_pk_fma_f32 v[122:123], v[224:225], v[232:233], v[54:55] op_sel_hi:[0,1,1]
	v_pk_fma_f32 v[132:133], v[74:75], v[232:233], v[42:43] op_sel_hi:[0,1,1]
	v_pk_fma_f32 v[232:233], v[38:39], v[44:45], v[104:105] op_sel_hi:[0,1,1]
	v_pk_fma_f32 v[36:37], v[210:211], v[44:45], v[118:119] op_sel_hi:[0,1,1]
	v_pk_fma_f32 v[42:43], v[210:211], v[44:45], v[112:113] op_sel:[1,0,0]
	v_pk_fma_f32 v[48:49], v[212:213], v[44:45], v[106:107] op_sel_hi:[0,1,1]
	v_pk_fma_f32 v[44:45], v[40:41], v[44:45], v[114:115] op_sel_hi:[0,1,1]
	v_pk_fma_f32 v[124:125], v[218:219], v[50:51], v[204:205] op_sel_hi:[0,1,1]
	v_pk_fma_f32 v[116:117], v[218:219], v[50:51], v[216:217] op_sel:[1,0,0]
	v_pk_fma_f32 v[110:111], v[220:221], v[50:51], v[228:229] op_sel_hi:[0,1,1]
	v_pk_fma_f32 v[204:205], v[206:207], v[46:47], v[230:231] op_sel_hi:[0,1,1]
	v_pk_fma_f32 v[206:207], v[206:207], v[46:47], v[58:59] op_sel:[1,0,0]
	v_pk_fma_f32 v[208:209], v[208:209], v[46:47], v[60:61] op_sel_hi:[0,1,1]
	v_pk_fma_f32 v[216:217], v[38:39], v[46:47], v[62:63] op_sel_hi:[0,1,1]
	v_pk_fma_f32 v[228:229], v[210:211], v[46:47], v[64:65] op_sel_hi:[0,1,1]
	v_pk_fma_f32 v[210:211], v[210:211], v[46:47], v[34:35] op_sel:[1,0,0]
	v_pk_fma_f32 v[212:213], v[212:213], v[46:47], v[214:215] op_sel_hi:[0,1,1]
	v_pk_fma_f32 v[214:215], v[40:41], v[46:47], v[226:227] op_sel_hi:[0,1,1]
	v_pk_fma_f32 v[104:105], v[72:73], v[50:51], v[232:233] op_sel_hi:[0,1,1]
	v_pk_fma_f32 v[118:119], v[222:223], v[50:51], v[36:37] op_sel_hi:[0,1,1]
	v_pk_fma_f32 v[112:113], v[222:223], v[50:51], v[42:43] op_sel:[1,0,0]
	v_pk_fma_f32 v[106:107], v[224:225], v[50:51], v[48:49] op_sel_hi:[0,1,1]
	v_pk_fma_f32 v[114:115], v[74:75], v[50:51], v[44:45] op_sel_hi:[0,1,1]
	v_pk_fma_f32 v[108:109], v[218:219], v[234:235], v[204:205] op_sel_hi:[0,1,1]
	v_pk_fma_f32 v[100:101], v[218:219], v[234:235], v[206:207] op_sel:[1,0,0]
	v_pk_fma_f32 v[94:95], v[220:221], v[234:235], v[208:209] op_sel_hi:[0,1,1]
	v_pk_fma_f32 v[90:91], v[72:73], v[234:235], v[216:217] op_sel_hi:[0,1,1]
	v_pk_fma_f32 v[102:103], v[222:223], v[234:235], v[228:229] op_sel_hi:[0,1,1]
	v_pk_fma_f32 v[96:97], v[222:223], v[234:235], v[210:211] op_sel:[1,0,0]
	v_pk_fma_f32 v[92:93], v[224:225], v[234:235], v[212:213] op_sel_hi:[0,1,1]
	v_pk_fma_f32 v[98:99], v[74:75], v[234:235], v[214:215] op_sel_hi:[0,1,1]
	v_add_u32_e32 v172, 0x800, v172
	s_branch .LBB0_1424
.LBB0_1529:
	v_mov_b32_e32 v224, v250
	v_mov_b32_e32 v225, 0x11ff0
	v_mov_b32_e32 v226, 1
	v_mov_b32_e32 v227, 0x11fe0
	v_mov_b32_e32 v228, 0x11fe4
	v_mov_b32_e32 v229, 0x100
	v_mov_b32_e32 v230, 2
	v_mov_b32_e32 v231, 0x3727c5ac
	v_mov_b32_e32 v232, 0x11fa0
	v_mov_b32_e32 v233, 0x80000
	v_mov_b32_e32 v234, 0x1d0000
	v_mov_b32_e32 v235, 0xa800
	s_barrier
	s_cbranch_execnz .LBB0_604
	s_branch .LBB0_810
